# Hyena loop: the 518 compiler s_nop 0 pads after single-instruction asm blocks removed (no hazard behind them), on top of nop-fill
# baseline (speedup 1.0000x reference)
.LBB0_411:
	s_or_b64 exec, exec, s[54:55]
	s_add_u32 s28, s36, 0xe000000
	s_addc_u32 s29, s37, 0
	s_add_i32 s0, 0, 0x27dc0
	s_waitcnt lgkmcnt(0)
	s_barrier
	v_mov_b32_e32 v0, s0
	s_waitcnt lgkmcnt(0)
	ds_read_b128 v[0:3], v0
	v_mov_b32_e32 v4, s82
	ds_read_b128 v[4:7], v4
	s_add_u32 s0, s24, s26
	s_addc_u32 s1, s25, s27
	s_waitcnt lgkmcnt(0)
	v_add_f32_e32 v0, 0, v0
	v_add_f32_e32 v0, v0, v1
	v_add_f32_e32 v0, v0, v2
	v_add_f32_e32 v0, v0, v3
	v_add_f32_e32 v0, v0, v4
	v_add_f32_e32 v0, v0, v5
	v_add_f32_e32 v0, v0, v6
	v_add_f32_e32 v0, v0, v7
	v_add_f32_e32 v34, 0x358637bd, v0
	global_load_dword v177, v83, s[0:1]
	ds_read_b64 v[28:29], v136
	ds_read_b64 v[22:23], v137 offset:4096
	ds_read_b64 v[178:179], v136 offset:544
	ds_read_b64 v[14:15], v137 offset:4640
	ds_read_b64 v[180:181], v136 offset:1088
	ds_read_b64 v[6:7], v137 offset:5184
	ds_read_b64 v[182:183], v136 offset:1632
	ds_read_b64 v[0:1], v137 offset:5728
	ds_read_b64 v[184:185], v136 offset:2176
	ds_read_b64 v[26:27], v137 offset:6272
	ds_read_b64 v[186:187], v136 offset:2720
	ds_read_b64 v[18:19], v137 offset:6816
	ds_read_b64 v[188:189], v136 offset:3264
	ds_read_b64 v[10:11], v137 offset:7360
	ds_read_b64 v[190:191], v136 offset:3808
	ds_read_b64 v[2:3], v137 offset:7904
	ds_read_b64 v[192:193], v136 offset:4352
	ds_read_b64 v[30:31], v137 offset:8448
	ds_read_b64 v[194:195], v136 offset:4896
	ds_read_b64 v[20:21], v137 offset:8992
	ds_read_b64 v[196:197], v136 offset:5440
	ds_read_b64 v[12:13], v137 offset:9536
	ds_read_b64 v[198:199], v136 offset:5984
	ds_read_b64 v[4:5], v137 offset:10080
	ds_read_b64 v[200:201], v136 offset:6528
	ds_read_b64 v[32:33], v137 offset:10624
	ds_read_b64 v[202:203], v136 offset:7072
	ds_read_b64 v[24:25], v137 offset:11168
	ds_read_b64 v[204:205], v136 offset:7616
	ds_read_b64 v[16:17], v137 offset:11712
	ds_read_b64 v[206:207], v136 offset:8160
	ds_read_b64 v[8:9], v137 offset:12256
	s_waitcnt lgkmcnt(0)
	v_add_f32_e32 v208, v28, v192
	v_add_f32_e32 v209, v29, v193
	v_sub_f32_e32 v28, v28, v192
	v_sub_f32_e32 v29, v29, v193
	v_add_f32_e32 v192, v184, v200
	v_add_f32_e32 v193, v185, v201
	v_sub_f32_e32 v184, v184, v200
	v_sub_f32_e32 v185, v185, v201
	v_mov_b32_e32 v35, v139
	v_add_f32_e32 v200, v208, v192
	v_add_f32_e32 v201, v209, v193
	v_sub_f32_e32 v192, v208, v192
	v_sub_f32_e32 v193, v209, v193
	v_add_f32_e32 v208, v28, v185
	v_sub_f32_e32 v209, v29, v184
	v_sub_f32_e32 v185, v28, v185
	v_add_f32_e32 v184, v29, v184
	v_add_f32_e32 v28, v178, v194
	v_add_f32_e32 v29, v179, v195
	v_sub_f32_e32 v178, v178, v194
	v_sub_f32_e32 v179, v179, v195
	v_add_f32_e32 v194, v186, v202
	v_add_f32_e32 v195, v187, v203
	v_sub_f32_e32 v186, v186, v202
	v_sub_f32_e32 v187, v187, v203
	v_mov_b32_e32 v132, v140
	v_add_f32_e32 v202, v28, v194
	v_add_f32_e32 v203, v29, v195
	v_sub_f32_e32 v28, v28, v194
	v_sub_f32_e32 v29, v29, v195
	v_add_f32_e32 v194, v178, v187
	v_sub_f32_e32 v195, v179, v186
	v_sub_f32_e32 v178, v178, v187
	v_add_f32_e32 v179, v179, v186
	v_add_f32_e32 v186, v180, v196
	v_add_f32_e32 v187, v181, v197
	v_sub_f32_e32 v180, v180, v196
	v_sub_f32_e32 v181, v181, v197
	v_add_f32_e32 v196, v188, v204
	v_add_f32_e32 v197, v189, v205
	v_sub_f32_e32 v188, v188, v204
	v_sub_f32_e32 v189, v189, v205
	s_nop 1
	s_mov_b32 m0, s92
	v_add_f32_e32 v204, v186, v196
	v_add_f32_e32 v205, v187, v197
	v_sub_f32_e32 v186, v186, v196
	v_sub_f32_e32 v196, v187, v197
	v_add_f32_e32 v187, v180, v189
	v_sub_f32_e32 v197, v181, v188
	v_sub_f32_e32 v180, v180, v189
	v_add_f32_e32 v181, v181, v188
	v_add_f32_e32 v188, v182, v198
	v_add_f32_e32 v189, v183, v199
	v_sub_f32_e32 v182, v182, v198
	v_sub_f32_e32 v183, v183, v199
	v_add_f32_e32 v198, v190, v206
	v_add_f32_e32 v199, v191, v207
	v_sub_f32_e32 v190, v190, v206
	v_sub_f32_e32 v191, v191, v207
	v_xor_b32_e32 v211, 0x80000000, v186
	v_add_f32_e32 v206, v188, v198
	v_add_f32_e32 v207, v189, v199
	v_sub_f32_e32 v188, v188, v198
	v_sub_f32_e32 v189, v189, v199
	v_add_f32_e32 v198, v182, v191
	v_sub_f32_e32 v199, v183, v190
	v_sub_f32_e32 v182, v182, v191
	v_add_f32_e32 v183, v183, v190
	v_mul_f32_e32 v190, v194, v152
	v_mul_f32_e32 v191, v194, v153
	v_mul_f32_e32 v194, v187, v154
	v_mul_f32_e32 v187, v187, v155
	v_xor_b32_e32 v134, 0x80000000, v35
	v_fma_f32 v190, -v195, v153, v190
	v_fma_f32 v191, v195, v152, v191
	v_fma_f32 v195, v197, v154, v187
	v_mul_f32_e32 v187, v198, v156
	v_fma_f32 v194, -v197, v155, v194
	v_mul_f32_e32 v35, v132, v132
	v_fma_f32 v197, -v199, v157, v187
	v_mul_f32_e32 v187, v198, v157
	v_fma_f32 v130, -v134, v134, v35
	v_mul_f32_e32 v35, v132, v134
	v_fma_f32 v198, v199, v156, v187
	v_mul_f32_e32 v187, v28, v154
	v_mul_f32_e32 v28, v28, v155
	v_fma_f32 v131, v134, v132, v35
	v_mul_f32_e32 v35, v130, v132
	v_fma_f32 v210, v29, v154, v28
	v_mul_f32_e32 v28, v188, v155
	v_sub_f32_e32 v188, v202, v206
	v_fma_f32 v199, -v29, v155, v187
	v_fma_f32 v128, -v131, v134, v35
	v_mul_f32_e32 v35, v130, v134
	v_fma_f32 v213, -v189, v155, v28
	v_fma_f32 v214, v189, v155, v28
	v_mul_f32_e32 v28, v178, v156
	v_sub_f32_e32 v189, v203, v207
	v_fma_f32 v129, v131, v132, v35
	v_mul_f32_e32 v35, v130, v130
	v_fma_f32 v215, -v179, v157, v28
	v_mul_f32_e32 v28, v178, v157
	v_add_f32_e32 v178, v200, v204
	v_fma_f32 v126, -v131, v131, v35
	v_mul_f32_e32 v35, v130, v131
	v_fma_f32 v216, v179, v156, v28
	v_mul_f32_e32 v28, v180, v155
	v_add_f32_e32 v179, v201, v205
	v_sub_f32_e32 v180, v200, v204
	v_fma_f32 v127, v131, v130, v35
	v_mul_f32_e32 v35, v126, v132
	v_fma_f32 v217, -v181, v155, v28
	v_fma_f32 v218, v181, v155, v28
	v_mul_f32_e32 v28, v182, v157
	v_sub_f32_e32 v181, v201, v205
	v_add_f32_e32 v200, v180, v189
	v_fma_f32 v124, -v127, v134, v35
	v_mul_f32_e32 v35, v126, v134
	v_fma_f32 v219, -v183, v156, v28
	v_mul_f32_e32 v28, v182, v156
	v_add_f32_e32 v182, v202, v206
	v_sub_f32_e32 v201, v181, v188
	v_fma_f32 v125, v127, v132, v35
	v_mul_f32_e32 v35, v128, v128
	v_sub_f32_e32 v206, v215, v219
	v_fma_f32 v220, v183, v157, v28
	v_add_f32_e32 v183, v203, v207
	v_add_f32_e32 v28, v178, v182
	v_sub_f32_e32 v186, v178, v182
	v_sub_f32_e32 v178, v180, v189
	v_add_f32_e32 v180, v208, v194
	v_sub_f32_e32 v182, v208, v194
	v_add_f32_e32 v29, v179, v183
	v_sub_f32_e32 v187, v179, v183
	v_add_f32_e32 v179, v181, v188
	v_add_f32_e32 v181, v209, v195
	v_sub_f32_e32 v183, v209, v195
	v_add_f32_e32 v188, v190, v197
	v_add_f32_e32 v189, v191, v198
	v_sub_f32_e32 v190, v190, v197
	v_sub_f32_e32 v191, v191, v198
	v_sub_f32_e32 v207, v216, v220
	v_fma_f32 v122, -v129, v129, v35
	v_add_f32_e32 v194, v180, v188
	v_add_f32_e32 v195, v181, v189
	v_sub_f32_e32 v188, v180, v188
	v_sub_f32_e32 v189, v181, v189
	v_add_f32_e32 v197, v182, v191
	v_sub_f32_e32 v198, v183, v190
	v_sub_f32_e32 v180, v182, v191
	v_add_f32_e32 v181, v183, v190
	v_add_f32_e32 v182, v192, v196
	v_add_f32_e32 v183, v193, v211
	v_sub_f32_e32 v192, v192, v196
	v_sub_f32_e32 v193, v193, v211
	v_add_f32_e32 v190, v199, v213
	v_add_f32_e32 v191, v210, v214
	v_sub_f32_e32 v196, v199, v213
	v_sub_f32_e32 v199, v210, v214
	v_mul_f32_e32 v35, v128, v129
	v_add_f32_e32 v202, v182, v190
	v_add_f32_e32 v203, v183, v191
	v_sub_f32_e32 v190, v182, v190
	v_sub_f32_e32 v191, v183, v191
	v_add_f32_e32 v204, v192, v199
	v_sub_f32_e32 v205, v193, v196
	v_sub_f32_e32 v182, v192, v199
	v_add_f32_e32 v183, v193, v196
	v_add_f32_e32 v192, v185, v217
	v_add_f32_e32 v193, v184, v218
	v_sub_f32_e32 v185, v185, v217
	v_sub_f32_e32 v196, v184, v218
	v_add_f32_e32 v184, v215, v219
	v_add_f32_e32 v199, v216, v220
	v_fma_f32 v123, v129, v128, v35
	v_mul_f32_e32 v35, v126, v128
	v_add_f32_e32 v208, v192, v184
	v_add_f32_e32 v209, v193, v199
	v_sub_f32_e32 v192, v192, v184
	v_sub_f32_e32 v193, v193, v199
	v_add_f32_e32 v199, v185, v207
	v_sub_f32_e32 v210, v196, v206
	v_sub_f32_e32 v184, v185, v207
	v_add_f32_e32 v185, v196, v206
	v_add_f32_e32 v196, v22, v30
	v_add_f32_e32 v206, v23, v31
	v_sub_f32_e32 v22, v22, v30
	v_sub_f32_e32 v23, v23, v31
	v_add_f32_e32 v30, v26, v32
	v_add_f32_e32 v31, v27, v33
	v_sub_f32_e32 v26, v26, v32
	v_sub_f32_e32 v27, v27, v33
	v_fma_f32 v120, -v127, v129, v35
	v_mul_f32_e32 v35, v126, v129
	v_add_f32_e32 v32, v196, v30
	v_add_f32_e32 v33, v206, v31
	v_sub_f32_e32 v30, v196, v30
	v_sub_f32_e32 v31, v206, v31
	v_add_f32_e32 v196, v22, v27
	v_sub_f32_e32 v206, v23, v26
	v_sub_f32_e32 v22, v22, v27
	v_add_f32_e32 v23, v23, v26
	v_add_f32_e32 v26, v14, v20
	v_add_f32_e32 v27, v15, v21
	v_sub_f32_e32 v14, v14, v20
	v_sub_f32_e32 v15, v15, v21
	v_add_f32_e32 v20, v18, v24
	v_add_f32_e32 v21, v19, v25
	v_sub_f32_e32 v18, v18, v24
	v_sub_f32_e32 v19, v19, v25
	v_fma_f32 v121, v127, v128, v35
	v_mul_f32_e32 v35, v126, v126
	v_add_f32_e32 v24, v26, v20
	v_add_f32_e32 v25, v27, v21
	v_sub_f32_e32 v20, v26, v20
	v_sub_f32_e32 v21, v27, v21
	v_add_f32_e32 v26, v14, v19
	v_sub_f32_e32 v27, v15, v18
	v_sub_f32_e32 v14, v14, v19
	v_add_f32_e32 v15, v15, v18
	v_add_f32_e32 v18, v6, v12
	v_add_f32_e32 v19, v7, v13
	v_sub_f32_e32 v6, v6, v12
	v_sub_f32_e32 v7, v7, v13
	v_add_f32_e32 v12, v10, v16
	v_add_f32_e32 v13, v11, v17
	v_sub_f32_e32 v10, v10, v16
	v_sub_f32_e32 v11, v11, v17
	v_fma_f32 v49, -v127, v127, v35
	v_mul_f32_e32 v35, v126, v127
	v_add_f32_e32 v16, v18, v12
	v_add_f32_e32 v17, v19, v13
	v_sub_f32_e32 v12, v18, v12
	v_sub_f32_e32 v13, v19, v13
	v_add_f32_e32 v18, v6, v11
	v_sub_f32_e32 v19, v7, v10
	v_sub_f32_e32 v6, v6, v11
	v_add_f32_e32 v7, v7, v10
	v_add_f32_e32 v10, v0, v4
	v_add_f32_e32 v11, v1, v5
	v_sub_f32_e32 v0, v0, v4
	v_sub_f32_e32 v1, v1, v5
	v_add_f32_e32 v4, v2, v8
	v_add_f32_e32 v5, v3, v9
	v_sub_f32_e32 v2, v2, v8
	v_sub_f32_e32 v3, v3, v9
	v_mul_f32_e32 v6, v6, v155
	v_add_f32_e32 v207, v32, v16
	v_add_f32_e32 v8, v10, v4
	v_add_f32_e32 v9, v11, v5
	v_sub_f32_e32 v4, v10, v4
	v_sub_f32_e32 v5, v11, v5
	v_add_f32_e32 v10, v0, v3
	v_sub_f32_e32 v11, v1, v2
	v_sub_f32_e32 v0, v0, v3
	v_add_f32_e32 v1, v1, v2
	v_mul_f32_e32 v2, v26, v152
	v_mul_f32_e32 v3, v26, v153
	v_mul_f32_e32 v26, v18, v154
	v_mul_f32_e32 v18, v18, v155
	v_mul_f32_e32 v4, v4, v155
	v_add_f32_e32 v211, v33, v17
	v_fma_f32 v2, -v27, v153, v2
	v_fma_f32 v3, v27, v152, v3
	v_fma_f32 v26, -v19, v155, v26
	v_fma_f32 v18, v19, v154, v18
	v_mul_f32_e32 v19, v10, v156
	v_mul_f32_e32 v10, v10, v157
	v_sub_f32_e32 v16, v32, v16
	v_sub_f32_e32 v17, v33, v17
	v_add_f32_e32 v32, v24, v8
	v_add_f32_e32 v33, v25, v9
	v_fma_f32 v19, -v11, v157, v19
	v_fma_f32 v10, v11, v156, v10
	v_mul_f32_e32 v11, v20, v154
	v_mul_f32_e32 v20, v20, v155
	v_sub_f32_e32 v8, v24, v8
	v_sub_f32_e32 v9, v25, v9
	v_xor_b32_e32 v12, 0x80000000, v12
	v_fma_f32 v11, -v21, v155, v11
	v_fma_f32 v20, v21, v154, v20
	v_fma_f32 v21, -v5, v155, v4
	v_fma_f32 v4, v5, v155, v4
	v_mul_f32_e32 v5, v14, v156
	v_mul_f32_e32 v14, v14, v157
	v_sub_f32_e32 v24, v207, v32
	v_sub_f32_e32 v25, v211, v33
	v_fma_f32 v82, v127, v126, v35
	v_mul_f32_e32 v35, v49, v132
	v_fma_f32 v5, -v15, v157, v5
	v_fma_f32 v14, v15, v156, v14
	v_fma_f32 v15, -v7, v155, v6
	v_fma_f32 v6, v7, v155, v6
	v_mul_f32_e32 v7, v0, v157
	v_mul_f32_e32 v0, v0, v156
	v_fma_f32 v47, -v82, v134, v35
	v_mul_f32_e32 v35, v49, v134
	v_mul_f32_e32 v36, v49, v121
	v_fma_f32 v7, -v1, v156, v7
	v_fma_f32 v27, v1, v157, v0
	v_add_f32_e32 v0, v207, v32
	v_add_f32_e32 v1, v211, v33
	v_add_f32_e32 v32, v16, v9
	v_sub_f32_e32 v33, v17, v8
	v_sub_f32_e32 v9, v16, v9
	v_add_f32_e32 v8, v17, v8
	v_add_f32_e32 v16, v196, v26
	v_add_f32_e32 v17, v206, v18
	v_sub_f32_e32 v26, v196, v26
	v_sub_f32_e32 v18, v206, v18
	v_add_f32_e32 v196, v2, v19
	v_add_f32_e32 v206, v3, v10
	v_sub_f32_e32 v2, v2, v19
	v_sub_f32_e32 v3, v3, v10
	ds_write_b64 v138, v[28:29]
	ds_write_b64 v137, v[0:1] offset:4096
	v_add_f32_e32 v10, v16, v196
	v_add_f32_e32 v19, v17, v206
	v_sub_f32_e32 v16, v16, v196
	v_sub_f32_e32 v17, v17, v206
	v_add_f32_e32 v196, v26, v3
	v_sub_f32_e32 v206, v18, v2
	v_sub_f32_e32 v26, v26, v3
	v_add_f32_e32 v18, v18, v2
	v_add_f32_e32 v2, v30, v13
	v_add_f32_e32 v3, v31, v12
	v_sub_f32_e32 v13, v30, v13
	v_sub_f32_e32 v12, v31, v12
	v_add_f32_e32 v30, v11, v21
	v_add_f32_e32 v31, v20, v4
	v_sub_f32_e32 v11, v11, v21
	v_sub_f32_e32 v4, v20, v4
	v_mul_f32_e32 v0, v194, v132
	v_mul_f32_e32 v1, v194, v134
	v_add_f32_e32 v20, v2, v30
	v_add_f32_e32 v21, v3, v31
	v_sub_f32_e32 v30, v2, v30
	v_sub_f32_e32 v31, v3, v31
	v_add_f32_e32 v207, v13, v4
	v_sub_f32_e32 v211, v12, v11
	v_sub_f32_e32 v4, v13, v4
	v_add_f32_e32 v11, v12, v11
	v_add_f32_e32 v2, v22, v15
	v_add_f32_e32 v3, v23, v6
	v_sub_f32_e32 v12, v22, v15
	v_add_f32_e32 v13, v5, v7
	v_add_f32_e32 v15, v14, v27
	v_sub_f32_e32 v5, v5, v7
	v_sub_f32_e32 v7, v14, v27
	v_fma_f32 v0, -v195, v134, v0
	v_fma_f32 v1, v195, v132, v1
	v_add_f32_e32 v14, v2, v13
	v_add_f32_e32 v22, v3, v15
	v_sub_f32_e32 v13, v2, v13
	v_sub_f32_e32 v15, v3, v15
	v_mul_f32_e32 v2, v10, v132
	v_mul_f32_e32 v3, v10, v134
	v_sub_f32_e32 v6, v23, v6
	v_add_f32_e32 v23, v12, v7
	v_fma_f32 v48, v82, v132, v35
	v_mul_f32_e32 v35, v124, v124
	v_fma_f32 v2, -v19, v134, v2
	v_fma_f32 v3, v19, v132, v3
	ds_write_b64 v138, v[0:1] offset:544
	ds_write_b64 v137, v[2:3] offset:4640
	v_mul_f32_e32 v0, v202, v130
	v_mul_f32_e32 v1, v202, v131
	v_mul_f32_e32 v2, v20, v130
	v_mul_f32_e32 v3, v20, v131
	v_sub_f32_e32 v27, v6, v5
	v_fma_f32 v45, -v125, v125, v35
	v_fma_f32 v0, -v203, v131, v0
	v_fma_f32 v1, v203, v130, v1
	v_fma_f32 v2, -v21, v131, v2
	v_fma_f32 v3, v21, v130, v3
	ds_write_b64 v138, v[0:1] offset:1088
	ds_write_b64 v137, v[2:3] offset:5184
	v_mul_f32_e32 v0, v208, v128
	v_mul_f32_e32 v1, v208, v129
	v_mul_f32_e32 v2, v14, v128
	v_mul_f32_e32 v3, v14, v129
	v_mul_f32_e32 v35, v124, v125
	v_fma_f32 v36, v82, v120, v36
	v_fma_f32 v0, -v209, v129, v0
	v_fma_f32 v1, v209, v128, v1
	v_fma_f32 v2, -v22, v129, v2
	v_fma_f32 v3, v22, v128, v3
	ds_write_b64 v138, v[0:1] offset:1632
	ds_write_b64 v137, v[2:3] offset:5728
	v_mul_f32_e32 v0, v200, v126
	v_mul_f32_e32 v1, v200, v127
	v_mul_f32_e32 v2, v32, v126
	v_mul_f32_e32 v3, v32, v127
	v_fma_f32 v46, v125, v124, v35
	v_mul_f32_e32 v35, v49, v128
	v_fma_f32 v0, -v201, v127, v0
	v_fma_f32 v1, v201, v126, v1
	v_fma_f32 v2, -v33, v127, v2
	v_fma_f32 v3, v33, v126, v3
	ds_write_b64 v138, v[0:1] offset:2176
	ds_write_b64 v137, v[2:3] offset:6272
	v_mul_f32_e32 v0, v197, v124
	v_mul_f32_e32 v1, v197, v125
	v_mul_f32_e32 v2, v196, v124
	v_mul_f32_e32 v3, v196, v125
	v_fma_f32 v43, -v82, v129, v35
	v_mul_f32_e32 v35, v49, v129
	v_fma_f32 v0, -v198, v125, v0
	v_fma_f32 v1, v198, v124, v1
	v_fma_f32 v2, -v206, v125, v2
	v_fma_f32 v3, v206, v124, v3
	ds_write_b64 v138, v[0:1] offset:2720
	ds_write_b64 v137, v[2:3] offset:6816
	v_mul_f32_e32 v0, v204, v122
	v_mul_f32_e32 v1, v204, v123
	v_mul_f32_e32 v2, v207, v122
	v_mul_f32_e32 v3, v207, v123
	v_fma_f32 v44, v82, v128, v35
	v_mul_f32_e32 v35, v122, v122
	v_fma_f32 v0, -v205, v123, v0
	v_fma_f32 v1, v205, v122, v1
	v_fma_f32 v2, -v211, v123, v2
	v_fma_f32 v3, v211, v122, v3
	ds_write_b64 v138, v[0:1] offset:3264
	ds_write_b64 v137, v[2:3] offset:7360
	v_mul_f32_e32 v0, v199, v120
	v_mul_f32_e32 v1, v199, v121
	v_mul_f32_e32 v2, v23, v120
	v_mul_f32_e32 v3, v23, v121
	v_fma_f32 v41, -v123, v123, v35
	v_mul_f32_e32 v35, v122, v123
	v_fma_f32 v0, -v210, v121, v0
	v_fma_f32 v1, v210, v120, v1
	v_fma_f32 v2, -v27, v121, v2
	v_fma_f32 v3, v27, v120, v3
	ds_write_b64 v138, v[0:1] offset:3808
	ds_write_b64 v137, v[2:3] offset:7904
	v_mul_f32_e32 v0, v186, v49
	v_mul_f32_e32 v1, v186, v82
	v_mul_f32_e32 v2, v24, v49
	v_mul_f32_e32 v3, v24, v82
	v_fma_f32 v42, v123, v122, v35
	v_mul_f32_e32 v35, v49, v124
	v_fma_f32 v0, -v187, v82, v0
	v_fma_f32 v1, v187, v49, v1
	v_fma_f32 v2, -v25, v82, v2
	v_fma_f32 v3, v25, v49, v3
	ds_write_b64 v138, v[0:1] offset:4352
	ds_write_b64 v137, v[2:3] offset:8448
	v_mul_f32_e32 v0, v188, v47
	v_mul_f32_e32 v1, v188, v48
	v_mul_f32_e32 v2, v16, v47
	v_mul_f32_e32 v3, v16, v48
	v_fma_f32 v39, -v82, v125, v35
	v_mul_f32_e32 v35, v49, v125
	v_fma_f32 v0, -v189, v48, v0
	v_fma_f32 v1, v189, v47, v1
	v_fma_f32 v2, -v17, v48, v2
	v_fma_f32 v3, v17, v47, v3
	ds_write_b64 v138, v[0:1] offset:4896
	ds_write_b64 v137, v[2:3] offset:8992
	v_mul_f32_e32 v0, v190, v45
	v_mul_f32_e32 v1, v190, v46
	v_mul_f32_e32 v2, v30, v45
	v_mul_f32_e32 v3, v30, v46
	v_fma_f32 v40, v82, v124, v35
	v_mul_f32_e32 v35, v120, v120
	v_fma_f32 v0, -v191, v46, v0
	v_fma_f32 v1, v191, v45, v1
	v_fma_f32 v2, -v31, v46, v2
	v_fma_f32 v3, v31, v45, v3
	ds_write_b64 v138, v[0:1] offset:5440
	ds_write_b64 v137, v[2:3] offset:9536
	v_mul_f32_e32 v0, v192, v43
	v_mul_f32_e32 v1, v192, v44
	v_mul_f32_e32 v2, v13, v43
	v_mul_f32_e32 v3, v13, v44
	v_fma_f32 v37, -v121, v121, v35
	v_mul_f32_e32 v35, v120, v121
	v_fma_f32 v0, -v193, v44, v0
	v_fma_f32 v1, v193, v43, v1
	v_fma_f32 v2, -v15, v44, v2
	v_fma_f32 v3, v15, v43, v3
	ds_write_b64 v138, v[0:1] offset:5984
	ds_write_b64 v137, v[2:3] offset:10080
	v_mul_f32_e32 v0, v178, v41
	v_mul_f32_e32 v1, v178, v42
	v_mul_f32_e32 v2, v9, v41
	v_mul_f32_e32 v3, v9, v42
	v_fma_f32 v38, v121, v120, v35
	v_mul_f32_e32 v35, v49, v120
	v_fma_f32 v0, -v179, v42, v0
	v_fma_f32 v1, v179, v41, v1
	v_fma_f32 v2, -v8, v42, v2
	v_fma_f32 v3, v8, v41, v3
	ds_write_b64 v138, v[0:1] offset:6528
	ds_write_b64 v137, v[2:3] offset:10624
	v_mul_f32_e32 v0, v180, v39
	v_mul_f32_e32 v1, v180, v40
	v_mul_f32_e32 v2, v26, v39
	v_mul_f32_e32 v3, v26, v40
	v_fma_f32 v35, -v82, v121, v35
	v_sub_f32_e32 v7, v12, v7
	v_fma_f32 v0, -v181, v40, v0
	v_fma_f32 v1, v181, v39, v1
	v_fma_f32 v2, -v18, v40, v2
	v_fma_f32 v3, v18, v39, v3
	ds_write_b64 v138, v[0:1] offset:7072
	ds_write_b64 v137, v[2:3] offset:11168
	v_mul_f32_e32 v0, v182, v37
	v_mul_f32_e32 v1, v182, v38
	v_mul_f32_e32 v2, v4, v37
	v_mul_f32_e32 v3, v4, v38
	v_add_f32_e32 v5, v6, v5
	v_mov_b32_e32 v132, v144
	v_fma_f32 v0, -v183, v38, v0
	v_fma_f32 v1, v183, v37, v1
	v_fma_f32 v2, -v11, v38, v2
	v_fma_f32 v3, v11, v37, v3
	ds_write_b64 v138, v[0:1] offset:7616
	ds_write_b64 v137, v[2:3] offset:11712
	v_mul_f32_e32 v0, v184, v35
	v_mul_f32_e32 v1, v184, v36
	v_mul_f32_e32 v2, v7, v35
	v_mul_f32_e32 v3, v7, v36
	v_fma_f32 v0, -v185, v36, v0
	v_fma_f32 v1, v185, v35, v1
	v_fma_f32 v2, -v5, v36, v2
	v_fma_f32 v3, v5, v35, v3
	ds_write_b64 v138, v[0:1] offset:8160
	ds_write_b64 v137, v[2:3] offset:12256
	ds_read_b64 v[28:29], v93
	ds_read_b64 v[22:23], v141 offset:4096
	ds_read_b64 v[178:179], v93 offset:32
	ds_read_b64 v[14:15], v141 offset:4128
	ds_read_b64 v[180:181], v93 offset:64
	ds_read_b64 v[6:7], v141 offset:4160
	ds_read_b64 v[182:183], v93 offset:96
	ds_read_b64 v[0:1], v141 offset:4192
	ds_read_b64 v[184:185], v93 offset:128
	ds_read_b64 v[26:27], v141 offset:4224
	ds_read_b64 v[186:187], v93 offset:160
	ds_read_b64 v[18:19], v141 offset:4256
	ds_read_b64 v[188:189], v93 offset:192
	ds_read_b64 v[10:11], v141 offset:4288
	ds_read_b64 v[190:191], v93 offset:224
	ds_read_b64 v[2:3], v141 offset:4320
	ds_read_b64 v[192:193], v93 offset:256
	ds_read_b64 v[30:31], v141 offset:4352
	ds_read_b64 v[194:195], v93 offset:288
	ds_read_b64 v[20:21], v141 offset:4384
	ds_read_b64 v[196:197], v93 offset:320
	ds_read_b64 v[12:13], v141 offset:4416
	ds_read_b64 v[198:199], v93 offset:352
	ds_read_b64 v[4:5], v141 offset:4448
	ds_read_b64 v[200:201], v93 offset:384
	ds_read_b64 v[32:33], v141 offset:4480
	ds_read_b64 v[202:203], v93 offset:416
	ds_read_b64 v[24:25], v141 offset:4512
	ds_read_b64 v[204:205], v93 offset:448
	ds_read_b64 v[16:17], v141 offset:4544
	ds_read_b64 v[206:207], v93 offset:480
	ds_read_b64 v[8:9], v141 offset:4576
	s_waitcnt lgkmcnt(0)
	v_add_f32_e32 v208, v28, v192
	v_add_f32_e32 v209, v29, v193
	v_sub_f32_e32 v28, v28, v192
	v_sub_f32_e32 v29, v29, v193
	v_add_f32_e32 v192, v184, v200
	v_add_f32_e32 v193, v185, v201
	v_sub_f32_e32 v184, v184, v200
	v_sub_f32_e32 v185, v185, v201
	v_mov_b32_e32 v35, v143
	v_add_f32_e32 v200, v208, v192
	v_add_f32_e32 v201, v209, v193
	v_sub_f32_e32 v192, v208, v192
	v_sub_f32_e32 v193, v209, v193
	v_add_f32_e32 v208, v28, v185
	v_sub_f32_e32 v209, v29, v184
	v_sub_f32_e32 v185, v28, v185
	v_add_f32_e32 v184, v29, v184
	v_add_f32_e32 v28, v178, v194
	v_add_f32_e32 v29, v179, v195
	v_sub_f32_e32 v178, v178, v194
	v_sub_f32_e32 v179, v179, v195
	v_add_f32_e32 v194, v186, v202
	v_add_f32_e32 v195, v187, v203
	v_sub_f32_e32 v186, v186, v202
	v_sub_f32_e32 v187, v187, v203
	s_nop 1
	v_add_f32_e32 v202, v28, v194
	v_add_f32_e32 v203, v29, v195
	v_sub_f32_e32 v28, v28, v194
	v_sub_f32_e32 v29, v29, v195
	v_add_f32_e32 v194, v178, v187
	v_sub_f32_e32 v195, v179, v186
	v_sub_f32_e32 v178, v178, v187
	v_add_f32_e32 v179, v179, v186
	v_add_f32_e32 v186, v180, v196
	v_add_f32_e32 v187, v181, v197
	v_sub_f32_e32 v180, v180, v196
	v_sub_f32_e32 v181, v181, v197
	v_add_f32_e32 v196, v188, v204
	v_add_f32_e32 v197, v189, v205
	v_sub_f32_e32 v188, v188, v204
	v_sub_f32_e32 v189, v189, v205
	v_xor_b32_e32 v134, 0x80000000, v35
	v_add_f32_e32 v204, v186, v196
	v_add_f32_e32 v205, v187, v197
	v_sub_f32_e32 v186, v186, v196
	v_sub_f32_e32 v196, v187, v197
	v_add_f32_e32 v187, v180, v189
	v_sub_f32_e32 v197, v181, v188
	v_sub_f32_e32 v180, v180, v189
	v_add_f32_e32 v181, v181, v188
	v_add_f32_e32 v188, v182, v198
	v_add_f32_e32 v189, v183, v199
	v_sub_f32_e32 v182, v182, v198
	v_sub_f32_e32 v183, v183, v199
	v_add_f32_e32 v198, v190, v206
	v_add_f32_e32 v199, v191, v207
	v_sub_f32_e32 v190, v190, v206
	v_sub_f32_e32 v191, v191, v207
	v_xor_b32_e32 v211, 0x80000000, v186
	v_add_f32_e32 v206, v188, v198
	v_add_f32_e32 v207, v189, v199
	v_sub_f32_e32 v188, v188, v198
	v_sub_f32_e32 v189, v189, v199
	v_add_f32_e32 v198, v182, v191
	v_sub_f32_e32 v199, v183, v190
	v_sub_f32_e32 v182, v182, v191
	v_add_f32_e32 v183, v183, v190
	v_mul_f32_e32 v190, v194, v152
	v_mul_f32_e32 v191, v194, v153
	v_mul_f32_e32 v194, v187, v154
	v_mul_f32_e32 v187, v187, v155
	v_mul_f32_e32 v35, v132, v132
	v_fma_f32 v190, -v195, v153, v190
	v_fma_f32 v191, v195, v152, v191
	v_fma_f32 v195, v197, v154, v187
	v_mul_f32_e32 v187, v198, v156
	v_fma_f32 v194, -v197, v155, v194
	v_fma_f32 v130, -v134, v134, v35
	v_mul_f32_e32 v35, v132, v134
	v_fma_f32 v197, -v199, v157, v187
	v_mul_f32_e32 v187, v198, v157
	v_fma_f32 v131, v134, v132, v35
	v_mul_f32_e32 v35, v130, v132
	v_fma_f32 v198, v199, v156, v187
	v_mul_f32_e32 v187, v28, v154
	v_mul_f32_e32 v28, v28, v155
	v_fma_f32 v128, -v131, v134, v35
	v_mul_f32_e32 v35, v130, v134
	v_fma_f32 v210, v29, v154, v28
	v_mul_f32_e32 v28, v188, v155
	v_sub_f32_e32 v188, v202, v206
	v_fma_f32 v199, -v29, v155, v187
	v_fma_f32 v129, v131, v132, v35
	v_mul_f32_e32 v35, v130, v130
	v_fma_f32 v213, -v189, v155, v28
	v_fma_f32 v214, v189, v155, v28
	v_mul_f32_e32 v28, v178, v156
	v_sub_f32_e32 v189, v203, v207
	v_fma_f32 v126, -v131, v131, v35
	v_mul_f32_e32 v35, v130, v131
	v_fma_f32 v215, -v179, v157, v28
	v_mul_f32_e32 v28, v178, v157
	v_add_f32_e32 v178, v200, v204
	v_fma_f32 v127, v131, v130, v35
	v_mul_f32_e32 v35, v126, v132
	v_fma_f32 v216, v179, v156, v28
	v_mul_f32_e32 v28, v180, v155
	v_add_f32_e32 v179, v201, v205
	v_sub_f32_e32 v180, v200, v204
	v_fma_f32 v124, -v127, v134, v35
	v_mul_f32_e32 v35, v126, v134
	v_fma_f32 v217, -v181, v155, v28
	v_fma_f32 v218, v181, v155, v28
	v_mul_f32_e32 v28, v182, v157
	v_sub_f32_e32 v181, v201, v205
	v_add_f32_e32 v200, v180, v189
	v_fma_f32 v125, v127, v132, v35
	v_mul_f32_e32 v35, v128, v128
	v_fma_f32 v219, -v183, v156, v28
	v_mul_f32_e32 v28, v182, v156
	v_add_f32_e32 v182, v202, v206
	v_sub_f32_e32 v201, v181, v188
	v_fma_f32 v122, -v129, v129, v35
	v_mul_f32_e32 v35, v128, v129
	v_sub_f32_e32 v206, v215, v219
	v_fma_f32 v220, v183, v157, v28
	v_add_f32_e32 v183, v203, v207
	v_add_f32_e32 v28, v178, v182
	v_sub_f32_e32 v186, v178, v182
	v_sub_f32_e32 v178, v180, v189
	v_add_f32_e32 v180, v208, v194
	v_sub_f32_e32 v182, v208, v194
	v_add_f32_e32 v29, v179, v183
	v_sub_f32_e32 v187, v179, v183
	v_add_f32_e32 v179, v181, v188
	v_add_f32_e32 v181, v209, v195
	v_sub_f32_e32 v183, v209, v195
	v_add_f32_e32 v188, v190, v197
	v_add_f32_e32 v189, v191, v198
	v_sub_f32_e32 v190, v190, v197
	v_sub_f32_e32 v191, v191, v198
	v_sub_f32_e32 v207, v216, v220
	v_fma_f32 v123, v129, v128, v35
	v_add_f32_e32 v194, v180, v188
	v_add_f32_e32 v195, v181, v189
	v_sub_f32_e32 v188, v180, v188
	v_sub_f32_e32 v189, v181, v189
	v_add_f32_e32 v197, v182, v191
	v_sub_f32_e32 v198, v183, v190
	v_sub_f32_e32 v180, v182, v191
	v_add_f32_e32 v181, v183, v190
	v_add_f32_e32 v182, v192, v196
	v_add_f32_e32 v183, v193, v211
	v_sub_f32_e32 v192, v192, v196
	v_sub_f32_e32 v193, v193, v211
	v_add_f32_e32 v190, v199, v213
	v_add_f32_e32 v191, v210, v214
	v_sub_f32_e32 v196, v199, v213
	v_sub_f32_e32 v199, v210, v214
	v_mul_f32_e32 v35, v126, v128
	v_add_f32_e32 v202, v182, v190
	v_add_f32_e32 v203, v183, v191
	v_sub_f32_e32 v190, v182, v190
	v_sub_f32_e32 v191, v183, v191
	v_add_f32_e32 v204, v192, v199
	v_sub_f32_e32 v205, v193, v196
	v_sub_f32_e32 v182, v192, v199
	v_add_f32_e32 v183, v193, v196
	v_add_f32_e32 v192, v185, v217
	v_add_f32_e32 v193, v184, v218
	v_sub_f32_e32 v185, v185, v217
	v_sub_f32_e32 v196, v184, v218
	v_add_f32_e32 v184, v215, v219
	v_add_f32_e32 v199, v216, v220
	v_fma_f32 v120, -v127, v129, v35
	v_mul_f32_e32 v35, v126, v129
	v_add_f32_e32 v208, v192, v184
	v_add_f32_e32 v209, v193, v199
	v_sub_f32_e32 v192, v192, v184
	v_sub_f32_e32 v193, v193, v199
	v_add_f32_e32 v199, v185, v207
	v_sub_f32_e32 v210, v196, v206
	v_sub_f32_e32 v184, v185, v207
	v_add_f32_e32 v185, v196, v206
	v_add_f32_e32 v196, v22, v30
	v_add_f32_e32 v206, v23, v31
	v_sub_f32_e32 v22, v22, v30
	v_sub_f32_e32 v23, v23, v31
	v_add_f32_e32 v30, v26, v32
	v_add_f32_e32 v31, v27, v33
	v_sub_f32_e32 v26, v26, v32
	v_sub_f32_e32 v27, v27, v33
	v_fma_f32 v121, v127, v128, v35
	v_mul_f32_e32 v35, v126, v126
	v_add_f32_e32 v32, v196, v30
	v_add_f32_e32 v33, v206, v31
	v_sub_f32_e32 v30, v196, v30
	v_sub_f32_e32 v31, v206, v31
	v_add_f32_e32 v196, v22, v27
	v_sub_f32_e32 v206, v23, v26
	v_sub_f32_e32 v22, v22, v27
	v_add_f32_e32 v23, v23, v26
	v_add_f32_e32 v26, v14, v20
	v_add_f32_e32 v27, v15, v21
	v_sub_f32_e32 v14, v14, v20
	v_sub_f32_e32 v15, v15, v21
	v_add_f32_e32 v20, v18, v24
	v_add_f32_e32 v21, v19, v25
	v_sub_f32_e32 v18, v18, v24
	v_sub_f32_e32 v19, v19, v25
	v_fma_f32 v49, -v127, v127, v35
	v_mul_f32_e32 v35, v126, v127
	v_add_f32_e32 v24, v26, v20
	v_add_f32_e32 v25, v27, v21
	v_sub_f32_e32 v20, v26, v20
	v_sub_f32_e32 v21, v27, v21
	v_add_f32_e32 v26, v14, v19
	v_sub_f32_e32 v27, v15, v18
	v_sub_f32_e32 v14, v14, v19
	v_add_f32_e32 v15, v15, v18
	v_add_f32_e32 v18, v6, v12
	v_add_f32_e32 v19, v7, v13
	v_sub_f32_e32 v6, v6, v12
	v_sub_f32_e32 v7, v7, v13
	v_add_f32_e32 v12, v10, v16
	v_add_f32_e32 v13, v11, v17
	v_sub_f32_e32 v10, v10, v16
	v_sub_f32_e32 v11, v11, v17
	v_fma_f32 v82, v127, v126, v35
	v_mul_f32_e32 v35, v49, v132
	v_add_f32_e32 v16, v18, v12
	v_add_f32_e32 v17, v19, v13
	v_sub_f32_e32 v12, v18, v12
	v_sub_f32_e32 v13, v19, v13
	v_add_f32_e32 v18, v6, v11
	v_sub_f32_e32 v19, v7, v10
	v_sub_f32_e32 v6, v6, v11
	v_add_f32_e32 v7, v7, v10
	v_add_f32_e32 v10, v0, v4
	v_add_f32_e32 v11, v1, v5
	v_sub_f32_e32 v0, v0, v4
	v_sub_f32_e32 v1, v1, v5
	v_add_f32_e32 v4, v2, v8
	v_add_f32_e32 v5, v3, v9
	v_sub_f32_e32 v2, v2, v8
	v_sub_f32_e32 v3, v3, v9
	v_mul_f32_e32 v6, v6, v155
	v_add_f32_e32 v207, v32, v16
	v_add_f32_e32 v8, v10, v4
	v_add_f32_e32 v9, v11, v5
	v_sub_f32_e32 v4, v10, v4
	v_sub_f32_e32 v5, v11, v5
	v_add_f32_e32 v10, v0, v3
	v_sub_f32_e32 v11, v1, v2
	v_sub_f32_e32 v0, v0, v3
	v_add_f32_e32 v1, v1, v2
	v_mul_f32_e32 v2, v26, v152
	v_mul_f32_e32 v3, v26, v153
	v_mul_f32_e32 v26, v18, v154
	v_mul_f32_e32 v18, v18, v155
	v_mul_f32_e32 v4, v4, v155
	v_add_f32_e32 v211, v33, v17
	v_fma_f32 v2, -v27, v153, v2
	v_fma_f32 v3, v27, v152, v3
	v_fma_f32 v26, -v19, v155, v26
	v_fma_f32 v18, v19, v154, v18
	v_mul_f32_e32 v19, v10, v156
	v_mul_f32_e32 v10, v10, v157
	v_sub_f32_e32 v16, v32, v16
	v_sub_f32_e32 v17, v33, v17
	v_add_f32_e32 v32, v24, v8
	v_add_f32_e32 v33, v25, v9
	v_fma_f32 v19, -v11, v157, v19
	v_fma_f32 v10, v11, v156, v10
	v_mul_f32_e32 v11, v20, v154
	v_mul_f32_e32 v20, v20, v155
	v_sub_f32_e32 v8, v24, v8
	v_sub_f32_e32 v9, v25, v9
	v_xor_b32_e32 v12, 0x80000000, v12
	v_fma_f32 v11, -v21, v155, v11
	v_fma_f32 v20, v21, v154, v20
	v_fma_f32 v21, -v5, v155, v4
	v_fma_f32 v4, v5, v155, v4
	v_mul_f32_e32 v5, v14, v156
	v_mul_f32_e32 v14, v14, v157
	v_sub_f32_e32 v24, v207, v32
	v_sub_f32_e32 v25, v211, v33
	v_fma_f32 v47, -v82, v134, v35
	v_mul_f32_e32 v35, v49, v134
	v_fma_f32 v5, -v15, v157, v5
	v_fma_f32 v14, v15, v156, v14
	v_fma_f32 v15, -v7, v155, v6
	v_fma_f32 v6, v7, v155, v6
	v_mul_f32_e32 v7, v0, v157
	v_mul_f32_e32 v0, v0, v156
	v_fma_f32 v48, v82, v132, v35
	v_mul_f32_e32 v35, v124, v124
	v_mul_f32_e32 v36, v49, v121
	v_fma_f32 v7, -v1, v156, v7
	v_fma_f32 v27, v1, v157, v0
	v_add_f32_e32 v0, v207, v32
	v_add_f32_e32 v1, v211, v33
	v_add_f32_e32 v32, v16, v9
	v_sub_f32_e32 v33, v17, v8
	v_sub_f32_e32 v9, v16, v9
	v_add_f32_e32 v8, v17, v8
	v_add_f32_e32 v16, v196, v26
	v_add_f32_e32 v17, v206, v18
	v_sub_f32_e32 v26, v196, v26
	v_sub_f32_e32 v18, v206, v18
	v_add_f32_e32 v196, v2, v19
	v_add_f32_e32 v206, v3, v10
	v_sub_f32_e32 v2, v2, v19
	v_sub_f32_e32 v3, v3, v10
	ds_write_b64 v142, v[28:29]
	ds_write_b64 v141, v[0:1] offset:4096
	v_add_f32_e32 v10, v16, v196
	v_add_f32_e32 v19, v17, v206
	v_sub_f32_e32 v16, v16, v196
	v_sub_f32_e32 v17, v17, v206
	v_add_f32_e32 v196, v26, v3
	v_sub_f32_e32 v206, v18, v2
	v_sub_f32_e32 v26, v26, v3
	v_add_f32_e32 v18, v18, v2
	v_add_f32_e32 v2, v30, v13
	v_add_f32_e32 v3, v31, v12
	v_sub_f32_e32 v13, v30, v13
	v_sub_f32_e32 v12, v31, v12
	v_add_f32_e32 v30, v11, v21
	v_add_f32_e32 v31, v20, v4
	v_sub_f32_e32 v11, v11, v21
	v_sub_f32_e32 v4, v20, v4
	v_mul_f32_e32 v0, v194, v132
	v_mul_f32_e32 v1, v194, v134
	v_add_f32_e32 v20, v2, v30
	v_add_f32_e32 v21, v3, v31
	v_sub_f32_e32 v30, v2, v30
	v_sub_f32_e32 v31, v3, v31
	v_add_f32_e32 v207, v13, v4
	v_sub_f32_e32 v211, v12, v11
	v_sub_f32_e32 v4, v13, v4
	v_add_f32_e32 v11, v12, v11
	v_add_f32_e32 v2, v22, v15
	v_add_f32_e32 v3, v23, v6
	v_sub_f32_e32 v12, v22, v15
	v_add_f32_e32 v13, v5, v7
	v_add_f32_e32 v15, v14, v27
	v_sub_f32_e32 v5, v5, v7
	v_sub_f32_e32 v7, v14, v27
	v_fma_f32 v0, -v195, v134, v0
	v_fma_f32 v1, v195, v132, v1
	v_add_f32_e32 v14, v2, v13
	v_add_f32_e32 v22, v3, v15
	v_sub_f32_e32 v13, v2, v13
	v_sub_f32_e32 v15, v3, v15
	v_mul_f32_e32 v2, v10, v132
	v_mul_f32_e32 v3, v10, v134
	v_sub_f32_e32 v6, v23, v6
	v_add_f32_e32 v23, v12, v7
	v_fma_f32 v45, -v125, v125, v35
	v_mul_f32_e32 v35, v124, v125
	v_fma_f32 v2, -v19, v134, v2
	v_fma_f32 v3, v19, v132, v3
	ds_write_b64 v142, v[0:1] offset:32
	ds_write_b64 v141, v[2:3] offset:4128
	v_mul_f32_e32 v0, v202, v130
	v_mul_f32_e32 v1, v202, v131
	v_mul_f32_e32 v2, v20, v130
	v_mul_f32_e32 v3, v20, v131
	v_sub_f32_e32 v27, v6, v5
	v_fma_f32 v46, v125, v124, v35
	v_fma_f32 v0, -v203, v131, v0
	v_fma_f32 v1, v203, v130, v1
	v_fma_f32 v2, -v21, v131, v2
	v_fma_f32 v3, v21, v130, v3
	ds_write_b64 v142, v[0:1] offset:64
	ds_write_b64 v141, v[2:3] offset:4160
	v_mul_f32_e32 v0, v208, v128
	v_mul_f32_e32 v1, v208, v129
	v_mul_f32_e32 v2, v14, v128
	v_mul_f32_e32 v3, v14, v129
	v_mul_f32_e32 v35, v49, v128
	v_fma_f32 v36, v82, v120, v36
	v_fma_f32 v0, -v209, v129, v0
	v_fma_f32 v1, v209, v128, v1
	v_fma_f32 v2, -v22, v129, v2
	v_fma_f32 v3, v22, v128, v3
	ds_write_b64 v142, v[0:1] offset:96
	ds_write_b64 v141, v[2:3] offset:4192
	v_mul_f32_e32 v0, v200, v126
	v_mul_f32_e32 v1, v200, v127
	v_mul_f32_e32 v2, v32, v126
	v_mul_f32_e32 v3, v32, v127
	v_fma_f32 v43, -v82, v129, v35
	v_mul_f32_e32 v35, v49, v129
	v_fma_f32 v0, -v201, v127, v0
	v_fma_f32 v1, v201, v126, v1
	v_fma_f32 v2, -v33, v127, v2
	v_fma_f32 v3, v33, v126, v3
	ds_write_b64 v142, v[0:1] offset:128
	ds_write_b64 v141, v[2:3] offset:4224
	v_mul_f32_e32 v0, v197, v124
	v_mul_f32_e32 v1, v197, v125
	v_mul_f32_e32 v2, v196, v124
	v_mul_f32_e32 v3, v196, v125
	v_fma_f32 v44, v82, v128, v35
	v_mul_f32_e32 v35, v122, v122
	v_fma_f32 v0, -v198, v125, v0
	v_fma_f32 v1, v198, v124, v1
	v_fma_f32 v2, -v206, v125, v2
	v_fma_f32 v3, v206, v124, v3
	ds_write_b64 v142, v[0:1] offset:160
	ds_write_b64 v141, v[2:3] offset:4256
	v_mul_f32_e32 v0, v204, v122
	v_mul_f32_e32 v1, v204, v123
	v_mul_f32_e32 v2, v207, v122
	v_mul_f32_e32 v3, v207, v123
	v_fma_f32 v41, -v123, v123, v35
	v_mul_f32_e32 v35, v122, v123
	v_fma_f32 v0, -v205, v123, v0
	v_fma_f32 v1, v205, v122, v1
	v_fma_f32 v2, -v211, v123, v2
	v_fma_f32 v3, v211, v122, v3
	ds_write_b64 v142, v[0:1] offset:192
	ds_write_b64 v141, v[2:3] offset:4288
	v_mul_f32_e32 v0, v199, v120
	v_mul_f32_e32 v1, v199, v121
	v_mul_f32_e32 v2, v23, v120
	v_mul_f32_e32 v3, v23, v121
	v_fma_f32 v42, v123, v122, v35
	v_mul_f32_e32 v35, v49, v124
	v_fma_f32 v0, -v210, v121, v0
	v_fma_f32 v1, v210, v120, v1
	v_fma_f32 v2, -v27, v121, v2
	v_fma_f32 v3, v27, v120, v3
	ds_write_b64 v142, v[0:1] offset:224
	ds_write_b64 v141, v[2:3] offset:4320
	v_mul_f32_e32 v0, v186, v49
	v_mul_f32_e32 v1, v186, v82
	v_mul_f32_e32 v2, v24, v49
	v_mul_f32_e32 v3, v24, v82
	v_fma_f32 v39, -v82, v125, v35
	v_mul_f32_e32 v35, v49, v125
	v_fma_f32 v0, -v187, v82, v0
	v_fma_f32 v1, v187, v49, v1
	v_fma_f32 v2, -v25, v82, v2
	v_fma_f32 v3, v25, v49, v3
	ds_write_b64 v142, v[0:1] offset:256
	ds_write_b64 v141, v[2:3] offset:4352
	v_mul_f32_e32 v0, v188, v47
	v_mul_f32_e32 v1, v188, v48
	v_mul_f32_e32 v2, v16, v47
	v_mul_f32_e32 v3, v16, v48
	v_fma_f32 v40, v82, v124, v35
	v_mul_f32_e32 v35, v120, v120
	v_fma_f32 v0, -v189, v48, v0
	v_fma_f32 v1, v189, v47, v1
	v_fma_f32 v2, -v17, v48, v2
	v_fma_f32 v3, v17, v47, v3
	ds_write_b64 v142, v[0:1] offset:288
	ds_write_b64 v141, v[2:3] offset:4384
	v_mul_f32_e32 v0, v190, v45
	v_mul_f32_e32 v1, v190, v46
	v_mul_f32_e32 v2, v30, v45
	v_mul_f32_e32 v3, v30, v46
	v_fma_f32 v37, -v121, v121, v35
	v_mul_f32_e32 v35, v120, v121
	v_fma_f32 v0, -v191, v46, v0
	v_fma_f32 v1, v191, v45, v1
	v_fma_f32 v2, -v31, v46, v2
	v_fma_f32 v3, v31, v45, v3
	ds_write_b64 v142, v[0:1] offset:320
	ds_write_b64 v141, v[2:3] offset:4416
	v_mul_f32_e32 v0, v192, v43
	v_mul_f32_e32 v1, v192, v44
	v_mul_f32_e32 v2, v13, v43
	v_mul_f32_e32 v3, v13, v44
	v_fma_f32 v38, v121, v120, v35
	v_mul_f32_e32 v35, v49, v120
	v_fma_f32 v0, -v193, v44, v0
	v_fma_f32 v1, v193, v43, v1
	v_fma_f32 v2, -v15, v44, v2
	v_fma_f32 v3, v15, v43, v3
	ds_write_b64 v142, v[0:1] offset:352
	ds_write_b64 v141, v[2:3] offset:4448
	v_mul_f32_e32 v0, v178, v41
	v_mul_f32_e32 v1, v178, v42
	v_mul_f32_e32 v2, v9, v41
	v_mul_f32_e32 v3, v9, v42
	v_lshl_add_u64 v[14:15], s[50:51], 0, v[86:87]
	v_fma_f32 v0, -v179, v42, v0
	v_fma_f32 v1, v179, v41, v1
	v_fma_f32 v2, -v8, v42, v2
	v_fma_f32 v3, v8, v41, v3
	ds_write_b64 v142, v[0:1] offset:384
	ds_write_b64 v141, v[2:3] offset:4480
	v_mul_f32_e32 v0, v180, v39
	v_mul_f32_e32 v1, v180, v40
	v_mul_f32_e32 v2, v26, v39
	v_mul_f32_e32 v3, v26, v40
	v_div_scale_f32 v26, s[0:1], v34, v34, 1.0
	v_fma_f32 v0, -v181, v40, v0
	v_fma_f32 v1, v181, v39, v1
	v_fma_f32 v2, -v18, v40, v2
	v_fma_f32 v3, v18, v39, v3
	ds_write_b64 v142, v[0:1] offset:416
	ds_write_b64 v141, v[2:3] offset:4512
	v_mul_f32_e32 v0, v182, v37
	v_mul_f32_e32 v1, v182, v38
	v_rcp_f32_e32 v27, v26
	v_fma_f32 v0, -v183, v38, v0
	v_fma_f32 v1, v183, v37, v1
	v_mul_f32_e32 v2, v4, v37
	v_mul_f32_e32 v3, v4, v38
	v_add_co_u32_e32 v24, vcc, s83, v14
	v_fma_f32 v35, -v82, v121, v35
	v_fma_f32 v2, -v11, v38, v2
	v_fma_f32 v3, v11, v37, v3
	ds_write_b64 v142, v[0:1] offset:448
	ds_write_b64 v141, v[2:3] offset:4544
	v_mul_f32_e32 v0, v184, v35
	v_mul_f32_e32 v1, v184, v36
	v_lshl_add_u64 v[8:9], s[52:53], 0, v[86:87]
	v_addc_co_u32_e32 v25, vcc, 0, v15, vcc
	v_sub_f32_e32 v7, v12, v7
	v_fma_f32 v0, -v185, v36, v0
	v_fma_f32 v1, v185, v35, v1
	v_add_co_u32_e32 v22, vcc, s83, v8
	v_mul_f32_e32 v2, v7, v35
	v_mul_f32_e32 v3, v7, v36
	v_add_f32_e32 v5, v6, v5
	s_lshl_b64 s[0:1], s[48:49], 2
	v_fma_f32 v2, -v5, v36, v2
	v_fma_f32 v3, v5, v35, v3
	ds_write_b64 v142, v[0:1] offset:480
	ds_write_b64 v141, v[2:3] offset:4576
	v_addc_co_u32_e32 v23, vcc, 0, v9, vcc
	v_fma_f32 v0, -v26, v27, 1.0
	v_fmac_f32_e32 v27, v0, v27
	v_div_scale_f32 v28, vcc, 1.0, v34, 1.0
	v_mul_f32_e32 v29, v28, v27
	v_fma_f32 v0, -v26, v29, v28
	v_fmac_f32_e32 v29, v0, v27
	ds_read_b128 v[0:3], v162
	ds_read_b128 v[4:7], v162 offset:16
	v_fma_f32 v26, -v26, v29, v28
	v_div_fmas_f32 v26, v26, v27, v29
	v_div_fixup_f32 v82, v26, v34, 1.0
	s_waitcnt lgkmcnt(0)
	v_add_f32_e32 v26, v0, v4
	v_add_f32_e32 v27, v1, v5
	v_sub_f32_e32 v4, v0, v4
	v_sub_f32_e32 v5, v1, v5
	v_add_f32_e32 v28, v2, v6
	v_add_f32_e32 v29, v3, v7
	v_sub_f32_e32 v6, v2, v6
	v_sub_f32_e32 v7, v3, v7
	s_add_u32 s30, s16, s0
	v_add_f32_e32 v0, v26, v28
	v_add_f32_e32 v1, v27, v29
	v_add_f32_e32 v2, v4, v7
	v_sub_f32_e32 v3, v5, v6
	v_sub_f32_e32 v26, v26, v28
	v_sub_f32_e32 v27, v27, v29
	v_sub_f32_e32 v28, v4, v7
	v_pk_mul_f32 v[0:1], v[82:83], v[0:1] op_sel_hi:[0,1]
	v_pk_mul_f32 v[2:3], v[82:83], v[2:3] op_sel_hi:[0,1]
	v_add_f32_e32 v29, v5, v6
	v_cvt_pk_f16_f32 v193, v0, v1
	v_cvt_pk_f16_f32 v190, v2, v3
	ds_read_b128 v[0:3], v163
	ds_read_b128 v[4:7], v163 offset:16
	v_pk_mul_f32 v[28:29], v[82:83], v[28:29] op_sel_hi:[0,1]
	v_pk_mul_f32 v[26:27], v[82:83], v[26:27] op_sel_hi:[0,1]
	v_cvt_pk_f16_f32 v195, v26, v27
	v_cvt_pk_f16_f32 v192, v28, v29
	s_waitcnt lgkmcnt(0)
	v_add_f32_e32 v26, v0, v4
	v_add_f32_e32 v27, v1, v5
	v_sub_f32_e32 v4, v0, v4
	v_sub_f32_e32 v5, v1, v5
	v_add_f32_e32 v28, v2, v6
	v_add_f32_e32 v29, v3, v7
	v_sub_f32_e32 v6, v2, v6
	v_sub_f32_e32 v7, v3, v7
	s_addc_u32 s31, s17, s1
	v_add_f32_e32 v0, v26, v28
	v_add_f32_e32 v1, v27, v29
	v_add_f32_e32 v2, v4, v7
	v_sub_f32_e32 v3, v5, v6
	v_sub_f32_e32 v26, v26, v28
	v_sub_f32_e32 v27, v27, v29
	v_sub_f32_e32 v28, v4, v7
	v_pk_mul_f32 v[0:1], v[82:83], v[0:1] op_sel_hi:[0,1]
	v_pk_mul_f32 v[2:3], v[82:83], v[2:3] op_sel_hi:[0,1]
	v_add_f32_e32 v29, v5, v6
	v_cvt_pk_f16_f32 v188, v0, v1
	v_cvt_pk_f16_f32 v186, v2, v3
	ds_read_b128 v[0:3], v164
	ds_read_b128 v[4:7], v164 offset:16
	v_pk_mul_f32 v[28:29], v[82:83], v[28:29] op_sel_hi:[0,1]
	v_pk_mul_f32 v[26:27], v[82:83], v[26:27] op_sel_hi:[0,1]
	v_cvt_pk_f16_f32 v189, v26, v27
	v_cvt_pk_f16_f32 v187, v28, v29
	s_waitcnt lgkmcnt(0)
	v_add_f32_e32 v26, v0, v4
	v_add_f32_e32 v27, v1, v5
	v_sub_f32_e32 v4, v0, v4
	v_sub_f32_e32 v5, v1, v5
	v_add_f32_e32 v28, v2, v6
	v_add_f32_e32 v29, v3, v7
	v_sub_f32_e32 v6, v2, v6
	v_sub_f32_e32 v7, v3, v7
	s_add_u32 s48, s42, s26
	v_add_f32_e32 v0, v26, v28
	v_add_f32_e32 v1, v27, v29
	v_add_f32_e32 v2, v4, v7
	v_sub_f32_e32 v3, v5, v6
	v_sub_f32_e32 v26, v26, v28
	v_sub_f32_e32 v27, v27, v29
	v_sub_f32_e32 v28, v4, v7
	v_pk_mul_f32 v[0:1], v[82:83], v[0:1] op_sel_hi:[0,1]
	v_pk_mul_f32 v[2:3], v[82:83], v[2:3] op_sel_hi:[0,1]
	v_add_f32_e32 v29, v5, v6
	v_cvt_pk_f16_f32 v184, v0, v1
	v_cvt_pk_f16_f32 v182, v2, v3
	ds_read_b128 v[0:3], v165
	ds_read_b128 v[4:7], v165 offset:16
	v_pk_mul_f32 v[28:29], v[82:83], v[28:29] op_sel_hi:[0,1]
	v_pk_mul_f32 v[26:27], v[82:83], v[26:27] op_sel_hi:[0,1]
	v_cvt_pk_f16_f32 v185, v26, v27
	v_cvt_pk_f16_f32 v183, v28, v29
	s_waitcnt lgkmcnt(0)
	v_add_f32_e32 v26, v0, v4
	v_add_f32_e32 v27, v1, v5
	v_sub_f32_e32 v28, v0, v4
	v_sub_f32_e32 v29, v1, v5
	v_add_f32_e32 v4, v2, v6
	v_add_f32_e32 v5, v3, v7
	v_sub_f32_e32 v30, v2, v6
	v_sub_f32_e32 v6, v3, v7
	v_lshl_add_u64 v[12:13], s[50:51], 0, v[110:111]
	v_add_f32_e32 v0, v26, v4
	v_add_f32_e32 v1, v27, v5
	v_sub_f32_e32 v2, v26, v4
	v_sub_f32_e32 v3, v27, v5
	v_add_f32_e32 v4, v28, v6
	v_sub_f32_e32 v5, v29, v30
	v_sub_f32_e32 v6, v28, v6
	v_add_f32_e32 v7, v29, v30
	ds_read_b128 v[26:29], v166
	ds_read_b128 v[30:33], v166 offset:16
	v_pk_mul_f32 v[0:1], v[82:83], v[0:1] op_sel_hi:[0,1]
	v_lshl_add_u64 v[10:11], s[52:53], 0, v[110:111]
	v_lshl_add_u64 v[38:39], s[50:51], 0, v[112:113]
	v_lshl_add_u64 v[18:19], s[50:51], 0, v[98:99]
	v_lshl_add_u64 v[16:17], s[50:51], 0, v[114:115]
	v_lshl_add_u64 v[20:21], s[52:53], 0, v[98:99]
	v_pk_mul_f32 v[4:5], v[82:83], v[4:5] op_sel_hi:[0,1]
	v_cvt_pk_f16_f32 v180, v0, v1
	v_pk_mul_f32 v[0:1], v[82:83], v[6:7] op_sel_hi:[0,1]
	v_pk_mul_f32 v[2:3], v[82:83], v[2:3] op_sel_hi:[0,1]
	s_addc_u32 s49, s43, s27
	v_lshl_add_u64 v[122:123], s[52:53], 0, v[112:113]
	v_lshl_add_u64 v[120:121], s[52:53], 0, v[114:115]
	v_lshl_add_u64 v[128:129], s[50:51], 0, v[116:117]
	v_lshl_add_u64 v[130:131], s[50:51], 0, v[118:119]
	v_lshl_add_u64 v[124:125], s[52:53], 0, v[116:117]
	v_lshl_add_u64 v[126:127], s[52:53], 0, v[118:119]
	v_cvt_pk_f16_f32 v178, v4, v5
	v_cvt_pk_f16_f32 v181, v2, v3
	v_cvt_pk_f16_f32 v179, v0, v1
	s_waitcnt lgkmcnt(0)
	v_add_f32_e32 v191, v26, v30
	v_add_f32_e32 v194, v27, v31
	v_sub_f32_e32 v208, v26, v30
	v_sub_f32_e32 v209, v27, v31
	v_add_f32_e32 v30, v28, v32
	v_sub_f32_e32 v210, v28, v32
	ds_read_b128 v[34:37], v167
	ds_read_b128 v[42:45], v167 offset:16
	ds_read_b128 v[196:199], v168
	ds_read_b128 v[200:203], v168 offset:16
	ds_read_b128 v[0:3], v169
	ds_read_b128 v[4:7], v169 offset:16
	global_load_dwordx4 v[24:27], v[24:25], off nt
	global_load_ushort v211, v159, s[50:51] offset:-2
	global_load_ushort v213, v159, s[52:53] offset:-2
	global_load_ushort v214, v[38:39], off offset:16
	global_load_dwordx4 v[38:41], v[14:15], off nt
	global_load_ushort v215, v158, s[50:51] offset:-2
	global_load_ushort v216, v158, s[52:53] offset:-2
	global_load_ushort v217, v[12:13], off offset:16
	global_load_dwordx4 v[46:49], v[22:23], off nt
	global_load_ushort v218, v[122:123], off offset:16
	global_load_dwordx4 v[204:207], v[8:9], off nt
	global_load_ushort v219, v[10:11], off offset:16
	global_load_dwordx4 v[8:11], v[128:129], off nt
	global_load_ushort v220, v161, s[50:51] offset:-2
	global_load_ushort v221, v161, s[52:53] offset:-2
	global_load_ushort v222, v[130:131], off offset:16
	global_load_dwordx4 v[12:15], v[18:19], off nt
	global_load_ushort v223, v160, s[50:51] offset:-2
	global_load_ushort v224, v160, s[52:53] offset:-2
	global_load_ushort v225, v[16:17], off offset:16
	global_load_dwordx4 v[16:19], v[124:125], off nt
	global_load_ushort v226, v[126:127], off offset:16
	global_load_dwordx4 v[20:23], v[20:21], off nt
	global_load_ushort v227, v[120:121], off offset:16
	s_waitcnt lgkmcnt(0)
	s_barrier
	v_mov_b32_e32 v28, 0x4000
	s_add_u32 s0, s18, s0
	global_load_dword v124, v28, s[48:49]
	s_addc_u32 s1, s19, s1
	global_load_dword v120, v83, s[30:31]
	global_load_dword v126, v83, s[0:1]
	v_mov_b32_e32 v28, 0x7000
	s_lshl_b64 s[0:1], s[46:47], 2
	global_load_dword v122, v28, s[48:49]
	global_load_dword v128, v172, s[48:49]
	global_load_dword v132, v173, s[48:49]
	global_load_dword v130, v174, s[48:49]
	s_add_u32 s0, s18, s0
	s_addc_u32 s1, s19, s1
	global_load_dword v134, v83, s[0:1]
	v_add_f32_e32 v31, v29, v33
	v_sub_f32_e32 v121, v29, v33
	v_add_f32_e32 v28, v191, v30
	v_sub_f32_e32 v30, v191, v30
	v_sub_f32_e32 v33, v209, v210
	v_add_f32_e32 v209, v209, v210
	v_add_f32_e32 v29, v194, v31
	v_sub_f32_e32 v31, v194, v31
	v_add_f32_e32 v32, v208, v121
	v_sub_f32_e32 v208, v208, v121
	s_add_i32 s52, s44, s22
	v_pk_mul_f32 v[28:29], v[82:83], v[28:29] op_sel_hi:[0,1]
	v_pk_mul_f32 v[32:33], v[82:83], v[32:33] op_sel_hi:[0,1]
	v_cvt_pk_f16_f32 v194, v28, v29
	v_pk_mul_f32 v[28:29], v[82:83], v[208:209] op_sel_hi:[0,1]
	v_pk_mul_f32 v[30:31], v[82:83], v[30:31] op_sel_hi:[0,1]
	v_cvt_pk_f16_f32 v191, v32, v33
	v_cvt_pk_f16_f32 v131, v30, v31
	v_cvt_pk_f16_f32 v129, v28, v29
	s_waitcnt lgkmcnt(0)
	v_add_f32_e32 v30, v34, v42
	v_add_f32_e32 v31, v35, v43
	v_add_f32_e32 v32, v36, v44
	v_add_f32_e32 v33, v37, v45
	v_sub_f32_e32 v34, v34, v42
	v_sub_f32_e32 v35, v35, v43
	v_sub_f32_e32 v36, v36, v44
	v_sub_f32_e32 v37, v37, v45
	v_add_f32_e32 v28, v30, v32
	v_add_f32_e32 v29, v31, v33
	v_sub_f32_e32 v30, v30, v32
	v_sub_f32_e32 v31, v31, v33
	v_sub_f32_e32 v33, v35, v36
	v_add_f32_e32 v32, v34, v37
	v_sub_f32_e32 v34, v34, v37
	v_pk_mul_f32 v[28:29], v[82:83], v[28:29] op_sel_hi:[0,1]
	v_add_f32_e32 v35, v35, v36
	v_cvt_pk_f16_f32 v127, v28, v29
	v_pk_mul_f32 v[28:29], v[82:83], v[34:35] op_sel_hi:[0,1]
	v_pk_mul_f32 v[30:31], v[82:83], v[30:31] op_sel_hi:[0,1]
	v_pk_mul_f32 v[32:33], v[82:83], v[32:33] op_sel_hi:[0,1]
	v_cvt_pk_f16_f32 v123, v30, v31
	v_cvt_pk_f16_f32 v121, v28, v29
	v_add_f32_e32 v28, v196, v200
	v_add_f32_e32 v29, v197, v201
	v_sub_f32_e32 v30, v196, v200
	v_sub_f32_e32 v31, v197, v201
	v_add_f32_e32 v34, v198, v202
	v_add_f32_e32 v35, v199, v203
	v_sub_f32_e32 v36, v198, v202
	v_sub_f32_e32 v37, v199, v203
	v_cvt_pk_f16_f32 v125, v32, v33
	v_add_f32_e32 v32, v28, v34
	v_add_f32_e32 v33, v29, v35
	v_sub_f32_e32 v28, v28, v34
	v_sub_f32_e32 v29, v29, v35
	v_add_f32_e32 v34, v30, v37
	v_sub_f32_e32 v35, v31, v36
	v_sub_f32_e32 v30, v30, v37
	v_add_f32_e32 v31, v31, v36
	s_waitcnt vmcnt(0)
	v_lshlrev_b32_e32 v37, 16, v24
	v_lshlrev_b32_e32 v36, 16, v38
	v_and_b32_e32 v197, 0xffff0000, v24
	v_and_b32_e32 v196, 0xffff0000, v38
	v_lshlrev_b32_e32 v24, 16, v215
	v_lshlrev_b32_e32 v38, 16, v211
	v_lshlrev_b32_e32 v45, 16, v46
	v_lshlrev_b32_e32 v44, 16, v204
	v_cndmask_b32_e64 v43, 0, v38, s[12:13]
	v_cndmask_b32_e64 v42, 0, v24, s[12:13]
	v_pk_mul_f32 v[200:201], v[124:125], v[36:37] op_sel_hi:[0,1]
	v_lshlrev_b32_e32 v24, 16, v216
	v_lshlrev_b32_e32 v38, 16, v213
	v_pk_fma_f32 v[42:43], v[42:43], v[120:121], v[200:201] op_sel_hi:[1,0,1]
	v_cndmask_b32_e64 v201, 0, v38, s[12:13]
	v_cndmask_b32_e64 v200, 0, v24, s[12:13]
	v_pk_mul_f32 v[202:203], v[132:133], v[44:45] op_sel_hi:[0,1]
	v_and_b32_e32 v199, 0xffff0000, v46
	v_and_b32_e32 v198, 0xffff0000, v204
	v_pk_fma_f32 v[200:201], v[200:201], v[128:129], v[202:203] op_sel_hi:[1,0,1]
	v_pk_fma_f32 v[42:43], v[122:123], v[196:197], v[42:43] op_sel_hi:[0,1,1]
	v_pk_fma_f32 v[200:201], v[130:131], v[198:199], v[200:201] op_sel_hi:[0,1,1]
	v_pk_mul_f32 v[208:209], v[124:125], v[196:197] op_sel_hi:[0,1]
	v_pk_add_f32 v[42:43], v[126:127], v[42:43] op_sel_hi:[0,1]
	v_pk_add_f32 v[200:201], v[134:135], v[200:201] op_sel_hi:[0,1]
	v_pk_fma_f32 v[36:37], v[120:121], v[36:37], v[208:209] op_sel_hi:[0,1,1]
	v_pk_mul_f32 v[208:209], v[132:133], v[198:199] op_sel_hi:[0,1]
	v_pk_mul_f32 v[42:43], v[42:43], v[200:201]
	v_lshlrev_b32_e32 v201, 16, v25
	v_lshlrev_b32_e32 v200, 16, v39
	v_lshlrev_b32_e32 v203, 16, v47
	v_lshlrev_b32_e32 v202, 16, v205
	v_pk_fma_f32 v[44:45], v[128:129], v[44:45], v[208:209] op_sel_hi:[0,1,1]
	v_pk_fma_f32 v[36:37], v[122:123], v[200:201], v[36:37] op_sel_hi:[0,1,1]
	v_pk_fma_f32 v[44:45], v[130:131], v[202:203], v[44:45] op_sel_hi:[0,1,1]
	v_pk_add_f32 v[36:37], v[126:127], v[36:37] op_sel_hi:[0,1]
	v_pk_add_f32 v[44:45], v[134:135], v[44:45] op_sel_hi:[0,1]
	v_and_b32_e32 v25, 0xffff0000, v25
	v_and_b32_e32 v24, 0xffff0000, v39
	v_pk_mul_f32 v[44:45], v[36:37], v[44:45]
	v_pk_mul_f32 v[36:37], v[124:125], v[24:25] op_sel_hi:[0,1]
	ds_write_b128 v145, v[42:45]
	v_lshlrev_b32_e32 v45, 16, v26
	v_lshlrev_b32_e32 v44, 16, v40
	v_pk_fma_f32 v[36:37], v[120:121], v[200:201], v[36:37] op_sel_hi:[0,1,1]
	v_and_b32_e32 v43, 0xffff0000, v47
	v_and_b32_e32 v42, 0xffff0000, v205
	v_pk_mul_f32 v[38:39], v[124:125], v[200:201] op_sel_hi:[0,1]
	v_pk_fma_f32 v[36:37], v[122:123], v[44:45], v[36:37] op_sel_hi:[0,1,1]
	v_pk_fma_f32 v[38:39], v[120:121], v[196:197], v[38:39] op_sel_hi:[0,1,1]
	v_pk_add_f32 v[196:197], v[126:127], v[36:37] op_sel_hi:[0,1]
	v_pk_mul_f32 v[36:37], v[132:133], v[42:43] op_sel_hi:[0,1]
	v_pk_mul_f32 v[200:201], v[132:133], v[202:203] op_sel_hi:[0,1]
	v_lshlrev_b32_e32 v47, 16, v48
	v_lshlrev_b32_e32 v46, 16, v206
	v_pk_fma_f32 v[36:37], v[128:129], v[202:203], v[36:37] op_sel_hi:[0,1,1]
	v_pk_fma_f32 v[198:199], v[128:129], v[198:199], v[200:201] op_sel_hi:[0,1,1]
	v_pk_fma_f32 v[38:39], v[122:123], v[24:25], v[38:39] op_sel_hi:[0,1,1]
	v_pk_fma_f32 v[198:199], v[130:131], v[42:43], v[198:199] op_sel_hi:[0,1,1]
	v_pk_fma_f32 v[36:37], v[130:131], v[46:47], v[36:37] op_sel_hi:[0,1,1]
	v_pk_add_f32 v[38:39], v[126:127], v[38:39] op_sel_hi:[0,1]
	v_pk_add_f32 v[198:199], v[134:135], v[198:199] op_sel_hi:[0,1]
	v_pk_add_f32 v[200:201], v[134:135], v[36:37] op_sel_hi:[0,1]
	v_pk_mul_f32 v[36:37], v[38:39], v[198:199]
	v_pk_mul_f32 v[38:39], v[196:197], v[200:201]
	v_and_b32_e32 v197, 0xffff0000, v26
	v_and_b32_e32 v196, 0xffff0000, v40
	ds_write_b128 v145, v[36:39] offset:16
	v_pk_mul_f32 v[36:37], v[124:125], v[196:197] op_sel_hi:[0,1]
	v_lshlrev_b32_e32 v201, 16, v27
	v_lshlrev_b32_e32 v200, 16, v41
	v_pk_fma_f32 v[36:37], v[120:121], v[44:45], v[36:37] op_sel_hi:[0,1,1]
	v_and_b32_e32 v199, 0xffff0000, v48
	v_and_b32_e32 v198, 0xffff0000, v206
	v_pk_mul_f32 v[38:39], v[124:125], v[44:45] op_sel_hi:[0,1]
	v_pk_fma_f32 v[36:37], v[122:123], v[200:201], v[36:37] op_sel_hi:[0,1,1]
	v_pk_fma_f32 v[24:25], v[120:121], v[24:25], v[38:39] op_sel_hi:[0,1,1]
	v_pk_add_f32 v[38:39], v[126:127], v[36:37] op_sel_hi:[0,1]
	v_pk_mul_f32 v[36:37], v[132:133], v[198:199] op_sel_hi:[0,1]
	v_pk_mul_f32 v[44:45], v[132:133], v[46:47] op_sel_hi:[0,1]
	v_lshlrev_b32_e32 v203, 16, v49
	v_lshlrev_b32_e32 v202, 16, v207
	v_pk_fma_f32 v[36:37], v[128:129], v[46:47], v[36:37] op_sel_hi:[0,1,1]
	v_pk_fma_f32 v[42:43], v[128:129], v[42:43], v[44:45] op_sel_hi:[0,1,1]
	v_pk_fma_f32 v[24:25], v[122:123], v[196:197], v[24:25] op_sel_hi:[0,1,1]
	v_pk_fma_f32 v[42:43], v[130:131], v[198:199], v[42:43] op_sel_hi:[0,1,1]
	v_pk_fma_f32 v[36:37], v[130:131], v[202:203], v[36:37] op_sel_hi:[0,1,1]
	v_pk_add_f32 v[24:25], v[126:127], v[24:25] op_sel_hi:[0,1]
	v_pk_add_f32 v[42:43], v[134:135], v[42:43] op_sel_hi:[0,1]
	v_pk_add_f32 v[44:45], v[134:135], v[36:37] op_sel_hi:[0,1]
	v_pk_mul_f32 v[36:37], v[24:25], v[42:43]
	v_pk_mul_f32 v[38:39], v[38:39], v[44:45]
	ds_write_b128 v145, v[36:39] offset:32
	v_pk_mul_f32 v[24:25], v[124:125], v[200:201] op_sel_hi:[0,1]
	v_pk_mul_f32 v[38:39], v[132:133], v[202:203] op_sel_hi:[0,1]
	v_and_b32_e32 v27, 0xffff0000, v27
	v_and_b32_e32 v26, 0xffff0000, v41
	v_and_b32_e32 v37, 0xffff0000, v49
	v_and_b32_e32 v36, 0xffff0000, v207
	v_pk_fma_f32 v[24:25], v[120:121], v[196:197], v[24:25] op_sel_hi:[0,1,1]
	v_pk_fma_f32 v[38:39], v[128:129], v[198:199], v[38:39] op_sel_hi:[0,1,1]
	v_pk_fma_f32 v[24:25], v[122:123], v[26:27], v[24:25] op_sel_hi:[0,1,1]
	v_pk_fma_f32 v[38:39], v[130:131], v[36:37], v[38:39] op_sel_hi:[0,1,1]
	v_pk_add_f32 v[24:25], v[126:127], v[24:25] op_sel_hi:[0,1]
	v_pk_add_f32 v[38:39], v[134:135], v[38:39] op_sel_hi:[0,1]
	v_pk_mul_f32 v[24:25], v[24:25], v[38:39]
	v_lshlrev_b32_e32 v38, 16, v217
	v_lshlrev_b32_e32 v39, 16, v214
	v_lshlrev_b32_e32 v40, 16, v219
	v_lshlrev_b32_e32 v41, 16, v218
	v_pk_mul_f32 v[26:27], v[124:125], v[26:27] op_sel_hi:[0,1]
	v_pk_mul_f32 v[36:37], v[132:133], v[36:37] op_sel_hi:[0,1]
	v_cndmask_b32_e64 v39, 0, v39, s[4:5]
	v_cndmask_b32_e64 v38, 0, v38, s[4:5]
	v_cndmask_b32_e64 v41, 0, v41, s[4:5]
	v_cndmask_b32_e64 v40, 0, v40, s[4:5]
	v_pk_fma_f32 v[26:27], v[120:121], v[200:201], v[26:27] op_sel_hi:[0,1,1]
	v_pk_fma_f32 v[36:37], v[128:129], v[202:203], v[36:37] op_sel_hi:[0,1,1]
	v_pk_fma_f32 v[26:27], v[38:39], v[122:123], v[26:27] op_sel_hi:[1,0,1]
	v_pk_fma_f32 v[36:37], v[40:41], v[130:131], v[36:37] op_sel_hi:[1,0,1]
	v_pk_add_f32 v[26:27], v[126:127], v[26:27] op_sel_hi:[0,1]
	v_pk_add_f32 v[36:37], v[134:135], v[36:37] op_sel_hi:[0,1]
	v_pk_mul_f32 v[26:27], v[26:27], v[36:37]
	ds_write_b128 v145, v[24:27] offset:48
	v_lshlrev_b32_e32 v27, 16, v8
	v_lshlrev_b32_e32 v26, 16, v12
	v_and_b32_e32 v37, 0xffff0000, v8
	v_and_b32_e32 v36, 0xffff0000, v12
	v_lshlrev_b32_e32 v8, 16, v223
	v_lshlrev_b32_e32 v12, 16, v220
	v_lshlrev_b32_e32 v39, 16, v16
	v_lshlrev_b32_e32 v38, 16, v20
	v_cndmask_b32_e64 v25, 0, v12, s[6:7]
	v_cndmask_b32_e64 v24, 0, v8, s[6:7]
	v_pk_mul_f32 v[42:43], v[124:125], v[26:27] op_sel_hi:[0,1]
	v_lshlrev_b32_e32 v8, 16, v224
	v_lshlrev_b32_e32 v12, 16, v221
	v_pk_fma_f32 v[24:25], v[24:25], v[120:121], v[42:43] op_sel_hi:[1,0,1]
	v_cndmask_b32_e64 v43, 0, v12, s[6:7]
	v_cndmask_b32_e64 v42, 0, v8, s[6:7]
	v_pk_mul_f32 v[44:45], v[132:133], v[38:39] op_sel_hi:[0,1]
	v_and_b32_e32 v41, 0xffff0000, v16
	v_and_b32_e32 v40, 0xffff0000, v20
	v_pk_fma_f32 v[42:43], v[42:43], v[128:129], v[44:45] op_sel_hi:[1,0,1]
	v_pk_fma_f32 v[24:25], v[122:123], v[36:37], v[24:25] op_sel_hi:[0,1,1]
	v_pk_fma_f32 v[42:43], v[130:131], v[40:41], v[42:43] op_sel_hi:[0,1,1]
	v_pk_mul_f32 v[46:47], v[124:125], v[36:37] op_sel_hi:[0,1]
	v_pk_add_f32 v[24:25], v[126:127], v[24:25] op_sel_hi:[0,1]
	v_pk_add_f32 v[42:43], v[134:135], v[42:43] op_sel_hi:[0,1]
	v_pk_fma_f32 v[26:27], v[120:121], v[26:27], v[46:47] op_sel_hi:[0,1,1]
	v_pk_mul_f32 v[46:47], v[132:133], v[40:41] op_sel_hi:[0,1]
	v_pk_mul_f32 v[24:25], v[24:25], v[42:43]
	v_lshlrev_b32_e32 v43, 16, v9
	v_lshlrev_b32_e32 v42, 16, v13
	v_lshlrev_b32_e32 v45, 16, v17
	v_lshlrev_b32_e32 v44, 16, v21
	v_pk_fma_f32 v[38:39], v[128:129], v[38:39], v[46:47] op_sel_hi:[0,1,1]
	v_pk_fma_f32 v[26:27], v[122:123], v[42:43], v[26:27] op_sel_hi:[0,1,1]
	v_pk_fma_f32 v[38:39], v[130:131], v[44:45], v[38:39] op_sel_hi:[0,1,1]
	v_pk_add_f32 v[26:27], v[126:127], v[26:27] op_sel_hi:[0,1]
	v_pk_add_f32 v[38:39], v[134:135], v[38:39] op_sel_hi:[0,1]
	v_pk_mul_f32 v[26:27], v[26:27], v[38:39]
	v_and_b32_e32 v9, 0xffff0000, v9
	v_and_b32_e32 v8, 0xffff0000, v13
	ds_write_b128 v146, v[24:27] offset:32768
	v_pk_mul_f32 v[24:25], v[124:125], v[8:9] op_sel_hi:[0,1]
	v_and_b32_e32 v13, 0xffff0000, v17
	v_lshlrev_b32_e32 v17, 16, v10
	v_lshlrev_b32_e32 v16, 16, v14
	v_pk_fma_f32 v[24:25], v[120:121], v[42:43], v[24:25] op_sel_hi:[0,1,1]
	v_and_b32_e32 v12, 0xffff0000, v21
	v_pk_mul_f32 v[26:27], v[124:125], v[42:43] op_sel_hi:[0,1]
	v_pk_fma_f32 v[24:25], v[122:123], v[16:17], v[24:25] op_sel_hi:[0,1,1]
	v_pk_fma_f32 v[26:27], v[120:121], v[36:37], v[26:27] op_sel_hi:[0,1,1]
	v_pk_add_f32 v[36:37], v[126:127], v[24:25] op_sel_hi:[0,1]
	v_pk_mul_f32 v[24:25], v[132:133], v[12:13] op_sel_hi:[0,1]
	v_pk_mul_f32 v[38:39], v[132:133], v[44:45] op_sel_hi:[0,1]
	v_lshlrev_b32_e32 v21, 16, v18
	v_lshlrev_b32_e32 v20, 16, v22
	v_pk_fma_f32 v[24:25], v[128:129], v[44:45], v[24:25] op_sel_hi:[0,1,1]
	v_pk_fma_f32 v[38:39], v[128:129], v[40:41], v[38:39] op_sel_hi:[0,1,1]
	v_pk_fma_f32 v[26:27], v[122:123], v[8:9], v[26:27] op_sel_hi:[0,1,1]
	v_pk_fma_f32 v[38:39], v[130:131], v[12:13], v[38:39] op_sel_hi:[0,1,1]
	v_pk_fma_f32 v[24:25], v[130:131], v[20:21], v[24:25] op_sel_hi:[0,1,1]
	v_pk_add_f32 v[26:27], v[126:127], v[26:27] op_sel_hi:[0,1]
	v_pk_add_f32 v[38:39], v[134:135], v[38:39] op_sel_hi:[0,1]
	v_pk_add_f32 v[40:41], v[134:135], v[24:25] op_sel_hi:[0,1]
	v_pk_mul_f32 v[24:25], v[26:27], v[38:39]
	v_pk_mul_f32 v[26:27], v[36:37], v[40:41]
	ds_write_b128 v146, v[24:27] offset:32784
	v_pk_mul_f32 v[26:27], v[124:125], v[16:17] op_sel_hi:[0,1]
	v_pk_fma_f32 v[8:9], v[120:121], v[8:9], v[26:27] op_sel_hi:[0,1,1]
	v_pk_mul_f32 v[26:27], v[132:133], v[20:21] op_sel_hi:[0,1]
	v_and_b32_e32 v37, 0xffff0000, v10
	v_and_b32_e32 v36, 0xffff0000, v14
	v_and_b32_e32 v39, 0xffff0000, v18
	v_and_b32_e32 v38, 0xffff0000, v22
	v_pk_fma_f32 v[12:13], v[128:129], v[12:13], v[26:27] op_sel_hi:[0,1,1]
	v_pk_mul_f32 v[24:25], v[124:125], v[36:37] op_sel_hi:[0,1]
	v_pk_fma_f32 v[8:9], v[122:123], v[36:37], v[8:9] op_sel_hi:[0,1,1]
	v_pk_fma_f32 v[12:13], v[130:131], v[38:39], v[12:13] op_sel_hi:[0,1,1]
	v_lshlrev_b32_e32 v41, 16, v11
	v_lshlrev_b32_e32 v40, 16, v15
	v_lshlrev_b32_e32 v43, 16, v19
	v_lshlrev_b32_e32 v42, 16, v23
	v_pk_fma_f32 v[16:17], v[120:121], v[16:17], v[24:25] op_sel_hi:[0,1,1]
	v_pk_add_f32 v[8:9], v[126:127], v[8:9] op_sel_hi:[0,1]
	v_pk_mul_f32 v[24:25], v[132:133], v[38:39] op_sel_hi:[0,1]
	v_pk_add_f32 v[12:13], v[134:135], v[12:13] op_sel_hi:[0,1]
	v_pk_fma_f32 v[20:21], v[128:129], v[20:21], v[24:25] op_sel_hi:[0,1,1]
	v_pk_mul_f32 v[24:25], v[8:9], v[12:13]
	v_and_b32_e32 v10, 0xffff0000, v15
	v_pk_mul_f32 v[8:9], v[124:125], v[40:41] op_sel_hi:[0,1]
	v_pk_mul_f32 v[14:15], v[132:133], v[42:43] op_sel_hi:[0,1]
	v_and_b32_e32 v11, 0xffff0000, v11
	v_and_b32_e32 v13, 0xffff0000, v19
	v_and_b32_e32 v12, 0xffff0000, v23
	v_pk_fma_f32 v[8:9], v[120:121], v[36:37], v[8:9] op_sel_hi:[0,1,1]
	v_pk_fma_f32 v[14:15], v[128:129], v[38:39], v[14:15] op_sel_hi:[0,1,1]
	v_pk_fma_f32 v[16:17], v[122:123], v[40:41], v[16:17] op_sel_hi:[0,1,1]
	v_pk_fma_f32 v[20:21], v[130:131], v[42:43], v[20:21] op_sel_hi:[0,1,1]
	v_pk_fma_f32 v[8:9], v[122:123], v[10:11], v[8:9] op_sel_hi:[0,1,1]
	v_pk_fma_f32 v[14:15], v[130:131], v[12:13], v[14:15] op_sel_hi:[0,1,1]
	v_pk_add_f32 v[16:17], v[126:127], v[16:17] op_sel_hi:[0,1]
	v_pk_add_f32 v[20:21], v[134:135], v[20:21] op_sel_hi:[0,1]
	v_pk_add_f32 v[8:9], v[126:127], v[8:9] op_sel_hi:[0,1]
	v_pk_add_f32 v[14:15], v[134:135], v[14:15] op_sel_hi:[0,1]
	v_pk_mul_f32 v[26:27], v[16:17], v[20:21]
	v_pk_mul_f32 v[8:9], v[8:9], v[14:15]
	v_lshlrev_b32_e32 v14, 16, v225
	v_lshlrev_b32_e32 v15, 16, v222
	v_lshlrev_b32_e32 v16, 16, v227
	v_lshlrev_b32_e32 v17, 16, v226
	v_pk_mul_f32 v[10:11], v[124:125], v[10:11] op_sel_hi:[0,1]
	v_pk_mul_f32 v[12:13], v[132:133], v[12:13] op_sel_hi:[0,1]
	v_cndmask_b32_e64 v15, 0, v15, s[8:9]
	v_cndmask_b32_e64 v14, 0, v14, s[8:9]
	v_cndmask_b32_e64 v17, 0, v17, s[8:9]
	v_cndmask_b32_e64 v16, 0, v16, s[8:9]
	v_pk_fma_f32 v[10:11], v[120:121], v[40:41], v[10:11] op_sel_hi:[0,1,1]
	v_pk_fma_f32 v[12:13], v[128:129], v[42:43], v[12:13] op_sel_hi:[0,1,1]
	s_cmpk_lt_i32 s52, 0x400
	v_pk_fma_f32 v[10:11], v[14:15], v[122:123], v[10:11] op_sel_hi:[1,0,1]
	v_pk_fma_f32 v[12:13], v[16:17], v[130:131], v[12:13] op_sel_hi:[1,0,1]
	s_cselect_b64 s[46:47], -1, 0
	v_pk_add_f32 v[10:11], v[126:127], v[10:11] op_sel_hi:[0,1]
	v_pk_add_f32 v[12:13], v[134:135], v[12:13] op_sel_hi:[0,1]
	s_and_b64 s[0:1], s[46:47], exec
	v_pk_mul_f32 v[10:11], v[10:11], v[12:13]
	s_cselect_b32 s50, s52, s44
	ds_write_b128 v146, v[24:27] offset:32800
	ds_write_b128 v146, v[8:11] offset:32816
	v_mov_b32_e32 v27, v92
	s_add_i32 s44, s50, 0x400
	s_waitcnt lgkmcnt(0)
	s_barrier
	v_mov_b32_e32 v8, s44
	v_mov_b32_e32 v9, s50
	v_cmp_gt_i32_e32 vcc, s86, v27
	v_mov_b32_e32 v10, s29
	s_ashr_i32 s51, s50, 31
	v_cndmask_b32_e32 v8, v8, v9, vcc
	v_ashrrev_i32_e32 v9, 31, v8
	v_lshlrev_b64 v[8:9], 14, v[8:9]
	v_lshl_add_u64 v[8:9], s[14:15], 0, v[8:9]
	v_cmp_gt_i32_e32 vcc, s63, v27
	s_ashr_i32 s45, s44, 31
	s_lshl_b64 s[0:1], s[50:51], 14
	v_cndmask_b32_e32 v9, v9, v10, vcc
	v_mov_b32_e32 v10, s28
	v_cndmask_b32_e32 v8, v8, v10, vcc
	v_and_b32_e32 v10, 0x7f, v27
	v_cndmask_b32_e32 v10, v10, v27, vcc
	v_ashrrev_i32_e32 v11, 31, v10
	v_lshlrev_b64 v[10:11], 7, v[10:11]
	v_lshl_add_u64 v[8:9], v[8:9], 0, v[10:11]
	global_load_lds_dword v[8:9], off
	v_add_u32_e32 v8, 0x200, v27
	v_ashrrev_i32_e32 v9, 31, v27
	v_lshrrev_b32_e32 v9, 22, v9
	v_ashrrev_i32_e32 v10, 31, v8
	v_add_u32_e32 v9, v27, v9
	v_lshrrev_b32_e32 v10, 22, v10
	v_ashrrev_i32_e32 v36, 10, v9
	v_add_u32_e32 v10, v8, v10
	v_mad_i32_i24 v9, v36, s64, v27
	v_ashrrev_i32_e32 v10, 10, v10
	v_mul_i32_i24_e32 v11, 0x3c00, v10
	v_mad_i32_i24 v8, v10, s64, v8
	v_ashrrev_i32_e32 v10, 4, v9
	v_lshlrev_b32_e32 v10, 3, v10
	v_ashrrev_i32_e32 v8, 4, v8
	v_and_b32_e32 v10, 0xffffffe0, v10
	v_lshlrev_b32_e32 v9, 3, v9
	v_lshlrev_b32_e32 v8, 3, v8
	v_add3_u32 v10, 0, v10, v9
	v_and_b32_e32 v8, 0xffffffe0, v8
	v_add_lshl_u32 v9, v11, v27, 3
	v_add3_u32 v26, 0, v8, v9
	ds_read_b64 v[24:25], v10
	ds_read_b64 v[20:21], v26 offset:4096
	ds_read_b64 v[202:203], v10 offset:8704
	ds_read_b64 v[16:17], v26 offset:12800
	ds_read_b64 v[204:205], v10 offset:17408
	ds_read_b64 v[12:13], v26 offset:21504
	ds_read_b64 v[206:207], v10 offset:26112
	ds_read_b64 v[8:9], v26 offset:30208
	ds_read_b64 v[214:215], v10 offset:34816
	ds_read_b64 v[22:23], v26 offset:38912
	ds_read_b64 v[216:217], v10 offset:43520
	ds_read_b64 v[18:19], v26 offset:47616
	ds_read_b64 v[218:219], v10 offset:52224
	ds_read_b64 v[14:15], v26 offset:56320
	ds_read_b64 v[220:221], v10 offset:60928
	ds_read_b64 v[10:11], v26 offset:65024
	s_waitcnt lgkmcnt(0)
	v_add_f32_e32 v200, v25, v215
	v_sub_f32_e32 v223, v25, v215
	v_add_f32_e32 v224, v24, v215
	v_sub_f32_e32 v226, v24, v215
	v_add_f32_e32 v215, v202, v217
	v_add_f32_e32 v199, v24, v214
	v_sub_f32_e32 v222, v24, v214
	v_sub_f32_e32 v225, v25, v214
	v_add_f32_e32 v227, v25, v214
	v_add_f32_e32 v24, v202, v216
	v_add_f32_e32 v25, v203, v217
	v_sub_f32_e32 v213, v202, v216
	v_sub_f32_e32 v214, v203, v217
	v_sub_f32_e32 v228, v203, v216
	v_sub_f32_e32 v202, v202, v217
	v_add_f32_e32 v203, v203, v216
	v_add_f32_e32 v216, v204, v218
	v_add_f32_e32 v217, v205, v219
	v_sub_f32_e32 v229, v204, v218
	v_sub_f32_e32 v230, v205, v219
	v_add_f32_e32 v231, v204, v219
	v_sub_f32_e32 v232, v205, v218
	v_sub_f32_e32 v204, v204, v219
	v_add_f32_e32 v205, v205, v218
	v_add_f32_e32 v218, v206, v220
	v_add_f32_e32 v219, v207, v221
	v_sub_f32_e32 v233, v206, v220
	v_sub_f32_e32 v234, v207, v221
	v_sub_f32_e32 v236, v207, v220
	v_add_f32_e32 v207, v207, v220
	v_mul_f32_e32 v220, v215, v152
	v_mul_f32_e32 v215, v215, v153
	v_add_f32_e32 v235, v206, v221
	v_sub_f32_e32 v206, v206, v221
	v_mul_f32_e32 v221, v231, v154
	v_xor_b32_e32 v229, 0x80000000, v229
	v_fma_f32 v220, -v228, v153, v220
	v_fma_f32 v215, v228, v152, v215
	v_mul_f32_e32 v228, v231, v155
	v_fma_f32 v221, -v232, v155, v221
	v_mul_f32_e32 v231, v235, v156
	v_sub_f32_e32 v244, v17, v18
	v_sub_f32_e32 v245, v12, v14
	v_sub_f32_e32 v246, v13, v15
	v_fma_f32 v228, v232, v154, v228
	v_mul_f32_e32 v232, v235, v157
	v_mul_f32_e32 v235, v213, v154
	v_mul_f32_e32 v213, v213, v155
	v_fma_f32 v231, -v236, v157, v231
	v_add_f32_e32 v247, v12, v15
	v_sub_f32_e32 v248, v13, v14
	v_fma_f32 v232, v236, v156, v232
	v_fma_f32 v235, -v214, v155, v235
	v_fma_f32 v236, v214, v154, v213
	v_mul_f32_e32 v213, v233, v155
	v_sub_f32_e32 v249, v8, v10
	v_sub_f32_e32 v250, v9, v11
	v_add_f32_e32 v251, v8, v11
	v_sub_f32_e32 v252, v9, v10
	v_mul_i32_i24_e32 v37, 0x400, v36
	v_fma_f32 v233, -v234, v155, v213
	v_fma_f32 v234, v234, v155, v213
	v_mul_f32_e32 v213, v202, v156
	v_mul_f32_e32 v202, v202, v157
	v_sub_u32_e32 v27, v27, v37
	v_fma_f32 v238, v203, v156, v202
	v_mul_f32_e32 v202, v204, v155
	v_fma_f32 v237, -v203, v157, v213
	v_add_f32_e32 v203, v200, v217
	v_sub_f32_e32 v200, v200, v217
	v_add_f32_e32 v204, v24, v218
	v_sub_f32_e32 v217, v220, v231
	v_fma_f32 v239, -v205, v155, v202
	v_fma_f32 v240, v205, v155, v202
	v_mul_f32_e32 v202, v206, v157
	v_add_f32_e32 v205, v25, v219
	v_cvt_f32_i32_e32 v37, v27
	v_fma_f32 v241, -v207, v156, v202
	v_mul_f32_e32 v202, v206, v156
	v_sub_f32_e32 v214, v203, v205
	v_lshl_add_u32 v27, v36, 14, v27
	v_fma_f32 v206, v207, v157, v202
	v_add_f32_e32 v202, v199, v216
	v_sub_f32_e32 v199, v199, v216
	v_sub_f32_e32 v207, v24, v218
	v_sub_f32_e32 v216, v25, v219
	v_add_f32_e32 v25, v203, v205
	v_add_f32_e32 v203, v225, v228
	v_add_f32_e32 v24, v202, v204
	v_sub_f32_e32 v213, v202, v204
	v_sub_f32_e32 v243, v200, v207
	v_add_f32_e32 v242, v199, v216
	v_sub_f32_e32 v199, v199, v216
	v_add_f32_e32 v200, v200, v207
	v_add_f32_e32 v202, v224, v221
	v_sub_f32_e32 v204, v224, v221
	v_sub_f32_e32 v205, v225, v228
	v_add_f32_e32 v207, v220, v231
	v_add_f32_e32 v216, v215, v232
	v_sub_f32_e32 v218, v215, v232
	v_sub_f32_e32 v219, v223, v229
	v_sub_f32_e32 v220, v235, v233
	v_sub_f32_e32 v228, v205, v217
	v_add_f32_e32 v221, v202, v207
	v_add_f32_e32 v224, v203, v216
	v_sub_f32_e32 v215, v202, v207
	v_sub_f32_e32 v216, v203, v216
	v_add_f32_e32 v225, v204, v218
	v_sub_f32_e32 v202, v204, v218
	v_add_f32_e32 v203, v205, v217
	v_add_f32_e32 v204, v222, v230
	v_add_f32_e32 v205, v223, v229
	v_sub_f32_e32 v207, v222, v230
	v_add_f32_e32 v217, v235, v233
	v_add_f32_e32 v218, v236, v234
	v_sub_f32_e32 v222, v236, v234
	v_sub_f32_e32 v231, v219, v220
	v_sub_f32_e32 v232, v237, v241
	v_sub_f32_e32 v236, v21, v23
	v_add_f32_e32 v223, v204, v217
	v_add_f32_e32 v229, v205, v218
	v_sub_f32_e32 v217, v204, v217
	v_sub_f32_e32 v218, v205, v218
	v_add_f32_e32 v230, v207, v222
	v_sub_f32_e32 v204, v207, v222
	v_add_f32_e32 v205, v219, v220
	v_add_f32_e32 v207, v226, v239
	v_add_f32_e32 v220, v227, v240
	v_sub_f32_e32 v222, v226, v239
	v_sub_f32_e32 v226, v227, v240
	v_add_f32_e32 v219, v237, v241
	v_add_f32_e32 v227, v238, v206
	v_sub_f32_e32 v206, v238, v206
	v_add_f32_e32 v237, v20, v23
	v_sub_f32_e32 v238, v21, v22
	v_sub_f32_e32 v235, v226, v232
	v_add_f32_e32 v233, v207, v219
	v_add_f32_e32 v234, v220, v227
	v_sub_f32_e32 v219, v207, v219
	v_sub_f32_e32 v220, v220, v227
	v_add_f32_e32 v227, v222, v206
	v_sub_f32_e32 v206, v222, v206
	v_add_f32_e32 v207, v226, v232
	v_add_f32_e32 v222, v20, v22
	v_add_f32_e32 v226, v21, v23
	v_sub_f32_e32 v232, v20, v22
	v_sub_f32_e32 v20, v20, v23
	v_add_f32_e32 v21, v21, v22
	v_add_f32_e32 v22, v16, v18
	v_add_f32_e32 v23, v17, v19
	v_sub_f32_e32 v239, v16, v18
	v_sub_f32_e32 v240, v17, v19
	v_add_f32_e32 v241, v16, v19
	v_sub_f32_e32 v16, v16, v19
	v_add_f32_e32 v17, v17, v18
	v_add_f32_e32 v18, v12, v14
	v_add_f32_e32 v19, v13, v15
	v_sub_f32_e32 v12, v12, v15
	v_add_f32_e32 v13, v13, v14
	v_add_f32_e32 v14, v8, v10
	v_add_f32_e32 v15, v9, v11
	v_sub_f32_e32 v8, v8, v11
	v_add_f32_e32 v9, v9, v10
	v_mul_f32_e32 v10, v241, v152
	v_mul_f32_e32 v11, v241, v153
	v_mul_f32_e32 v241, v247, v154
	v_mul_f32_e32 v12, v12, v155
	v_add_f32_e32 v253, v222, v18
	v_add_f32_e32 v254, v226, v19
	v_fma_f32 v10, -v244, v153, v10
	v_fma_f32 v11, v244, v152, v11
	v_mul_f32_e32 v244, v247, v155
	v_fma_f32 v241, -v248, v155, v241
	v_mul_f32_e32 v247, v251, v156
	v_sub_f32_e32 v18, v222, v18
	v_sub_f32_e32 v19, v226, v19
	v_add_f32_e32 v222, v22, v14
	v_fma_f32 v244, v248, v154, v244
	v_mul_f32_e32 v248, v251, v157
	v_mul_f32_e32 v251, v239, v154
	v_mul_f32_e32 v239, v239, v155
	v_add_f32_e32 v226, v23, v15
	v_sub_f32_e32 v14, v22, v14
	v_sub_f32_e32 v15, v23, v15
	v_ashrrev_i32_e32 v36, 4, v27
	v_fma_f32 v251, -v240, v155, v251
	v_fma_f32 v239, v240, v154, v239
	v_xor_b32_e32 v240, 0x80000000, v245
	v_mul_f32_e32 v245, v249, v155
	v_fma_f32 v247, -v252, v157, v247
	v_fma_f32 v248, v252, v156, v248
	v_sub_f32_e32 v22, v253, v222
	v_sub_f32_e32 v23, v254, v226
	v_lshlrev_b32_e32 v36, 3, v36
	v_fma_f32 v249, -v250, v155, v245
	v_fma_f32 v245, v250, v155, v245
	v_mul_f32_e32 v250, v16, v156
	v_mul_f32_e32 v16, v16, v157
	v_mul_f32_e32 v37, 0x38800000, v37
	v_fma_f32 v250, -v17, v157, v250
	v_fma_f32 v16, v17, v156, v16
	v_fma_f32 v17, -v13, v155, v12
	v_fma_f32 v12, v13, v155, v12
	v_mul_f32_e32 v13, v8, v157
	v_mul_f32_e32 v8, v8, v156
	v_and_b32_e32 v36, 0xffffffe0, v36
	v_fma_f32 v13, -v9, v156, v13
	v_fma_f32 v252, v9, v157, v8
	v_add_f32_e32 v8, v253, v222
	v_add_f32_e32 v9, v254, v226
	v_add_f32_e32 v222, v18, v15
	v_sub_f32_e32 v226, v19, v14
	v_sub_f32_e32 v15, v18, v15
	v_add_f32_e32 v14, v19, v14
	v_add_f32_e32 v18, v237, v241
	v_add_f32_e32 v19, v238, v244
	v_sub_f32_e32 v237, v237, v241
	v_sub_f32_e32 v238, v238, v244
	v_add_f32_e32 v241, v10, v247
	v_add_f32_e32 v244, v11, v248
	v_sub_f32_e32 v10, v10, v247
	v_sub_f32_e32 v11, v11, v248
	v_lshlrev_b32_e32 v27, 3, v27
	v_add_f32_e32 v247, v18, v241
	v_add_f32_e32 v248, v19, v244
	v_sub_f32_e32 v18, v18, v241
	v_sub_f32_e32 v19, v19, v244
	v_add_f32_e32 v241, v237, v11
	v_sub_f32_e32 v244, v238, v10
	v_sub_f32_e32 v237, v237, v11
	v_add_f32_e32 v238, v238, v10
	v_add_f32_e32 v10, v232, v246
	v_add_f32_e32 v11, v236, v240
	v_sub_f32_e32 v232, v232, v246
	v_sub_f32_e32 v236, v236, v240
	v_add_f32_e32 v240, v251, v249
	v_add_f32_e32 v246, v239, v245
	v_sub_f32_e32 v249, v251, v249
	v_sub_f32_e32 v239, v239, v245
	v_sin_f32_e32 v38, v37
	v_add_f32_e32 v245, v10, v240
	v_add_f32_e32 v251, v11, v246
	v_sub_f32_e32 v240, v10, v240
	v_sub_f32_e32 v246, v11, v246
	v_add_f32_e32 v10, v20, v17
	v_add_f32_e32 v11, v21, v12
	v_sub_f32_e32 v17, v20, v17
	v_sub_f32_e32 v12, v21, v12
	v_add_f32_e32 v20, v250, v13
	v_add_f32_e32 v21, v16, v252
	v_cos_f32_e32 v210, v37
	v_add3_u32 v27, 0, v36, v27
	v_add_f32_e32 v253, v232, v239
	v_sub_f32_e32 v254, v236, v249
	v_sub_f32_e32 v232, v232, v239
	v_add_f32_e32 v236, v236, v249
	v_sub_f32_e32 v13, v250, v13
	v_add_f32_e32 v239, v10, v20
	v_add_f32_e32 v249, v11, v21
	v_sub_f32_e32 v20, v10, v20
	v_sub_f32_e32 v21, v11, v21
	v_mul_f32_e32 v10, s71, v247
	v_mul_f32_e32 v11, s72, v247
	s_nop 1
	v_sub_f32_e32 v16, v16, v252
	v_sub_f32_e32 v252, v12, v13
	v_add_f32_e32 v12, v12, v13
	ds_write_b64 v27, v[24:25]
	ds_write_b64 v26, v[8:9] offset:4096
	v_xor_b32_e32 v211, 0x80000000, v38
	v_mul_f32_e32 v8, v221, v210
	v_mul_f32_e32 v9, v221, v211
	v_fma_f32 v13, -v248, s72, v10
	v_fma_f32 v11, v248, s71, v11
	v_mul_f32_e32 v36, v210, v210
	v_add_f32_e32 v250, v17, v16
	v_fma_f32 v8, -v224, v211, v8
	v_fma_f32 v9, v224, v210, v9
	v_mul_f32_e32 v10, v13, v210
	v_mul_f32_e32 v13, v13, v211
	v_fma_f32 v208, -v211, v211, v36
	v_mul_f32_e32 v36, v210, v211
	v_sub_f32_e32 v16, v17, v16
	s_lshl_b64 s[28:29], s[44:45], 14
	v_fma_f32 v10, -v11, v211, v10
	v_fma_f32 v11, v11, v210, v13
	ds_write_b64 v27, v[8:9] offset:8704
	ds_write_b64 v26, v[10:11] offset:12800
	v_mul_f32_e32 v10, s65, v245
	v_mul_f32_e32 v11, s66, v245
	v_fma_f32 v209, v211, v210, v36
	v_mul_f32_e32 v8, v223, v208
	v_mul_f32_e32 v36, v208, v210
	s_add_u32 s44, s14, s28
	v_mul_f32_e32 v9, v223, v209
	v_fma_f32 v13, -v251, s66, v10
	v_fma_f32 v11, v251, s65, v11
	v_fma_f32 v8, -v229, v209, v8
	v_fma_f32 v198, -v209, v211, v36
	v_mul_f32_e32 v36, v208, v211
	v_fma_f32 v9, v229, v208, v9
	v_mul_f32_e32 v10, v13, v208
	v_mul_f32_e32 v13, v13, v209
	s_addc_u32 s45, s15, s29
	v_fma_f32 v10, -v11, v209, v10
	v_fma_f32 v11, v11, v208, v13
	ds_write_b64 v27, v[8:9] offset:17408
	ds_write_b64 v26, v[10:11] offset:21504
	v_mul_f32_e32 v10, s73, v239
	v_mul_f32_e32 v11, s74, v239
	v_fma_f32 v201, v209, v210, v36
	v_mul_f32_e32 v8, v233, v198
	v_mul_f32_e32 v36, v208, v208
	v_mul_f32_e32 v9, v233, v201
	v_fma_f32 v13, -v249, s74, v10
	v_fma_f32 v11, v249, s73, v11
	v_fma_f32 v8, -v234, v201, v8
	v_fma_f32 v196, -v209, v209, v36
	v_mul_f32_e32 v36, v208, v209
	v_fma_f32 v9, v234, v198, v9
	v_mul_f32_e32 v10, v13, v198
	v_mul_f32_e32 v13, v13, v201
	v_fma_f32 v10, -v11, v201, v10
	v_fma_f32 v11, v11, v198, v13
	ds_write_b64 v27, v[8:9] offset:26112
	ds_write_b64 v26, v[10:11] offset:30208
	v_mul_f32_e32 v10, s67, v222
	v_mul_f32_e32 v11, s68, v222
	v_fma_f32 v197, v209, v208, v36
	v_mul_f32_e32 v8, v242, v196
	v_mul_f32_e32 v36, v196, v210
	v_mul_f32_e32 v9, v242, v197
	v_fma_f32 v13, -v226, s68, v10
	v_fma_f32 v11, v226, s67, v11
	v_fma_f32 v8, -v243, v197, v8
	v_fma_f32 v132, -v197, v211, v36
	v_mul_f32_e32 v36, v196, v211
	v_fma_f32 v9, v243, v196, v9
	v_mul_f32_e32 v10, v13, v196
	v_mul_f32_e32 v13, v13, v197
	v_fma_f32 v10, -v11, v197, v10
	v_fma_f32 v11, v11, v196, v13
	ds_write_b64 v27, v[8:9] offset:34816
	ds_write_b64 v26, v[10:11] offset:38912
	v_mul_f32_e32 v10, s75, v241
	v_mul_f32_e32 v11, s76, v241
	v_fma_f32 v134, v197, v210, v36
	v_mul_f32_e32 v8, v225, v132
	v_mul_f32_e32 v36, v198, v198
	v_mul_f32_e32 v9, v225, v134
	v_fma_f32 v13, -v244, s76, v10
	v_fma_f32 v11, v244, s75, v11
	v_fma_f32 v8, -v228, v134, v8
	v_fma_f32 v128, -v201, v201, v36
	v_mul_f32_e32 v36, v198, v201
	v_fma_f32 v9, v228, v132, v9
	v_mul_f32_e32 v10, v13, v132
	v_mul_f32_e32 v13, v13, v134
	v_fma_f32 v10, -v11, v134, v10
	v_fma_f32 v11, v11, v132, v13
	ds_write_b64 v27, v[8:9] offset:43520
	ds_write_b64 v26, v[10:11] offset:47616
	v_mul_f32_e32 v10, s69, v253
	v_mul_f32_e32 v11, s70, v253
	v_fma_f32 v130, v201, v198, v36
	v_mul_f32_e32 v8, v230, v128
	v_mul_f32_e32 v36, v196, v198
	v_mul_f32_e32 v9, v230, v130
	v_fma_f32 v13, -v254, s70, v10
	v_fma_f32 v11, v254, s69, v11
	v_fma_f32 v8, -v231, v130, v8
	v_fma_f32 v124, -v197, v201, v36
	v_mul_f32_e32 v36, v196, v201
	v_fma_f32 v9, v231, v128, v9
	v_mul_f32_e32 v10, v13, v128
	v_mul_f32_e32 v13, v13, v130
	v_fma_f32 v10, -v11, v130, v10
	v_fma_f32 v11, v11, v128, v13
	ds_write_b64 v27, v[8:9] offset:52224
	ds_write_b64 v26, v[10:11] offset:56320
	v_mul_f32_e32 v10, s77, v250
	v_mul_f32_e32 v11, s78, v250
	v_fma_f32 v126, v197, v198, v36
	v_mul_f32_e32 v8, v227, v124
	v_mul_f32_e32 v36, v196, v196
	v_mul_f32_e32 v9, v227, v126
	v_fma_f32 v13, -v252, s78, v10
	v_fma_f32 v11, v252, s77, v11
	v_fma_f32 v8, -v235, v126, v8
	v_fma_f32 v120, -v197, v197, v36
	v_mul_f32_e32 v36, v196, v197
	v_fma_f32 v9, v235, v124, v9
	v_mul_f32_e32 v10, v13, v124
	v_mul_f32_e32 v13, v13, v126
	v_fma_f32 v10, -v11, v126, v10
	v_fma_f32 v11, v11, v124, v13
	ds_write_b64 v27, v[8:9] offset:60928
	ds_write_b64 v26, v[10:11] offset:65024
	v_mul_f32_e32 v10, s59, v22
	v_mul_f32_e32 v11, s79, v22
	v_fma_f32 v122, v197, v196, v36
	v_mul_f32_e32 v8, v213, v120
	v_mul_f32_e32 v36, v120, v210
	v_mul_f32_e32 v37, v120, v126
	v_fma_f32 v13, -v23, s79, v10
	v_fma_f32 v11, v23, s59, v11
	v_mul_f32_e32 v9, v213, v122
	v_fma_f32 v8, -v214, v122, v8
	v_fma_f32 v48, -v122, v211, v36
	v_mul_f32_e32 v36, v120, v211
	v_mul_f32_e32 v10, v13, v120
	v_mul_f32_e32 v13, v13, v122
	v_fma_f32 v9, v214, v120, v9
	v_fma_f32 v37, v122, v124, v37
	v_fma_f32 v10, -v11, v122, v10
	v_fma_f32 v11, v11, v120, v13
	v_add_u32_e32 v13, 0x11000, v27
	ds_write_b64 v13, v[8:9]
	v_add_u32_e32 v8, 0x12000, v26
	ds_write_b64 v8, v[10:11]
	v_mul_f32_e32 v10, s72, v18
	v_mul_f32_e32 v11, s78, v18
	v_fma_f32 v49, v122, v210, v36
	v_mul_f32_e32 v8, v215, v48
	v_mul_f32_e32 v36, v132, v132
	v_fma_f32 v13, -v19, s78, v10
	v_fma_f32 v11, v19, s72, v11
	v_fma_f32 v8, -v216, v49, v8
	v_mul_f32_e32 v9, v215, v49
	v_fma_f32 v46, -v134, v134, v36
	v_mul_f32_e32 v36, v132, v134
	v_mul_f32_e32 v10, v13, v48
	v_mul_f32_e32 v13, v13, v49
	v_fma_f32 v10, -v11, v49, v10
	v_fma_f32 v11, v11, v48, v13
	v_add_u32_e32 v13, 0x13200, v27
	v_fma_f32 v9, v216, v48, v9
	ds_write_b64 v13, v[8:9]
	v_add_u32_e32 v8, 0x14200, v26
	ds_write_b64 v8, v[10:11]
	v_mul_f32_e32 v10, s66, v240
	v_mul_f32_e32 v11, s70, v240
	v_fma_f32 v47, v134, v132, v36
	v_mul_f32_e32 v8, v217, v46
	v_mul_f32_e32 v36, v120, v198
	v_fma_f32 v13, -v246, s70, v10
	v_fma_f32 v11, v246, s66, v11
	v_fma_f32 v8, -v218, v47, v8
	v_mul_f32_e32 v9, v217, v47
	v_fma_f32 v44, -v122, v201, v36
	v_mul_f32_e32 v36, v120, v201
	v_mul_f32_e32 v10, v13, v46
	v_mul_f32_e32 v13, v13, v47
	v_mov_b32_e32 v217, v140
	v_fma_f32 v10, -v11, v47, v10
	v_fma_f32 v11, v11, v46, v13
	v_add_u32_e32 v13, 0x15400, v27
	v_fma_f32 v9, v218, v46, v9
	ds_write_b64 v13, v[8:9]
	v_add_u32_e32 v8, 0x16400, v26
	ds_write_b64 v8, v[10:11]
	v_mul_f32_e32 v10, s74, v20
	v_mul_f32_e32 v11, s76, v20
	v_fma_f32 v45, v122, v198, v36
	v_mul_f32_e32 v8, v219, v44
	v_mul_f32_e32 v36, v128, v128
	v_fma_f32 v13, -v21, s76, v10
	v_fma_f32 v11, v21, s74, v11
	v_fma_f32 v8, -v220, v45, v8
	v_mul_f32_e32 v9, v219, v45
	v_fma_f32 v42, -v130, v130, v36
	v_mul_f32_e32 v36, v128, v130
	v_mul_f32_e32 v10, v13, v44
	v_mul_f32_e32 v13, v13, v45
	v_fma_f32 v10, -v11, v45, v10
	v_fma_f32 v11, v11, v44, v13
	v_add_u32_e32 v13, 0x17600, v27
	v_fma_f32 v9, v220, v44, v9
	ds_write_b64 v13, v[8:9]
	v_add_u32_e32 v8, 0x18600, v26
	ds_write_b64 v8, v[10:11]
	v_mul_f32_e32 v10, s68, v15
	v_fma_f32 v43, v130, v128, v36
	v_mul_f32_e32 v8, v199, v42
	v_mul_f32_e32 v36, v120, v132
	v_fma_f32 v11, -v14, s68, v10
	v_fma_f32 v13, v14, s68, v10
	v_fma_f32 v8, -v200, v43, v8
	v_mul_f32_e32 v9, v199, v43
	v_fma_f32 v40, -v122, v134, v36
	v_mul_f32_e32 v36, v120, v134
	v_mul_f32_e32 v10, v11, v42
	v_mul_f32_e32 v11, v11, v43
	v_fma_f32 v10, -v13, v43, v10
	v_fma_f32 v11, v13, v42, v11
	v_add_u32_e32 v13, 0x19800, v27
	v_fma_f32 v9, v200, v42, v9
	ds_write_b64 v13, v[8:9]
	v_add_u32_e32 v8, 0x1a800, v26
	ds_write_b64 v8, v[10:11]
	v_mul_f32_e32 v10, s76, v237
	v_mul_f32_e32 v11, s74, v237
	v_fma_f32 v41, v122, v132, v36
	v_mul_f32_e32 v8, v202, v40
	v_mul_f32_e32 v36, v124, v124
	v_fma_f32 v13, -v238, s74, v10
	v_fma_f32 v11, v238, s76, v11
	v_fma_f32 v8, -v203, v41, v8
	v_mul_f32_e32 v9, v202, v41
	v_fma_f32 v38, -v126, v126, v36
	v_mul_f32_e32 v36, v124, v126
	v_mul_f32_e32 v10, v13, v40
	v_mul_f32_e32 v13, v13, v41
	v_fma_f32 v10, -v11, v41, v10
	v_fma_f32 v11, v11, v40, v13
	v_add_u32_e32 v13, 0x1ba00, v27
	v_fma_f32 v9, v203, v40, v9
	ds_write_b64 v13, v[8:9]
	v_add_u32_e32 v8, 0x1ca00, v26
	ds_write_b64 v8, v[10:11]
	v_mul_f32_e32 v10, s70, v232
	v_mul_f32_e32 v11, s66, v232
	v_fma_f32 v39, v126, v124, v36
	v_mul_f32_e32 v8, v204, v38
	v_mul_f32_e32 v36, v120, v124
	v_mov_b32_e32 v120, v139
	v_fma_f32 v13, -v236, s66, v10
	v_fma_f32 v11, v236, s70, v11
	v_fma_f32 v8, -v205, v39, v8
	v_mul_f32_e32 v9, v204, v39
	v_fma_f32 v36, -v122, v126, v36
	v_mul_f32_e32 v10, v13, v38
	v_mul_f32_e32 v13, v13, v39
	v_fma_f32 v9, v205, v38, v9
	v_fma_f32 v10, -v11, v39, v10
	v_fma_f32 v11, v11, v38, v13
	v_add_u32_e32 v13, 0x1dc00, v27
	ds_write_b64 v13, v[8:9]
	v_add_u32_e32 v8, 0x1ec00, v26
	ds_write_b64 v8, v[10:11]
	v_mul_f32_e32 v10, s78, v16
	v_mul_f32_e32 v11, s72, v16
	v_mul_f32_e32 v8, v206, v36
	v_mul_f32_e32 v9, v206, v37
	v_fma_f32 v13, -v12, s72, v10
	v_fma_f32 v11, v12, s78, v11
	v_fma_f32 v8, -v207, v37, v8
	v_fma_f32 v9, v207, v36, v9
	v_mul_f32_e32 v10, v13, v36
	v_mul_f32_e32 v12, v13, v37
	v_fma_f32 v10, -v11, v37, v10
	v_fma_f32 v11, v11, v36, v12
	v_add_u32_e32 v12, 0x1fe00, v27
	ds_write_b64 v12, v[8:9]
	v_add_u32_e32 v8, 0x20e00, v26
	ds_write_b64 v8, v[10:11]
	s_waitcnt lgkmcnt(0)
	s_barrier
	ds_read_b64 v[44:45], v136
	ds_read_b64 v[38:39], v137 offset:4096
	ds_read_b64 v[220:221], v136 offset:544
	ds_read_b64 v[22:23], v137 offset:4640
	ds_read_b64 v[222:223], v136 offset:1088
	ds_read_b64 v[14:15], v137 offset:5184
	ds_read_b64 v[224:225], v136 offset:1632
	ds_read_b64 v[8:9], v137 offset:5728
	ds_read_b64 v[226:227], v136 offset:2176
	ds_read_b64 v[42:43], v137 offset:6272
	ds_read_b64 v[228:229], v136 offset:2720
	ds_read_b64 v[26:27], v137 offset:6816
	ds_read_b64 v[230:231], v136 offset:3264
	ds_read_b64 v[18:19], v137 offset:7360
	ds_read_b64 v[232:233], v136 offset:3808
	ds_read_b64 v[10:11], v137 offset:7904
	ds_read_b64 v[234:235], v136 offset:4352
	ds_read_b64 v[46:47], v137 offset:8448
	ds_read_b64 v[236:237], v136 offset:4896
	ds_read_b64 v[36:37], v137 offset:8992
	ds_read_b64 v[238:239], v136 offset:5440
	ds_read_b64 v[20:21], v137 offset:9536
	ds_read_b64 v[240:241], v136 offset:5984
	ds_read_b64 v[12:13], v137 offset:10080
	ds_read_b64 v[242:243], v136 offset:6528
	ds_read_b64 v[48:49], v137 offset:10624
	ds_read_b64 v[244:245], v136 offset:7072
	ds_read_b64 v[40:41], v137 offset:11168
	ds_read_b64 v[246:247], v136 offset:7616
	ds_read_b64 v[24:25], v137 offset:11712
	ds_read_b64 v[248:249], v136 offset:8160
	ds_read_b64 v[16:17], v137 offset:12256
	s_waitcnt lgkmcnt(0)
	v_add_f32_e32 v219, v44, v234
	v_add_f32_e32 v250, v45, v235
	v_sub_f32_e32 v44, v44, v234
	v_sub_f32_e32 v45, v45, v235
	v_add_f32_e32 v234, v226, v242
	v_add_f32_e32 v235, v227, v243
	v_sub_f32_e32 v226, v226, v242
	v_sub_f32_e32 v227, v227, v243
	s_nop 1
	v_add_f32_e32 v242, v219, v234
	v_add_f32_e32 v243, v250, v235
	v_sub_f32_e32 v234, v219, v234
	v_sub_f32_e32 v235, v250, v235
	v_add_f32_e32 v250, v44, v227
	v_sub_f32_e32 v251, v45, v226
	v_sub_f32_e32 v252, v44, v227
	v_add_f32_e32 v226, v45, v226
	v_add_f32_e32 v44, v220, v236
	v_add_f32_e32 v45, v221, v237
	v_sub_f32_e32 v219, v220, v236
	v_sub_f32_e32 v220, v221, v237
	v_add_f32_e32 v221, v228, v244
	v_add_f32_e32 v227, v229, v245
	v_sub_f32_e32 v228, v228, v244
	v_sub_f32_e32 v229, v229, v245
	v_xor_b32_e32 v218, 0x80000000, v120
	v_add_f32_e32 v236, v44, v221
	v_add_f32_e32 v237, v45, v227
	v_sub_f32_e32 v44, v44, v221
	v_sub_f32_e32 v45, v45, v227
	v_add_f32_e32 v221, v219, v229
	v_sub_f32_e32 v227, v220, v228
	v_sub_f32_e32 v219, v219, v229
	v_add_f32_e32 v220, v220, v228
	v_add_f32_e32 v228, v222, v238
	v_add_f32_e32 v229, v223, v239
	v_sub_f32_e32 v222, v222, v238
	v_sub_f32_e32 v223, v223, v239
	v_add_f32_e32 v238, v230, v246
	v_add_f32_e32 v239, v231, v247
	v_sub_f32_e32 v230, v230, v246
	v_sub_f32_e32 v231, v231, v247
	v_mul_f32_e32 v120, v217, v217
	v_add_f32_e32 v244, v228, v238
	v_add_f32_e32 v245, v229, v239
	v_sub_f32_e32 v228, v228, v238
	v_sub_f32_e32 v238, v229, v239
	v_add_f32_e32 v229, v222, v231
	v_sub_f32_e32 v239, v223, v230
	v_sub_f32_e32 v222, v222, v231
	v_add_f32_e32 v223, v223, v230
	v_add_f32_e32 v230, v224, v240
	v_add_f32_e32 v231, v225, v241
	v_sub_f32_e32 v224, v224, v240
	v_sub_f32_e32 v225, v225, v241
	v_add_f32_e32 v240, v232, v248
	v_add_f32_e32 v241, v233, v249
	v_sub_f32_e32 v232, v232, v248
	v_sub_f32_e32 v233, v233, v249
	v_xor_b32_e32 v249, 0x80000000, v228
	v_add_f32_e32 v247, v231, v241
	v_sub_f32_e32 v231, v231, v241
	v_sub_f32_e32 v241, v225, v232
	v_add_f32_e32 v225, v225, v232
	v_mul_f32_e32 v232, v221, v152
	v_mul_f32_e32 v221, v221, v153
	v_add_f32_e32 v246, v230, v240
	v_sub_f32_e32 v230, v230, v240
	v_add_f32_e32 v240, v224, v233
	v_sub_f32_e32 v224, v224, v233
	v_fma_f32 v232, -v227, v153, v232
	v_fma_f32 v221, v227, v152, v221
	v_mul_f32_e32 v227, v229, v154
	v_add_f32_e32 v228, v237, v247
	v_fma_f32 v215, -v218, v218, v120
	v_mul_f32_e32 v120, v217, v218
	v_fma_f32 v233, -v239, v155, v227
	v_mul_f32_e32 v227, v229, v155
	v_fma_f32 v216, v218, v217, v120
	v_mul_f32_e32 v120, v215, v217
	v_fma_f32 v229, v239, v154, v227
	v_mul_f32_e32 v227, v240, v156
	v_fma_f32 v213, -v216, v218, v120
	v_mul_f32_e32 v120, v215, v218
	v_fma_f32 v239, -v241, v157, v227
	v_mul_f32_e32 v227, v240, v157
	v_fma_f32 v214, v216, v217, v120
	v_mul_f32_e32 v120, v215, v215
	v_fma_f32 v240, v241, v156, v227
	v_mul_f32_e32 v227, v44, v154
	v_mul_f32_e32 v44, v44, v155
	v_fma_f32 v210, -v216, v216, v120
	v_mul_f32_e32 v120, v215, v216
	v_fma_f32 v248, v45, v154, v44
	v_mul_f32_e32 v44, v230, v155
	v_sub_f32_e32 v230, v236, v246
	v_fma_f32 v241, -v45, v155, v227
	v_fma_f32 v211, v216, v215, v120
	v_mul_f32_e32 v120, v210, v217
	v_fma_f32 v253, -v231, v155, v44
	v_fma_f32 v231, v231, v155, v44
	v_mul_f32_e32 v44, v219, v156
	v_fma_f32 v208, -v211, v218, v120
	v_mul_f32_e32 v120, v210, v218
	v_fma_f32 v254, -v220, v157, v44
	v_mul_f32_e32 v44, v219, v157
	v_add_f32_e32 v219, v242, v244
	v_fma_f32 v209, v211, v217, v120
	v_mul_f32_e32 v120, v213, v213
	v_fma_f32 v212, v220, v156, v44
	v_mul_f32_e32 v44, v222, v155
	v_add_f32_e32 v220, v243, v245
	v_sub_f32_e32 v222, v242, v244
	v_fma_f32 v206, -v214, v214, v120
	v_mul_f32_e32 v120, v213, v214
	v_fma_f32 v151, -v223, v155, v44
	v_fma_f32 v170, v223, v155, v44
	v_mul_f32_e32 v44, v224, v157
	v_sub_f32_e32 v223, v243, v245
	v_add_f32_e32 v45, v220, v228
	v_sub_f32_e32 v228, v220, v228
	v_fma_f32 v207, v214, v213, v120
	v_mul_f32_e32 v120, v210, v213
	v_fma_f32 v171, -v225, v156, v44
	v_mul_f32_e32 v44, v224, v156
	v_add_f32_e32 v224, v236, v246
	v_sub_f32_e32 v236, v237, v247
	v_sub_f32_e32 v242, v223, v230
	v_add_f32_e32 v220, v223, v230
	v_add_f32_e32 v223, v251, v229
	v_fma_f32 v225, v225, v157, v44
	v_add_f32_e32 v44, v219, v224
	v_sub_f32_e32 v227, v219, v224
	v_add_f32_e32 v237, v222, v236
	v_sub_f32_e32 v219, v222, v236
	v_add_f32_e32 v222, v250, v233
	v_sub_f32_e32 v224, v250, v233
	v_sub_f32_e32 v233, v251, v229
	v_add_f32_e32 v229, v232, v239
	v_add_f32_e32 v230, v221, v240
	v_sub_f32_e32 v232, v232, v239
	v_sub_f32_e32 v221, v221, v240
	v_fma_f32 v204, -v211, v214, v120
	v_mul_f32_e32 v120, v210, v214
	v_add_f32_e32 v236, v222, v229
	v_add_f32_e32 v239, v223, v230
	v_sub_f32_e32 v229, v222, v229
	v_sub_f32_e32 v230, v223, v230
	v_add_f32_e32 v240, v224, v221
	v_sub_f32_e32 v243, v233, v232
	v_sub_f32_e32 v221, v224, v221
	v_add_f32_e32 v222, v233, v232
	v_add_f32_e32 v223, v234, v238
	v_add_f32_e32 v224, v235, v249
	v_sub_f32_e32 v233, v234, v238
	v_sub_f32_e32 v234, v235, v249
	v_add_f32_e32 v232, v241, v253
	v_add_f32_e32 v235, v248, v231
	v_sub_f32_e32 v238, v241, v253
	v_sub_f32_e32 v241, v248, v231
	v_fma_f32 v205, v211, v213, v120
	v_mul_f32_e32 v120, v210, v210
	v_add_f32_e32 v244, v223, v232
	v_add_f32_e32 v245, v224, v235
	v_sub_f32_e32 v231, v223, v232
	v_sub_f32_e32 v232, v224, v235
	v_add_f32_e32 v235, v233, v241
	v_sub_f32_e32 v246, v234, v238
	v_sub_f32_e32 v223, v233, v241
	v_add_f32_e32 v224, v234, v238
	v_add_f32_e32 v233, v252, v151
	v_add_f32_e32 v234, v226, v170
	v_sub_f32_e32 v151, v252, v151
	v_sub_f32_e32 v170, v226, v170
	v_add_f32_e32 v226, v254, v171
	v_add_f32_e32 v238, v212, v225
	v_sub_f32_e32 v171, v254, v171
	v_sub_f32_e32 v212, v212, v225
	v_fma_f32 v202, -v211, v211, v120
	v_mul_f32_e32 v120, v210, v211
	v_add_f32_e32 v241, v233, v226
	v_add_f32_e32 v247, v234, v238
	v_sub_f32_e32 v233, v233, v226
	v_sub_f32_e32 v234, v234, v238
	v_add_f32_e32 v238, v151, v212
	v_sub_f32_e32 v248, v170, v171
	v_sub_f32_e32 v225, v151, v212
	v_add_f32_e32 v226, v170, v171
	v_add_f32_e32 v151, v38, v46
	v_add_f32_e32 v170, v39, v47
	v_sub_f32_e32 v38, v38, v46
	v_sub_f32_e32 v39, v39, v47
	v_add_f32_e32 v46, v42, v48
	v_add_f32_e32 v47, v43, v49
	v_sub_f32_e32 v42, v42, v48
	v_sub_f32_e32 v43, v43, v49
	v_fma_f32 v203, v211, v210, v120
	v_mul_f32_e32 v120, v202, v217
	v_add_f32_e32 v48, v151, v46
	v_add_f32_e32 v49, v170, v47
	v_sub_f32_e32 v46, v151, v46
	v_sub_f32_e32 v47, v170, v47
	v_add_f32_e32 v151, v38, v43
	v_sub_f32_e32 v170, v39, v42
	v_sub_f32_e32 v38, v38, v43
	v_add_f32_e32 v39, v39, v42
	v_add_f32_e32 v42, v22, v36
	v_add_f32_e32 v43, v23, v37
	v_sub_f32_e32 v22, v22, v36
	v_sub_f32_e32 v23, v23, v37
	v_add_f32_e32 v36, v26, v40
	v_add_f32_e32 v37, v27, v41
	v_sub_f32_e32 v26, v26, v40
	v_sub_f32_e32 v27, v27, v41
	v_fma_f32 v200, -v203, v218, v120
	v_mul_f32_e32 v120, v202, v218
	v_add_f32_e32 v40, v42, v36
	v_add_f32_e32 v41, v43, v37
	v_sub_f32_e32 v36, v42, v36
	v_sub_f32_e32 v37, v43, v37
	v_add_f32_e32 v42, v22, v27
	v_sub_f32_e32 v43, v23, v26
	v_sub_f32_e32 v22, v22, v27
	v_add_f32_e32 v23, v23, v26
	v_add_f32_e32 v26, v14, v20
	v_add_f32_e32 v27, v15, v21
	v_sub_f32_e32 v14, v14, v20
	v_sub_f32_e32 v15, v15, v21
	v_add_f32_e32 v20, v18, v24
	v_add_f32_e32 v21, v19, v25
	v_sub_f32_e32 v18, v18, v24
	v_sub_f32_e32 v19, v19, v25
	v_fma_f32 v201, v203, v217, v120
	v_mul_f32_e32 v120, v208, v208
	v_add_f32_e32 v24, v26, v20
	v_add_f32_e32 v25, v27, v21
	v_sub_f32_e32 v20, v26, v20
	v_sub_f32_e32 v21, v27, v21
	v_add_f32_e32 v26, v14, v19
	v_sub_f32_e32 v27, v15, v18
	v_sub_f32_e32 v14, v14, v19
	v_add_f32_e32 v15, v15, v18
	v_add_f32_e32 v18, v8, v12
	v_add_f32_e32 v19, v9, v13
	v_sub_f32_e32 v8, v8, v12
	v_sub_f32_e32 v9, v9, v13
	v_add_f32_e32 v12, v10, v16
	v_add_f32_e32 v13, v11, v17
	v_sub_f32_e32 v10, v10, v16
	v_sub_f32_e32 v11, v11, v17
	v_mul_f32_e32 v14, v14, v155
	v_add_f32_e32 v171, v48, v24
	v_add_f32_e32 v16, v18, v12
	v_add_f32_e32 v17, v19, v13
	v_sub_f32_e32 v12, v18, v12
	v_sub_f32_e32 v13, v19, v13
	v_add_f32_e32 v18, v8, v11
	v_sub_f32_e32 v19, v9, v10
	v_sub_f32_e32 v8, v8, v11
	v_add_f32_e32 v9, v9, v10
	v_mul_f32_e32 v10, v42, v152
	v_mul_f32_e32 v11, v42, v153
	v_mul_f32_e32 v42, v26, v154
	v_mul_f32_e32 v26, v26, v155
	v_mul_f32_e32 v12, v12, v155
	v_add_f32_e32 v212, v49, v25
	v_fma_f32 v10, -v43, v153, v10
	v_fma_f32 v11, v43, v152, v11
	v_fma_f32 v42, -v27, v155, v42
	v_fma_f32 v26, v27, v154, v26
	v_mul_f32_e32 v27, v18, v156
	v_mul_f32_e32 v18, v18, v157
	v_sub_f32_e32 v24, v48, v24
	v_sub_f32_e32 v25, v49, v25
	v_add_f32_e32 v48, v40, v16
	v_add_f32_e32 v49, v41, v17
	v_fma_f32 v27, -v19, v157, v27
	v_fma_f32 v18, v19, v156, v18
	v_mul_f32_e32 v19, v36, v154
	v_mul_f32_e32 v36, v36, v155
	v_sub_f32_e32 v16, v40, v16
	v_sub_f32_e32 v17, v41, v17
	v_xor_b32_e32 v20, 0x80000000, v20
	v_fma_f32 v19, -v37, v155, v19
	v_fma_f32 v36, v37, v154, v36
	v_fma_f32 v37, -v13, v155, v12
	v_fma_f32 v12, v13, v155, v12
	v_mul_f32_e32 v13, v22, v156
	v_mul_f32_e32 v22, v22, v157
	v_sub_f32_e32 v40, v171, v48
	v_sub_f32_e32 v41, v212, v49
	v_fma_f32 v198, -v209, v209, v120
	v_mul_f32_e32 v120, v208, v209
	v_fma_f32 v13, -v23, v157, v13
	v_fma_f32 v22, v23, v156, v22
	v_fma_f32 v23, -v15, v155, v14
	v_fma_f32 v14, v15, v155, v14
	v_mul_f32_e32 v15, v8, v157
	v_mul_f32_e32 v8, v8, v156
	v_fma_f32 v199, v209, v208, v120
	v_mul_f32_e32 v120, v202, v213
	v_mul_f32_e32 v122, v202, v205
	v_fma_f32 v15, -v9, v156, v15
	v_fma_f32 v43, v9, v157, v8
	v_add_f32_e32 v8, v171, v48
	v_add_f32_e32 v9, v212, v49
	v_add_f32_e32 v48, v24, v17
	v_sub_f32_e32 v49, v25, v16
	v_sub_f32_e32 v17, v24, v17
	v_add_f32_e32 v16, v25, v16
	v_add_f32_e32 v24, v151, v42
	v_add_f32_e32 v25, v170, v26
	v_sub_f32_e32 v42, v151, v42
	v_sub_f32_e32 v26, v170, v26
	v_add_f32_e32 v151, v10, v27
	v_add_f32_e32 v170, v11, v18
	v_sub_f32_e32 v10, v10, v27
	v_sub_f32_e32 v11, v11, v18
	ds_write_b64 v138, v[44:45]
	ds_write_b64 v137, v[8:9] offset:4096
	v_add_f32_e32 v18, v24, v151
	v_add_f32_e32 v27, v25, v170
	v_sub_f32_e32 v24, v24, v151
	v_sub_f32_e32 v25, v25, v170
	v_add_f32_e32 v151, v42, v11
	v_sub_f32_e32 v170, v26, v10
	v_sub_f32_e32 v42, v42, v11
	v_add_f32_e32 v26, v26, v10
	v_add_f32_e32 v10, v46, v21
	v_add_f32_e32 v11, v47, v20
	v_sub_f32_e32 v21, v46, v21
	v_sub_f32_e32 v20, v47, v20
	v_add_f32_e32 v46, v19, v37
	v_add_f32_e32 v47, v36, v12
	v_sub_f32_e32 v19, v19, v37
	v_sub_f32_e32 v12, v36, v12
	v_mul_f32_e32 v8, v236, v217
	v_mul_f32_e32 v9, v236, v218
	v_add_f32_e32 v36, v10, v46
	v_add_f32_e32 v37, v11, v47
	v_sub_f32_e32 v46, v10, v46
	v_sub_f32_e32 v47, v11, v47
	v_add_f32_e32 v171, v21, v12
	v_sub_f32_e32 v212, v20, v19
	v_sub_f32_e32 v12, v21, v12
	v_add_f32_e32 v19, v20, v19
	v_add_f32_e32 v10, v38, v23
	v_add_f32_e32 v11, v39, v14
	v_sub_f32_e32 v20, v38, v23
	v_add_f32_e32 v21, v13, v15
	v_add_f32_e32 v23, v22, v43
	v_sub_f32_e32 v13, v13, v15
	v_sub_f32_e32 v15, v22, v43
	v_fma_f32 v8, -v239, v218, v8
	v_fma_f32 v9, v239, v217, v9
	v_add_f32_e32 v22, v10, v21
	v_add_f32_e32 v38, v11, v23
	v_sub_f32_e32 v21, v10, v21
	v_sub_f32_e32 v23, v11, v23
	v_mul_f32_e32 v10, v18, v217
	v_mul_f32_e32 v11, v18, v218
	v_sub_f32_e32 v14, v39, v14
	v_add_f32_e32 v39, v20, v15
	v_fma_f32 v196, -v203, v214, v120
	v_mul_f32_e32 v120, v202, v214
	v_fma_f32 v10, -v27, v218, v10
	v_fma_f32 v11, v27, v217, v11
	ds_write_b64 v138, v[8:9] offset:544
	ds_write_b64 v137, v[10:11] offset:4640
	v_mul_f32_e32 v8, v244, v215
	v_mul_f32_e32 v9, v244, v216
	v_mul_f32_e32 v10, v36, v215
	v_mul_f32_e32 v11, v36, v216
	v_sub_f32_e32 v43, v14, v13
	v_fma_f32 v197, v203, v213, v120
	v_fma_f32 v8, -v245, v216, v8
	v_fma_f32 v9, v245, v215, v9
	v_fma_f32 v10, -v37, v216, v10
	v_fma_f32 v11, v37, v215, v11
	ds_write_b64 v138, v[8:9] offset:1088
	ds_write_b64 v137, v[10:11] offset:5184
	v_mul_f32_e32 v8, v241, v213
	v_mul_f32_e32 v9, v241, v214
	v_mul_f32_e32 v10, v22, v213
	v_mul_f32_e32 v11, v22, v214
	v_mul_f32_e32 v120, v206, v206
	v_fma_f32 v122, v203, v204, v122
	v_fma_f32 v8, -v247, v214, v8
	v_fma_f32 v9, v247, v213, v9
	v_fma_f32 v10, -v38, v214, v10
	v_fma_f32 v11, v38, v213, v11
	ds_write_b64 v138, v[8:9] offset:1632
	ds_write_b64 v137, v[10:11] offset:5728
	v_mul_f32_e32 v8, v237, v210
	v_mul_f32_e32 v9, v237, v211
	v_mul_f32_e32 v10, v48, v210
	v_mul_f32_e32 v11, v48, v211
	v_fma_f32 v132, -v207, v207, v120
	v_mul_f32_e32 v120, v206, v207
	v_fma_f32 v8, -v242, v211, v8
	v_fma_f32 v9, v242, v210, v9
	v_fma_f32 v10, -v49, v211, v10
	v_fma_f32 v11, v49, v210, v11
	ds_write_b64 v138, v[8:9] offset:2176
	ds_write_b64 v137, v[10:11] offset:6272
	v_mul_f32_e32 v8, v240, v208
	v_mul_f32_e32 v9, v240, v209
	v_mul_f32_e32 v10, v151, v208
	v_mul_f32_e32 v11, v151, v209
	v_fma_f32 v134, v207, v206, v120
	v_mul_f32_e32 v120, v202, v208
	v_fma_f32 v8, -v243, v209, v8
	v_fma_f32 v9, v243, v208, v9
	v_fma_f32 v10, -v170, v209, v10
	v_fma_f32 v11, v170, v208, v11
	ds_write_b64 v138, v[8:9] offset:2720
	ds_write_b64 v137, v[10:11] offset:6816
	v_mul_f32_e32 v8, v235, v206
	v_mul_f32_e32 v9, v235, v207
	v_mul_f32_e32 v10, v171, v206
	v_mul_f32_e32 v11, v171, v207
	v_fma_f32 v128, -v203, v209, v120
	v_mul_f32_e32 v120, v202, v209
	v_fma_f32 v8, -v246, v207, v8
	v_fma_f32 v9, v246, v206, v9
	v_fma_f32 v10, -v212, v207, v10
	v_fma_f32 v11, v212, v206, v11
	ds_write_b64 v138, v[8:9] offset:3264
	ds_write_b64 v137, v[10:11] offset:7360
	v_mul_f32_e32 v8, v238, v204
	v_mul_f32_e32 v9, v238, v205
	v_mul_f32_e32 v10, v39, v204
	v_mul_f32_e32 v11, v39, v205
	v_fma_f32 v130, v203, v208, v120
	v_mul_f32_e32 v120, v204, v204
	v_fma_f32 v8, -v248, v205, v8
	v_fma_f32 v9, v248, v204, v9
	v_fma_f32 v10, -v43, v205, v10
	v_fma_f32 v11, v43, v204, v11
	ds_write_b64 v138, v[8:9] offset:3808
	ds_write_b64 v137, v[10:11] offset:7904
	v_mul_f32_e32 v8, v227, v202
	v_mul_f32_e32 v9, v227, v203
	v_mul_f32_e32 v10, v40, v202
	v_mul_f32_e32 v11, v40, v203
	v_fma_f32 v124, -v205, v205, v120
	v_mul_f32_e32 v120, v204, v205
	v_fma_f32 v8, -v228, v203, v8
	v_fma_f32 v9, v228, v202, v9
	v_fma_f32 v10, -v41, v203, v10
	v_fma_f32 v11, v41, v202, v11
	ds_write_b64 v138, v[8:9] offset:4352
	ds_write_b64 v137, v[10:11] offset:8448
	v_mul_f32_e32 v8, v229, v200
	v_mul_f32_e32 v9, v229, v201
	v_mul_f32_e32 v10, v24, v200
	v_mul_f32_e32 v11, v24, v201
	v_fma_f32 v126, v205, v204, v120
	v_mul_f32_e32 v120, v202, v204
	v_fma_f32 v8, -v230, v201, v8
	v_fma_f32 v9, v230, v200, v9
	v_fma_f32 v10, -v25, v201, v10
	v_fma_f32 v11, v25, v200, v11
	ds_write_b64 v138, v[8:9] offset:4896
	ds_write_b64 v137, v[10:11] offset:8992
	v_mul_f32_e32 v8, v231, v198
	v_mul_f32_e32 v9, v231, v199
	v_mul_f32_e32 v10, v46, v198
	v_mul_f32_e32 v11, v46, v199
	v_fma_f32 v120, -v203, v205, v120
	v_sub_f32_e32 v15, v20, v15
	v_fma_f32 v8, -v232, v199, v8
	v_fma_f32 v9, v232, v198, v9
	v_fma_f32 v10, -v47, v199, v10
	v_fma_f32 v11, v47, v198, v11
	ds_write_b64 v138, v[8:9] offset:5440
	ds_write_b64 v137, v[10:11] offset:9536
	v_mul_f32_e32 v8, v233, v196
	v_mul_f32_e32 v9, v233, v197
	v_mul_f32_e32 v10, v21, v196
	v_mul_f32_e32 v11, v21, v197
	v_add_f32_e32 v13, v14, v13
	v_mov_b32_e32 v217, v144
	v_fma_f32 v8, -v234, v197, v8
	v_fma_f32 v9, v234, v196, v9
	v_fma_f32 v10, -v23, v197, v10
	v_fma_f32 v11, v23, v196, v11
	ds_write_b64 v138, v[8:9] offset:5984
	ds_write_b64 v137, v[10:11] offset:10080
	v_mul_f32_e32 v8, v219, v132
	v_mul_f32_e32 v9, v219, v134
	v_mul_f32_e32 v10, v17, v132
	v_mul_f32_e32 v11, v17, v134
	v_fma_f32 v8, -v220, v134, v8
	v_fma_f32 v9, v220, v132, v9
	v_fma_f32 v10, -v16, v134, v10
	v_fma_f32 v11, v16, v132, v11
	ds_write_b64 v138, v[8:9] offset:6528
	ds_write_b64 v137, v[10:11] offset:10624
	v_mul_f32_e32 v8, v221, v128
	v_mul_f32_e32 v9, v221, v130
	v_mul_f32_e32 v10, v42, v128
	v_mul_f32_e32 v11, v42, v130
	v_fma_f32 v8, -v222, v130, v8
	v_fma_f32 v9, v222, v128, v9
	v_fma_f32 v10, -v26, v130, v10
	v_fma_f32 v11, v26, v128, v11
	ds_write_b64 v138, v[8:9] offset:7072
	ds_write_b64 v137, v[10:11] offset:11168
	v_mul_f32_e32 v8, v223, v124
	v_mul_f32_e32 v9, v223, v126
	v_mul_f32_e32 v10, v12, v124
	v_mul_f32_e32 v11, v12, v126
	v_fma_f32 v8, -v224, v126, v8
	v_fma_f32 v9, v224, v124, v9
	v_fma_f32 v10, -v19, v126, v10
	v_fma_f32 v11, v19, v124, v11
	ds_write_b64 v138, v[8:9] offset:7616
	ds_write_b64 v137, v[10:11] offset:11712
	v_mul_f32_e32 v8, v225, v120
	v_mul_f32_e32 v9, v225, v122
	v_mul_f32_e32 v10, v15, v120
	v_mul_f32_e32 v11, v15, v122
	v_fma_f32 v8, -v226, v122, v8
	v_fma_f32 v9, v226, v120, v9
	v_fma_f32 v10, -v13, v122, v10
	v_fma_f32 v11, v13, v120, v11
	ds_write_b64 v138, v[8:9] offset:8160
	ds_write_b64 v137, v[10:11] offset:12256
	ds_read_b64 v[44:45], v93
	ds_read_b64 v[38:39], v141 offset:4096
	ds_read_b64 v[220:221], v93 offset:32
	ds_read_b64 v[22:23], v141 offset:4128
	ds_read_b64 v[222:223], v93 offset:64
	ds_read_b64 v[14:15], v141 offset:4160
	ds_read_b64 v[224:225], v93 offset:96
	ds_read_b64 v[8:9], v141 offset:4192
	ds_read_b64 v[226:227], v93 offset:128
	ds_read_b64 v[42:43], v141 offset:4224
	ds_read_b64 v[228:229], v93 offset:160
	ds_read_b64 v[26:27], v141 offset:4256
	ds_read_b64 v[230:231], v93 offset:192
	ds_read_b64 v[18:19], v141 offset:4288
	ds_read_b64 v[232:233], v93 offset:224
	ds_read_b64 v[10:11], v141 offset:4320
	ds_read_b64 v[234:235], v93 offset:256
	ds_read_b64 v[46:47], v141 offset:4352
	ds_read_b64 v[236:237], v93 offset:288
	ds_read_b64 v[36:37], v141 offset:4384
	ds_read_b64 v[238:239], v93 offset:320
	ds_read_b64 v[20:21], v141 offset:4416
	ds_read_b64 v[240:241], v93 offset:352
	ds_read_b64 v[12:13], v141 offset:4448
	ds_read_b64 v[242:243], v93 offset:384
	ds_read_b64 v[48:49], v141 offset:4480
	ds_read_b64 v[244:245], v93 offset:416
	ds_read_b64 v[40:41], v141 offset:4512
	ds_read_b64 v[246:247], v93 offset:448
	ds_read_b64 v[24:25], v141 offset:4544
	ds_read_b64 v[248:249], v93 offset:480
	ds_read_b64 v[16:17], v141 offset:4576
	s_waitcnt lgkmcnt(0)
	v_add_f32_e32 v151, v44, v234
	v_add_f32_e32 v170, v45, v235
	v_sub_f32_e32 v44, v44, v234
	v_sub_f32_e32 v45, v45, v235
	v_add_f32_e32 v171, v226, v242
	v_add_f32_e32 v212, v227, v243
	v_sub_f32_e32 v219, v226, v242
	v_sub_f32_e32 v226, v227, v243
	v_mov_b32_e32 v120, v143
	v_add_f32_e32 v227, v151, v171
	v_add_f32_e32 v234, v170, v212
	v_sub_f32_e32 v151, v151, v171
	v_sub_f32_e32 v170, v170, v212
	v_add_f32_e32 v171, v44, v226
	v_sub_f32_e32 v212, v45, v219
	v_sub_f32_e32 v226, v44, v226
	v_add_f32_e32 v235, v45, v219
	v_add_f32_e32 v44, v220, v236
	v_add_f32_e32 v45, v221, v237
	v_sub_f32_e32 v219, v220, v236
	v_sub_f32_e32 v220, v221, v237
	v_add_f32_e32 v221, v228, v244
	v_add_f32_e32 v236, v229, v245
	v_sub_f32_e32 v228, v228, v244
	v_sub_f32_e32 v229, v229, v245
	s_nop 1
	v_add_f32_e32 v237, v44, v221
	v_add_f32_e32 v242, v45, v236
	v_sub_f32_e32 v44, v44, v221
	v_sub_f32_e32 v45, v45, v236
	v_add_f32_e32 v221, v219, v229
	v_sub_f32_e32 v236, v220, v228
	v_sub_f32_e32 v219, v219, v229
	v_add_f32_e32 v220, v220, v228
	v_add_f32_e32 v228, v222, v238
	v_add_f32_e32 v229, v223, v239
	v_sub_f32_e32 v222, v222, v238
	v_sub_f32_e32 v223, v223, v239
	v_add_f32_e32 v238, v230, v246
	v_add_f32_e32 v239, v231, v247
	v_sub_f32_e32 v230, v230, v246
	v_sub_f32_e32 v231, v231, v247
	v_xor_b32_e32 v218, 0x80000000, v120
	v_add_f32_e32 v243, v228, v238
	v_add_f32_e32 v244, v229, v239
	v_sub_f32_e32 v228, v228, v238
	v_sub_f32_e32 v238, v229, v239
	v_add_f32_e32 v229, v222, v231
	v_sub_f32_e32 v239, v223, v230
	v_sub_f32_e32 v222, v222, v231
	v_add_f32_e32 v223, v223, v230
	v_add_f32_e32 v230, v224, v240
	v_add_f32_e32 v231, v225, v241
	v_sub_f32_e32 v224, v224, v240
	v_sub_f32_e32 v225, v225, v241
	v_add_f32_e32 v240, v232, v248
	v_add_f32_e32 v241, v233, v249
	v_sub_f32_e32 v232, v232, v248
	v_sub_f32_e32 v233, v233, v249
	v_xor_b32_e32 v247, 0x80000000, v228
	v_add_f32_e32 v245, v230, v240
	v_add_f32_e32 v246, v231, v241
	v_sub_f32_e32 v230, v230, v240
	v_sub_f32_e32 v231, v231, v241
	v_add_f32_e32 v240, v224, v233
	v_sub_f32_e32 v241, v225, v232
	v_sub_f32_e32 v224, v224, v233
	v_add_f32_e32 v225, v225, v232
	v_mul_f32_e32 v232, v221, v152
	v_mul_f32_e32 v221, v221, v153
	v_mul_f32_e32 v233, v229, v154
	v_mul_f32_e32 v229, v229, v155
	v_add_f32_e32 v228, v242, v246
	v_mul_f32_e32 v120, v217, v217
	v_fma_f32 v232, -v236, v153, v232
	v_fma_f32 v221, v236, v152, v221
	v_fma_f32 v233, -v239, v155, v233
	v_fma_f32 v229, v239, v154, v229
	v_mul_f32_e32 v236, v240, v156
	v_mul_f32_e32 v239, v240, v157
	v_mul_f32_e32 v240, v44, v154
	v_mul_f32_e32 v44, v44, v155
	v_fma_f32 v215, -v218, v218, v120
	v_mul_f32_e32 v120, v217, v218
	v_fma_f32 v236, -v241, v157, v236
	v_fma_f32 v239, v241, v156, v239
	v_fma_f32 v240, -v45, v155, v240
	v_fma_f32 v241, v45, v154, v44
	v_mul_f32_e32 v44, v230, v155
	v_sub_f32_e32 v230, v237, v245
	v_fma_f32 v216, v218, v217, v120
	v_mul_f32_e32 v120, v215, v217
	v_fma_f32 v248, -v231, v155, v44
	v_fma_f32 v231, v231, v155, v44
	v_mul_f32_e32 v44, v219, v156
	v_fma_f32 v213, -v216, v218, v120
	v_mul_f32_e32 v120, v215, v218
	v_fma_f32 v249, -v220, v157, v44
	v_mul_f32_e32 v44, v219, v157
	v_add_f32_e32 v219, v227, v243
	v_fma_f32 v214, v216, v217, v120
	v_mul_f32_e32 v120, v215, v215
	v_fma_f32 v250, v220, v156, v44
	v_mul_f32_e32 v44, v222, v155
	v_add_f32_e32 v220, v234, v244
	v_sub_f32_e32 v222, v227, v243
	v_fma_f32 v210, -v216, v216, v120
	v_mul_f32_e32 v120, v215, v216
	v_fma_f32 v251, -v223, v155, v44
	v_fma_f32 v252, v223, v155, v44
	v_mul_f32_e32 v44, v224, v157
	v_sub_f32_e32 v223, v234, v244
	v_sub_f32_e32 v234, v242, v246
	v_add_f32_e32 v45, v220, v228
	v_sub_f32_e32 v228, v220, v228
	v_fma_f32 v211, v216, v215, v120
	v_fma_f32 v253, -v225, v156, v44
	v_mul_f32_e32 v44, v224, v156
	v_add_f32_e32 v224, v237, v245
	v_add_f32_e32 v237, v222, v234
	v_sub_f32_e32 v242, v223, v230
	v_add_f32_e32 v220, v223, v230
	v_add_f32_e32 v223, v212, v229
	v_fma_f32 v225, v225, v157, v44
	v_add_f32_e32 v44, v219, v224
	v_sub_f32_e32 v227, v219, v224
	v_sub_f32_e32 v219, v222, v234
	v_add_f32_e32 v222, v171, v233
	v_sub_f32_e32 v171, v171, v233
	v_sub_f32_e32 v212, v212, v229
	v_add_f32_e32 v224, v232, v236
	v_add_f32_e32 v230, v221, v239
	v_sub_f32_e32 v221, v221, v239
	v_sub_f32_e32 v232, v232, v236
	v_sub_f32_e32 v233, v240, v248
	v_sub_f32_e32 v234, v241, v231
	v_add_f32_e32 v236, v222, v224
	v_add_f32_e32 v239, v223, v230
	v_sub_f32_e32 v229, v222, v224
	v_sub_f32_e32 v230, v223, v230
	v_add_f32_e32 v243, v171, v221
	v_sub_f32_e32 v244, v212, v232
	v_sub_f32_e32 v221, v171, v221
	v_add_f32_e32 v222, v212, v232
	v_add_f32_e32 v171, v151, v238
	v_add_f32_e32 v212, v170, v247
	v_sub_f32_e32 v151, v151, v238
	v_sub_f32_e32 v170, v170, v247
	v_add_f32_e32 v223, v240, v248
	v_add_f32_e32 v224, v241, v231
	v_sub_f32_e32 v241, v249, v253
	v_mul_f32_e32 v120, v210, v217
	v_add_f32_e32 v238, v171, v223
	v_add_f32_e32 v240, v212, v224
	v_sub_f32_e32 v231, v171, v223
	v_sub_f32_e32 v232, v212, v224
	v_add_f32_e32 v171, v151, v234
	v_sub_f32_e32 v212, v170, v233
	v_sub_f32_e32 v223, v151, v234
	v_add_f32_e32 v224, v170, v233
	v_add_f32_e32 v151, v226, v251
	v_add_f32_e32 v170, v235, v252
	v_sub_f32_e32 v226, v226, v251
	v_sub_f32_e32 v235, v235, v252
	v_add_f32_e32 v233, v249, v253
	v_add_f32_e32 v234, v250, v225
	v_sub_f32_e32 v225, v250, v225
	v_fma_f32 v208, -v211, v218, v120
	v_mul_f32_e32 v120, v210, v218
	v_add_f32_e32 v245, v151, v233
	v_add_f32_e32 v246, v170, v234
	v_sub_f32_e32 v233, v151, v233
	v_sub_f32_e32 v234, v170, v234
	v_add_f32_e32 v151, v226, v225
	v_sub_f32_e32 v170, v235, v241
	v_sub_f32_e32 v225, v226, v225
	v_add_f32_e32 v226, v235, v241
	v_add_f32_e32 v235, v38, v46
	v_add_f32_e32 v241, v39, v47
	v_sub_f32_e32 v38, v38, v46
	v_sub_f32_e32 v39, v39, v47
	v_add_f32_e32 v46, v42, v48
	v_add_f32_e32 v47, v43, v49
	v_sub_f32_e32 v42, v42, v48
	v_sub_f32_e32 v43, v43, v49
	v_fma_f32 v209, v211, v217, v120
	v_mul_f32_e32 v120, v213, v213
	v_add_f32_e32 v48, v235, v46
	v_add_f32_e32 v49, v241, v47
	v_sub_f32_e32 v46, v235, v46
	v_sub_f32_e32 v47, v241, v47
	v_add_f32_e32 v235, v38, v43
	v_sub_f32_e32 v241, v39, v42
	v_sub_f32_e32 v38, v38, v43
	v_add_f32_e32 v39, v39, v42
	v_add_f32_e32 v42, v22, v36
	v_add_f32_e32 v43, v23, v37
	v_sub_f32_e32 v22, v22, v36
	v_sub_f32_e32 v23, v23, v37
	v_add_f32_e32 v36, v26, v40
	v_add_f32_e32 v37, v27, v41
	v_sub_f32_e32 v26, v26, v40
	v_sub_f32_e32 v27, v27, v41
	v_fma_f32 v206, -v214, v214, v120
	v_mul_f32_e32 v120, v213, v214
	v_add_f32_e32 v40, v42, v36
	v_add_f32_e32 v41, v43, v37
	v_sub_f32_e32 v36, v42, v36
	v_sub_f32_e32 v37, v43, v37
	v_add_f32_e32 v42, v22, v27
	v_sub_f32_e32 v43, v23, v26
	v_sub_f32_e32 v22, v22, v27
	v_add_f32_e32 v23, v23, v26
	v_add_f32_e32 v26, v14, v20
	v_add_f32_e32 v27, v15, v21
	v_sub_f32_e32 v14, v14, v20
	v_sub_f32_e32 v15, v15, v21
	v_add_f32_e32 v20, v18, v24
	v_add_f32_e32 v21, v19, v25
	v_sub_f32_e32 v18, v18, v24
	v_sub_f32_e32 v19, v19, v25
	v_fma_f32 v207, v214, v213, v120
	v_mul_f32_e32 v120, v210, v213
	v_add_f32_e32 v24, v26, v20
	v_add_f32_e32 v25, v27, v21
	v_sub_f32_e32 v20, v26, v20
	v_sub_f32_e32 v21, v27, v21
	v_add_f32_e32 v26, v14, v19
	v_sub_f32_e32 v27, v15, v18
	v_sub_f32_e32 v14, v14, v19
	v_add_f32_e32 v15, v15, v18
	v_add_f32_e32 v18, v8, v12
	v_add_f32_e32 v19, v9, v13
	v_sub_f32_e32 v8, v8, v12
	v_sub_f32_e32 v9, v9, v13
	v_add_f32_e32 v12, v10, v16
	v_add_f32_e32 v13, v11, v17
	v_sub_f32_e32 v10, v10, v16
	v_sub_f32_e32 v11, v11, v17
	v_mul_f32_e32 v14, v14, v155
	v_add_f32_e32 v247, v48, v24
	v_add_f32_e32 v16, v18, v12
	v_add_f32_e32 v17, v19, v13
	v_sub_f32_e32 v12, v18, v12
	v_sub_f32_e32 v13, v19, v13
	v_add_f32_e32 v18, v8, v11
	v_sub_f32_e32 v19, v9, v10
	v_sub_f32_e32 v8, v8, v11
	v_add_f32_e32 v9, v9, v10
	v_mul_f32_e32 v10, v42, v152
	v_mul_f32_e32 v11, v42, v153
	v_mul_f32_e32 v42, v26, v154
	v_mul_f32_e32 v26, v26, v155
	v_mul_f32_e32 v12, v12, v155
	v_add_f32_e32 v248, v49, v25
	v_fma_f32 v10, -v43, v153, v10
	v_fma_f32 v11, v43, v152, v11
	v_fma_f32 v42, -v27, v155, v42
	v_fma_f32 v26, v27, v154, v26
	v_mul_f32_e32 v27, v18, v156
	v_mul_f32_e32 v18, v18, v157
	v_sub_f32_e32 v24, v48, v24
	v_sub_f32_e32 v25, v49, v25
	v_add_f32_e32 v48, v40, v16
	v_add_f32_e32 v49, v41, v17
	v_fma_f32 v27, -v19, v157, v27
	v_fma_f32 v18, v19, v156, v18
	v_mul_f32_e32 v19, v36, v154
	v_mul_f32_e32 v36, v36, v155
	v_sub_f32_e32 v16, v40, v16
	v_sub_f32_e32 v17, v41, v17
	v_xor_b32_e32 v20, 0x80000000, v20
	v_fma_f32 v19, -v37, v155, v19
	v_fma_f32 v36, v37, v154, v36
	v_fma_f32 v37, -v13, v155, v12
	v_fma_f32 v12, v13, v155, v12
	v_mul_f32_e32 v13, v22, v156
	v_mul_f32_e32 v22, v22, v157
	v_sub_f32_e32 v40, v247, v48
	v_sub_f32_e32 v41, v248, v49
	v_fma_f32 v204, -v211, v214, v120
	v_mul_f32_e32 v120, v210, v214
	v_fma_f32 v13, -v23, v157, v13
	v_fma_f32 v22, v23, v156, v22
	v_fma_f32 v23, -v15, v155, v14
	v_fma_f32 v14, v15, v155, v14
	v_mul_f32_e32 v15, v8, v157
	v_mul_f32_e32 v8, v8, v156
	v_fma_f32 v205, v211, v213, v120
	v_mul_f32_e32 v120, v210, v210
	v_fma_f32 v15, -v9, v156, v15
	v_fma_f32 v43, v9, v157, v8
	v_add_f32_e32 v8, v247, v48
	v_add_f32_e32 v9, v248, v49
	v_add_f32_e32 v48, v24, v17
	v_sub_f32_e32 v49, v25, v16
	v_sub_f32_e32 v17, v24, v17
	v_add_f32_e32 v16, v25, v16
	v_add_f32_e32 v24, v235, v42
	v_add_f32_e32 v25, v241, v26
	v_sub_f32_e32 v42, v235, v42
	v_sub_f32_e32 v26, v241, v26
	v_add_f32_e32 v235, v10, v27
	v_add_f32_e32 v241, v11, v18
	v_sub_f32_e32 v10, v10, v27
	v_sub_f32_e32 v11, v11, v18
	ds_write_b64 v142, v[44:45]
	ds_write_b64 v141, v[8:9] offset:4096
	v_add_f32_e32 v18, v24, v235
	v_add_f32_e32 v27, v25, v241
	v_sub_f32_e32 v24, v24, v235
	v_sub_f32_e32 v25, v25, v241
	v_add_f32_e32 v235, v42, v11
	v_sub_f32_e32 v241, v26, v10
	v_sub_f32_e32 v42, v42, v11
	v_add_f32_e32 v26, v26, v10
	v_add_f32_e32 v10, v46, v21
	v_add_f32_e32 v11, v47, v20
	v_sub_f32_e32 v21, v46, v21
	v_sub_f32_e32 v20, v47, v20
	v_add_f32_e32 v46, v19, v37
	v_add_f32_e32 v47, v36, v12
	v_sub_f32_e32 v19, v19, v37
	v_sub_f32_e32 v12, v36, v12
	v_mul_f32_e32 v8, v236, v217
	v_mul_f32_e32 v9, v236, v218
	v_add_f32_e32 v36, v10, v46
	v_add_f32_e32 v37, v11, v47
	v_sub_f32_e32 v46, v10, v46
	v_sub_f32_e32 v47, v11, v47
	v_add_f32_e32 v247, v21, v12
	v_sub_f32_e32 v248, v20, v19
	v_sub_f32_e32 v12, v21, v12
	v_add_f32_e32 v19, v20, v19
	v_add_f32_e32 v10, v38, v23
	v_add_f32_e32 v11, v39, v14
	v_sub_f32_e32 v20, v38, v23
	v_add_f32_e32 v21, v13, v15
	v_add_f32_e32 v23, v22, v43
	v_sub_f32_e32 v13, v13, v15
	v_sub_f32_e32 v15, v22, v43
	v_fma_f32 v8, -v239, v218, v8
	v_fma_f32 v9, v239, v217, v9
	v_add_f32_e32 v22, v10, v21
	v_add_f32_e32 v38, v11, v23
	v_sub_f32_e32 v21, v10, v21
	v_sub_f32_e32 v23, v11, v23
	v_mul_f32_e32 v10, v18, v217
	v_mul_f32_e32 v11, v18, v218
	v_sub_f32_e32 v14, v39, v14
	v_add_f32_e32 v39, v20, v15
	v_fma_f32 v202, -v211, v211, v120
	v_mul_f32_e32 v120, v210, v211
	v_fma_f32 v10, -v27, v218, v10
	v_fma_f32 v11, v27, v217, v11
	ds_write_b64 v142, v[8:9] offset:32
	ds_write_b64 v141, v[10:11] offset:4128
	v_mul_f32_e32 v8, v238, v215
	v_mul_f32_e32 v9, v238, v216
	v_mul_f32_e32 v10, v36, v215
	v_mul_f32_e32 v11, v36, v216
	v_fma_f32 v203, v211, v210, v120
	v_sub_f32_e32 v43, v14, v13
	v_fma_f32 v8, -v240, v216, v8
	v_fma_f32 v9, v240, v215, v9
	v_fma_f32 v10, -v37, v216, v10
	v_fma_f32 v11, v37, v215, v11
	ds_write_b64 v142, v[8:9] offset:64
	ds_write_b64 v141, v[10:11] offset:4160
	v_mul_f32_e32 v8, v245, v213
	v_mul_f32_e32 v9, v245, v214
	v_mul_f32_e32 v10, v22, v213
	v_mul_f32_e32 v11, v22, v214
	v_mul_f32_e32 v120, v202, v217
	v_mul_f32_e32 v122, v202, v205
	v_fma_f32 v8, -v246, v214, v8
	v_fma_f32 v9, v246, v213, v9
	v_fma_f32 v10, -v38, v214, v10
	v_fma_f32 v11, v38, v213, v11
	ds_write_b64 v142, v[8:9] offset:96
	ds_write_b64 v141, v[10:11] offset:4192
	v_mul_f32_e32 v8, v237, v210
	v_mul_f32_e32 v9, v237, v211
	v_mul_f32_e32 v10, v48, v210
	v_mul_f32_e32 v11, v48, v211
	v_fma_f32 v200, -v203, v218, v120
	v_mul_f32_e32 v120, v202, v218
	v_fma_f32 v8, -v242, v211, v8
	v_fma_f32 v9, v242, v210, v9
	v_fma_f32 v10, -v49, v211, v10
	v_fma_f32 v11, v49, v210, v11
	ds_write_b64 v142, v[8:9] offset:128
	ds_write_b64 v141, v[10:11] offset:4224
	v_mul_f32_e32 v8, v243, v208
	v_mul_f32_e32 v9, v243, v209
	v_mul_f32_e32 v10, v235, v208
	v_mul_f32_e32 v11, v235, v209
	v_fma_f32 v201, v203, v217, v120
	v_mul_f32_e32 v120, v208, v208
	v_fma_f32 v8, -v244, v209, v8
	v_fma_f32 v9, v244, v208, v9
	v_fma_f32 v10, -v241, v209, v10
	v_fma_f32 v11, v241, v208, v11
	ds_write_b64 v142, v[8:9] offset:160
	ds_write_b64 v141, v[10:11] offset:4256
	v_mul_f32_e32 v8, v171, v206
	v_mul_f32_e32 v9, v171, v207
	v_mul_f32_e32 v10, v247, v206
	v_mul_f32_e32 v11, v247, v207
	v_fma_f32 v198, -v209, v209, v120
	v_mul_f32_e32 v120, v208, v209
	v_fma_f32 v8, -v212, v207, v8
	v_fma_f32 v9, v212, v206, v9
	v_fma_f32 v10, -v248, v207, v10
	v_fma_f32 v11, v248, v206, v11
	ds_write_b64 v142, v[8:9] offset:192
	ds_write_b64 v141, v[10:11] offset:4288
	v_mul_f32_e32 v8, v151, v204
	v_mul_f32_e32 v9, v151, v205
	v_mul_f32_e32 v10, v39, v204
	v_mul_f32_e32 v11, v39, v205
	v_fma_f32 v199, v209, v208, v120
	v_mul_f32_e32 v120, v202, v213
	v_fma_f32 v8, -v170, v205, v8
	v_fma_f32 v9, v170, v204, v9
	v_fma_f32 v10, -v43, v205, v10
	v_fma_f32 v11, v43, v204, v11
	ds_write_b64 v142, v[8:9] offset:224
	ds_write_b64 v141, v[10:11] offset:4320
	v_mul_f32_e32 v8, v227, v202
	v_mul_f32_e32 v9, v227, v203
	v_mul_f32_e32 v10, v40, v202
	v_mul_f32_e32 v11, v40, v203
	v_fma_f32 v196, -v203, v214, v120
	v_mul_f32_e32 v120, v202, v214
	v_fma_f32 v8, -v228, v203, v8
	v_fma_f32 v9, v228, v202, v9
	v_fma_f32 v10, -v41, v203, v10
	v_fma_f32 v11, v41, v202, v11
	ds_write_b64 v142, v[8:9] offset:256
	ds_write_b64 v141, v[10:11] offset:4352
	v_mul_f32_e32 v8, v229, v200
	v_mul_f32_e32 v9, v229, v201
	v_mul_f32_e32 v10, v24, v200
	v_mul_f32_e32 v11, v24, v201
	v_fma_f32 v197, v203, v213, v120
	v_mul_f32_e32 v120, v206, v206
	v_fma_f32 v8, -v230, v201, v8
	v_fma_f32 v9, v230, v200, v9
	v_fma_f32 v10, -v25, v201, v10
	v_fma_f32 v11, v25, v200, v11
	ds_write_b64 v142, v[8:9] offset:288
	ds_write_b64 v141, v[10:11] offset:4384
	v_mul_f32_e32 v8, v231, v198
	v_mul_f32_e32 v9, v231, v199
	v_mul_f32_e32 v10, v46, v198
	v_mul_f32_e32 v11, v46, v199
	v_fma_f32 v132, -v207, v207, v120
	v_mul_f32_e32 v120, v206, v207
	v_fma_f32 v8, -v232, v199, v8
	v_fma_f32 v9, v232, v198, v9
	v_fma_f32 v10, -v47, v199, v10
	v_fma_f32 v11, v47, v198, v11
	ds_write_b64 v142, v[8:9] offset:320
	ds_write_b64 v141, v[10:11] offset:4416
	v_mul_f32_e32 v8, v233, v196
	v_mul_f32_e32 v9, v233, v197
	v_mul_f32_e32 v10, v21, v196
	v_mul_f32_e32 v11, v21, v197
	v_fma_f32 v134, v207, v206, v120
	v_mul_f32_e32 v120, v202, v208
	v_fma_f32 v8, -v234, v197, v8
	v_fma_f32 v9, v234, v196, v9
	v_fma_f32 v10, -v23, v197, v10
	v_fma_f32 v11, v23, v196, v11
	ds_write_b64 v142, v[8:9] offset:352
	ds_write_b64 v141, v[10:11] offset:4448
	v_mul_f32_e32 v8, v219, v132
	v_mul_f32_e32 v9, v219, v134
	v_mul_f32_e32 v10, v17, v132
	v_mul_f32_e32 v11, v17, v134
	v_fma_f32 v128, -v203, v209, v120
	v_mul_f32_e32 v120, v202, v209
	v_fma_f32 v8, -v220, v134, v8
	v_fma_f32 v9, v220, v132, v9
	v_fma_f32 v10, -v16, v134, v10
	v_fma_f32 v11, v16, v132, v11
	ds_write_b64 v142, v[8:9] offset:384
	ds_write_b64 v141, v[10:11] offset:4480
	v_fma_f32 v130, v203, v208, v120
	v_mul_f32_e32 v8, v221, v128
	v_mul_f32_e32 v120, v204, v204
	v_mul_f32_e32 v10, v42, v128
	v_fma_f32 v122, v203, v204, v122
	v_sub_f32_e32 v15, v20, v15
	v_mul_f32_e32 v9, v221, v130
	v_fma_f32 v8, -v222, v130, v8
	v_mul_f32_e32 v11, v42, v130
	v_fma_f32 v124, -v205, v205, v120
	v_mul_f32_e32 v120, v204, v205
	v_fma_f32 v10, -v26, v130, v10
	v_fma_f32 v9, v222, v128, v9
	v_add_f32_e32 v13, v14, v13
	v_fma_f32 v11, v26, v128, v11
	ds_write_b64 v142, v[8:9] offset:416
	ds_write_b64 v141, v[10:11] offset:4512
	v_fma_f32 v126, v205, v204, v120
	v_mul_f32_e32 v8, v223, v124
	v_mul_f32_e32 v120, v202, v204
	v_mul_f32_e32 v10, v12, v124
	v_cvt_f32_f16_e32 v21, v193
	v_mul_f32_e32 v9, v223, v126
	v_fma_f32 v8, -v224, v126, v8
	v_mul_f32_e32 v11, v12, v126
	v_fma_f32 v120, -v203, v205, v120
	v_fma_f32 v10, -v19, v126, v10
	v_cvt_f32_f16_e32 v20, v190
	v_fma_f32 v9, v224, v124, v9
	v_fma_f32 v11, v19, v124, v11
	ds_write_b64 v142, v[8:9] offset:448
	ds_write_b64 v141, v[10:11] offset:4544
	v_mul_f32_e32 v8, v225, v120
	v_mul_f32_e32 v9, v225, v122
	v_mul_f32_e32 v10, v15, v120
	v_mul_f32_e32 v11, v15, v122
	v_pk_mul_f32 v[18:19], v[82:83], v[34:35] op_sel_hi:[0,1]
	v_fma_f32 v8, -v226, v122, v8
	v_fma_f32 v9, v226, v120, v9
	v_fma_f32 v10, -v13, v122, v10
	v_fma_f32 v11, v13, v120, v11
	ds_write_b64 v142, v[8:9] offset:480
	ds_write_b64 v141, v[10:11] offset:4576
	ds_read_b128 v[10:13], v162
	ds_read_b128 v[14:17], v162 offset:16
	v_pk_mul_f32 v[8:9], v[82:83], v[32:33] op_sel_hi:[0,1]
	v_cvt_pk_f16_f32 v9, v8, v9
	v_cvt_pk_f16_f32 v8, v18, v19
	s_waitcnt lgkmcnt(0)
	v_add_f32_e32 v18, v10, v14
	v_add_f32_e32 v19, v11, v15
	v_sub_f32_e32 v10, v10, v14
	v_sub_f32_e32 v11, v11, v15
	v_add_f32_e32 v14, v12, v16
	v_add_f32_e32 v15, v13, v17
	v_sub_f32_e32 v13, v13, v17
	v_sub_f32_e32 v12, v12, v16
	v_cvt_f32_f16_e32 v24, v195
	v_add_f32_e32 v16, v18, v14
	v_sub_f32_e32 v14, v18, v14
	v_add_f32_e32 v18, v10, v13
	v_sub_f32_e32 v10, v10, v13
	v_cvt_f32_f16_sdwa v13, v193 dst_sel:DWORD dst_unused:UNUSED_PAD src0_sel:WORD_1
	v_add_f32_e32 v17, v19, v15
	v_sub_f32_e32 v15, v19, v15
	v_sub_f32_e32 v19, v11, v12
	v_add_f32_e32 v11, v11, v12
	v_cvt_f32_f16_sdwa v12, v190 dst_sel:DWORD dst_unused:UNUSED_PAD src0_sel:WORD_1
	v_cvt_f32_f16_sdwa v23, v195 dst_sel:DWORD dst_unused:UNUSED_PAD src0_sel:WORD_1
	v_cvt_f32_f16_e32 v25, v192
	v_cvt_f32_f16_sdwa v22, v192 dst_sel:DWORD dst_unused:UNUSED_PAD src0_sel:WORD_1
	v_add_f32_e32 v21, v177, v21
	v_add_f32_e32 v20, v177, v20
	v_mul_f32_e32 v13, v13, v17
	v_mul_f32_e32 v17, v21, v17
	v_add_f32_e32 v24, v177, v24
	v_fma_f32 v13, v21, v16, -v13
	v_fma_mix_f32 v16, v193, v16, v17 op_sel:[1,0,0] op_sel_hi:[1,0,0]
	v_mul_f32_e32 v12, v12, v19
	v_mul_f32_e32 v17, v20, v19
	v_add_f32_e32 v25, v177, v25
	v_fma_f32 v12, v20, v18, -v12
	v_fma_mix_f32 v17, v190, v18, v17 op_sel:[1,0,0] op_sel_hi:[1,0,0]
	v_mul_f32_e32 v18, v23, v15
	v_mul_f32_e32 v15, v24, v15
	v_fma_f32 v18, v24, v14, -v18
	v_fma_mix_f32 v14, v195, v14, v15 op_sel:[1,0,0] op_sel_hi:[1,0,0]
	v_mul_f32_e32 v15, v22, v11
	v_mul_f32_e32 v11, v25, v11
	v_mul_f32_e32 v13, 0x38800000, v13
	v_mul_f32_e32 v18, 0x38800000, v18
	v_fma_f32 v15, v25, v10, -v15
	v_fma_mix_f32 v10, v192, v10, v11 op_sel:[1,0,0] op_sel_hi:[1,0,0]
	v_mul_f32_e32 v16, 0x38800000, v16
	v_mul_f32_e32 v12, 0x38800000, v12
	v_mul_f32_e32 v17, 0x38800000, v17
	v_mul_f32_e32 v14, 0x38800000, v14
	v_mul_f32_e32 v15, 0x38800000, v15
	v_mul_f32_e32 v10, 0x38800000, v10
	v_add_f32_e32 v19, v13, v18
	v_sub_f32_e32 v18, v13, v18
	v_add_f32_e32 v13, v12, v15
	v_add_f32_e32 v20, v16, v14
	v_sub_f32_e32 v21, v16, v14
	v_add_f32_e32 v16, v17, v10
	v_sub_f32_e32 v22, v12, v15
	v_sub_f32_e32 v17, v17, v10
	v_add_f32_e32 v10, v19, v13
	v_sub_f32_e32 v14, v19, v13
	v_cvt_f32_f16_e32 v23, v188
	v_add_f32_e32 v11, v20, v16
	v_sub_f32_e32 v12, v18, v17
	v_add_f32_e32 v13, v21, v22
	v_sub_f32_e32 v15, v20, v16
	v_add_f32_e32 v16, v18, v17
	v_sub_f32_e32 v17, v21, v22
	ds_write_b128 v162, v[10:13]
	ds_write_b128 v162, v[14:17] offset:16
	ds_read_b128 v[12:15], v163
	ds_read_b128 v[16:19], v163 offset:16
	v_pk_mul_f32 v[20:21], v[82:83], v[30:31] op_sel_hi:[0,1]
	v_pk_mul_f32 v[10:11], v[82:83], v[28:29] op_sel_hi:[0,1]
	v_cvt_pk_f16_f32 v11, v10, v11
	v_cvt_pk_f16_f32 v10, v20, v21
	s_waitcnt lgkmcnt(0)
	v_add_f32_e32 v20, v12, v16
	v_add_f32_e32 v21, v13, v17
	v_sub_f32_e32 v12, v12, v16
	v_sub_f32_e32 v13, v13, v17
	v_add_f32_e32 v16, v14, v18
	v_add_f32_e32 v17, v15, v19
	v_sub_f32_e32 v15, v15, v19
	v_sub_f32_e32 v14, v14, v18
	v_cvt_f32_f16_e32 v22, v186
	v_add_f32_e32 v18, v20, v16
	v_sub_f32_e32 v16, v20, v16
	v_add_f32_e32 v20, v12, v15
	v_sub_f32_e32 v12, v12, v15
	v_cvt_f32_f16_sdwa v15, v188 dst_sel:DWORD dst_unused:UNUSED_PAD src0_sel:WORD_1
	v_add_f32_e32 v19, v21, v17
	v_sub_f32_e32 v17, v21, v17
	v_sub_f32_e32 v21, v13, v14
	v_add_f32_e32 v13, v13, v14
	v_cvt_f32_f16_sdwa v14, v186 dst_sel:DWORD dst_unused:UNUSED_PAD src0_sel:WORD_1
	v_cvt_f32_f16_e32 v26, v189
	v_cvt_f32_f16_sdwa v25, v189 dst_sel:DWORD dst_unused:UNUSED_PAD src0_sel:WORD_1
	v_cvt_f32_f16_e32 v27, v187
	v_cvt_f32_f16_sdwa v24, v187 dst_sel:DWORD dst_unused:UNUSED_PAD src0_sel:WORD_1
	v_add_f32_e32 v23, v177, v23
	v_add_f32_e32 v22, v177, v22
	v_mul_f32_e32 v15, v15, v19
	v_mul_f32_e32 v19, v23, v19
	v_add_f32_e32 v26, v177, v26
	v_fma_f32 v15, v23, v18, -v15
	v_fma_mix_f32 v18, v188, v18, v19 op_sel:[1,0,0] op_sel_hi:[1,0,0]
	v_mul_f32_e32 v14, v14, v21
	v_mul_f32_e32 v19, v22, v21
	v_add_f32_e32 v27, v177, v27
	v_fma_f32 v14, v22, v20, -v14
	v_fma_mix_f32 v19, v186, v20, v19 op_sel:[1,0,0] op_sel_hi:[1,0,0]
	v_mul_f32_e32 v20, v25, v17
	v_mul_f32_e32 v17, v26, v17
	v_fma_f32 v20, v26, v16, -v20
	v_fma_mix_f32 v16, v189, v16, v17 op_sel:[1,0,0] op_sel_hi:[1,0,0]
	v_mul_f32_e32 v17, v24, v13
	v_mul_f32_e32 v13, v27, v13
	v_mul_f32_e32 v15, 0x38800000, v15
	v_mul_f32_e32 v20, 0x38800000, v20
	v_fma_f32 v17, v27, v12, -v17
	v_fma_mix_f32 v12, v187, v12, v13 op_sel:[1,0,0] op_sel_hi:[1,0,0]
	v_mul_f32_e32 v18, 0x38800000, v18
	v_mul_f32_e32 v14, 0x38800000, v14
	v_mul_f32_e32 v19, 0x38800000, v19
	v_mul_f32_e32 v16, 0x38800000, v16
	v_mul_f32_e32 v17, 0x38800000, v17
	v_mul_f32_e32 v12, 0x38800000, v12
	v_add_f32_e32 v21, v15, v20
	v_sub_f32_e32 v20, v15, v20
	v_add_f32_e32 v15, v14, v17
	v_add_f32_e32 v22, v18, v16
	v_sub_f32_e32 v23, v18, v16
	v_add_f32_e32 v18, v19, v12
	v_sub_f32_e32 v24, v14, v17
	v_sub_f32_e32 v19, v19, v12
	v_add_f32_e32 v12, v21, v15
	v_sub_f32_e32 v16, v21, v15
	v_add_f32_e32 v21, v1, v5
	v_add_f32_e32 v13, v22, v18
	v_add_f32_e32 v15, v23, v24
	v_sub_f32_e32 v14, v20, v19
	v_sub_f32_e32 v17, v22, v18
	v_add_f32_e32 v18, v20, v19
	v_sub_f32_e32 v19, v23, v24
	ds_write_b128 v163, v[12:15]
	ds_write_b128 v163, v[16:19] offset:16
	ds_read_b128 v[12:15], v164
	ds_read_b128 v[16:19], v164 offset:16
	v_add_f32_e32 v20, v0, v4
	v_sub_f32_e32 v22, v0, v4
	v_sub_f32_e32 v23, v1, v5
	s_waitcnt lgkmcnt(0)
	v_add_f32_e32 v0, v12, v16
	v_add_f32_e32 v1, v13, v17
	v_sub_f32_e32 v4, v12, v16
	v_sub_f32_e32 v5, v13, v17
	v_add_f32_e32 v12, v14, v18
	v_add_f32_e32 v13, v15, v19
	v_sub_f32_e32 v14, v14, v18
	v_cvt_f32_f16_e32 v18, v182
	v_sub_f32_e32 v15, v15, v19
	v_add_f32_e32 v17, v1, v13
	v_sub_f32_e32 v1, v1, v13
	v_sub_f32_e32 v13, v5, v14
	v_add_f32_e32 v5, v5, v14
	v_cvt_f32_f16_sdwa v14, v182 dst_sel:DWORD dst_unused:UNUSED_PAD src0_sel:WORD_1
	v_cvt_f32_f16_e32 v26, v185
	v_add_f32_e32 v16, v0, v12
	v_sub_f32_e32 v0, v0, v12
	v_add_f32_e32 v12, v4, v15
	v_sub_f32_e32 v4, v4, v15
	v_cvt_f32_f16_sdwa v15, v184 dst_sel:DWORD dst_unused:UNUSED_PAD src0_sel:WORD_1
	v_cvt_f32_f16_e32 v19, v184
	v_cvt_f32_f16_sdwa v25, v185 dst_sel:DWORD dst_unused:UNUSED_PAD src0_sel:WORD_1
	v_cvt_f32_f16_e32 v27, v183
	v_cvt_f32_f16_sdwa v24, v183 dst_sel:DWORD dst_unused:UNUSED_PAD src0_sel:WORD_1
	v_add_f32_e32 v18, v177, v18
	v_add_f32_e32 v26, v177, v26
	v_mul_f32_e32 v14, v14, v13
	v_mul_f32_e32 v13, v18, v13
	v_add_f32_e32 v19, v177, v19
	v_add_f32_e32 v27, v177, v27
	v_mul_f32_e32 v15, v15, v17
	v_fma_f32 v14, v18, v12, -v14
	v_fma_mix_f32 v12, v182, v12, v13 op_sel:[1,0,0] op_sel_hi:[1,0,0]
	v_mul_f32_e32 v13, v25, v1
	v_mul_f32_e32 v1, v26, v1
	v_fma_f32 v15, v19, v16, -v15
	v_mul_f32_e32 v17, v19, v17
	v_fma_f32 v13, v26, v0, -v13
	v_fma_mix_f32 v0, v185, v0, v1 op_sel:[1,0,0] op_sel_hi:[1,0,0]
	v_mul_f32_e32 v1, v24, v5
	v_mul_f32_e32 v5, v27, v5
	v_mul_f32_e32 v15, 0x38800000, v15
	v_fma_mix_f32 v16, v184, v16, v17 op_sel:[1,0,0] op_sel_hi:[1,0,0]
	v_fma_f32 v1, v27, v4, -v1
	v_fma_mix_f32 v4, v183, v4, v5 op_sel:[1,0,0] op_sel_hi:[1,0,0]
	v_mul_f32_e32 v16, 0x38800000, v16
	v_mul_f32_e32 v14, 0x38800000, v14
	v_mul_f32_e32 v12, 0x38800000, v12
	v_mul_f32_e32 v13, 0x38800000, v13
	v_mul_f32_e32 v0, 0x38800000, v0
	v_mul_f32_e32 v1, 0x38800000, v1
	v_mul_f32_e32 v4, 0x38800000, v4
	v_add_f32_e32 v5, v15, v13
	v_sub_f32_e32 v18, v15, v13
	v_add_f32_e32 v15, v14, v1
	v_add_f32_e32 v17, v16, v0
	v_sub_f32_e32 v0, v16, v0
	v_add_f32_e32 v19, v12, v4
	v_sub_f32_e32 v1, v14, v1
	v_sub_f32_e32 v4, v12, v4
	v_add_f32_e32 v12, v5, v15
	v_sub_f32_e32 v16, v5, v15
	v_add_f32_e32 v24, v2, v6
	v_add_f32_e32 v13, v17, v19
	v_add_f32_e32 v15, v0, v1
	v_sub_f32_e32 v14, v18, v4
	v_sub_f32_e32 v17, v17, v19
	v_add_f32_e32 v18, v18, v4
	v_sub_f32_e32 v19, v0, v1
	ds_write_b128 v164, v[12:15]
	ds_write_b128 v164, v[16:19] offset:16
	ds_read_b128 v[12:15], v165
	ds_read_b128 v[16:19], v165 offset:16
	v_add_f32_e32 v25, v3, v7
	v_sub_f32_e32 v26, v2, v6
	v_sub_f32_e32 v27, v3, v7
	s_waitcnt lgkmcnt(0)
	v_add_f32_e32 v1, v13, v17
	v_sub_f32_e32 v3, v13, v17
	v_add_f32_e32 v4, v14, v18
	v_add_f32_e32 v5, v15, v19
	v_sub_f32_e32 v6, v14, v18
	v_cvt_f32_f16_e32 v14, v178
	v_add_f32_e32 v13, v1, v5
	v_sub_f32_e32 v1, v1, v5
	v_sub_f32_e32 v5, v3, v6
	v_add_f32_e32 v3, v3, v6
	v_cvt_f32_f16_sdwa v6, v178 dst_sel:DWORD dst_unused:UNUSED_PAD src0_sel:WORD_1
	v_cvt_f32_f16_e32 v18, v181
	v_add_f32_e32 v0, v12, v16
	v_sub_f32_e32 v2, v12, v16
	v_sub_f32_e32 v7, v15, v19
	v_cvt_f32_f16_e32 v15, v180
	v_cvt_f32_f16_sdwa v17, v181 dst_sel:DWORD dst_unused:UNUSED_PAD src0_sel:WORD_1
	v_cvt_f32_f16_e32 v19, v179
	v_add_f32_e32 v12, v0, v4
	v_sub_f32_e32 v0, v0, v4
	v_add_f32_e32 v4, v2, v7
	v_sub_f32_e32 v2, v2, v7
	v_cvt_f32_f16_sdwa v7, v180 dst_sel:DWORD dst_unused:UNUSED_PAD src0_sel:WORD_1
	v_cvt_f32_f16_sdwa v16, v179 dst_sel:DWORD dst_unused:UNUSED_PAD src0_sel:WORD_1
	v_add_f32_e32 v14, v177, v14
	v_add_f32_e32 v18, v177, v18
	v_mul_f32_e32 v6, v6, v5
	v_mul_f32_e32 v5, v14, v5
	v_add_f32_e32 v15, v177, v15
	v_add_f32_e32 v19, v177, v19
	v_fma_f32 v6, v14, v4, -v6
	v_fma_mix_f32 v4, v178, v4, v5 op_sel:[1,0,0] op_sel_hi:[1,0,0]
	v_mul_f32_e32 v5, v17, v1
	v_mul_f32_e32 v1, v18, v1
	v_mul_f32_e32 v7, v7, v13
	v_mul_f32_e32 v13, v15, v13
	v_fma_f32 v5, v18, v0, -v5
	v_fma_mix_f32 v0, v181, v0, v1 op_sel:[1,0,0] op_sel_hi:[1,0,0]
	v_mul_f32_e32 v1, v16, v3
	v_mul_f32_e32 v3, v19, v3
	v_fma_f32 v7, v15, v12, -v7
	v_fma_mix_f32 v12, v180, v12, v13 op_sel:[1,0,0] op_sel_hi:[1,0,0]
	v_fma_f32 v1, v19, v2, -v1
	v_fma_mix_f32 v2, v179, v2, v3 op_sel:[1,0,0] op_sel_hi:[1,0,0]
	v_mul_f32_e32 v7, 0x38800000, v7
	v_mul_f32_e32 v12, 0x38800000, v12
	v_mul_f32_e32 v6, 0x38800000, v6
	v_mul_f32_e32 v4, 0x38800000, v4
	v_mul_f32_e32 v5, 0x38800000, v5
	v_mul_f32_e32 v0, 0x38800000, v0
	v_mul_f32_e32 v1, 0x38800000, v1
	v_mul_f32_e32 v2, 0x38800000, v2
	v_add_f32_e32 v3, v7, v5
	v_add_f32_e32 v13, v12, v0
	v_sub_f32_e32 v7, v7, v5
	v_sub_f32_e32 v12, v12, v0
	v_add_f32_e32 v5, v6, v1
	v_add_f32_e32 v14, v4, v2
	v_sub_f32_e32 v15, v6, v1
	v_sub_f32_e32 v6, v4, v2
	v_cvt_f32_f16_e32 v19, v194
	v_add_f32_e32 v0, v3, v5
	v_add_f32_e32 v1, v13, v14
	v_sub_f32_e32 v4, v3, v5
	v_sub_f32_e32 v2, v7, v6
	v_add_f32_e32 v3, v12, v15
	v_sub_f32_e32 v5, v13, v14
	v_add_f32_e32 v6, v7, v6
	v_sub_f32_e32 v7, v12, v15
	ds_write_b128 v165, v[0:3]
	ds_write_b128 v165, v[4:7] offset:16
	ds_read_b128 v[2:5], v166
	ds_read_b128 v[12:15], v166 offset:16
	s_waitcnt lgkmcnt(0)
	v_add_f32_e32 v16, v2, v12
	v_add_f32_e32 v17, v3, v13
	v_sub_f32_e32 v2, v2, v12
	v_sub_f32_e32 v3, v3, v13
	v_add_f32_e32 v12, v4, v14
	v_add_f32_e32 v13, v5, v15
	v_sub_f32_e32 v5, v5, v15
	v_sub_f32_e32 v4, v4, v14
	v_cvt_f32_f16_e32 v18, v191
	v_add_f32_e32 v14, v16, v12
	v_sub_f32_e32 v12, v16, v12
	v_add_f32_e32 v16, v2, v5
	v_sub_f32_e32 v2, v2, v5
	v_cvt_f32_f16_sdwa v5, v194 dst_sel:DWORD dst_unused:UNUSED_PAD src0_sel:WORD_1
	v_add_f32_e32 v6, v20, v24
	v_sub_f32_e32 v0, v20, v24
	v_add_f32_e32 v15, v17, v13
	v_sub_f32_e32 v13, v17, v13
	v_sub_f32_e32 v17, v3, v4
	v_add_f32_e32 v3, v3, v4
	v_cvt_f32_f16_sdwa v4, v191 dst_sel:DWORD dst_unused:UNUSED_PAD src0_sel:WORD_1
	v_cvt_f32_f16_e32 v24, v131
	v_add_f32_e32 v7, v21, v25
	v_sub_f32_e32 v1, v21, v25
	v_cvt_f32_f16_sdwa v21, v131 dst_sel:DWORD dst_unused:UNUSED_PAD src0_sel:WORD_1
	v_cvt_f32_f16_e32 v25, v129
	v_cvt_f32_f16_sdwa v20, v129 dst_sel:DWORD dst_unused:UNUSED_PAD src0_sel:WORD_1
	v_add_f32_e32 v19, v177, v19
	v_add_f32_e32 v18, v177, v18
	v_mul_f32_e32 v5, v5, v15
	v_mul_f32_e32 v15, v19, v15
	v_add_f32_e32 v24, v177, v24
	v_fma_f32 v5, v19, v14, -v5
	v_fma_mix_f32 v14, v194, v14, v15 op_sel:[1,0,0] op_sel_hi:[1,0,0]
	v_mul_f32_e32 v4, v4, v17
	v_mul_f32_e32 v15, v18, v17
	v_add_f32_e32 v25, v177, v25
	v_fma_f32 v4, v18, v16, -v4
	v_fma_mix_f32 v15, v191, v16, v15 op_sel:[1,0,0] op_sel_hi:[1,0,0]
	v_mul_f32_e32 v16, v21, v13
	v_mul_f32_e32 v13, v24, v13
	v_fma_f32 v16, v24, v12, -v16
	v_fma_mix_f32 v12, v131, v12, v13 op_sel:[1,0,0] op_sel_hi:[1,0,0]
	v_mul_f32_e32 v13, v20, v3
	v_mul_f32_e32 v3, v25, v3
	v_mul_f32_e32 v5, 0x38800000, v5
	v_mul_f32_e32 v16, 0x38800000, v16
	v_fma_f32 v13, v25, v2, -v13
	v_fma_mix_f32 v2, v129, v2, v3 op_sel:[1,0,0] op_sel_hi:[1,0,0]
	v_mul_f32_e32 v14, 0x38800000, v14
	v_mul_f32_e32 v4, 0x38800000, v4
	v_mul_f32_e32 v15, 0x38800000, v15
	v_mul_f32_e32 v12, 0x38800000, v12
	v_mul_f32_e32 v13, 0x38800000, v13
	v_mul_f32_e32 v2, 0x38800000, v2
	v_add_f32_e32 v17, v5, v16
	v_sub_f32_e32 v16, v5, v16
	v_add_f32_e32 v5, v4, v13
	v_add_f32_e32 v18, v14, v12
	v_sub_f32_e32 v19, v14, v12
	v_add_f32_e32 v14, v15, v2
	v_sub_f32_e32 v20, v4, v13
	v_sub_f32_e32 v15, v15, v2
	v_add_f32_e32 v2, v17, v5
	v_sub_f32_e32 v12, v17, v5
	v_sub_f32_e32 v17, v23, v26
	v_add_f32_e32 v3, v18, v14
	v_add_f32_e32 v5, v19, v20
	v_sub_f32_e32 v4, v16, v15
	v_sub_f32_e32 v13, v18, v14
	v_add_f32_e32 v14, v16, v15
	v_sub_f32_e32 v15, v19, v20
	ds_write_b128 v166, v[2:5]
	ds_write_b128 v166, v[12:15] offset:16
	ds_read_b128 v[2:5], v167
	ds_read_b128 v[12:15], v167 offset:16
	v_add_f32_e32 v19, v23, v26
	s_waitcnt lgkmcnt(0)
	v_add_f32_e32 v20, v2, v12
	v_add_f32_e32 v21, v3, v13
	v_sub_f32_e32 v2, v2, v12
	v_sub_f32_e32 v3, v3, v13
	v_add_f32_e32 v12, v4, v14
	v_add_f32_e32 v13, v5, v15
	v_sub_f32_e32 v5, v5, v15
	v_cvt_f32_f16_e32 v23, v127
	v_add_f32_e32 v16, v22, v27
	v_sub_f32_e32 v18, v22, v27
	v_sub_f32_e32 v4, v4, v14
	v_add_f32_e32 v14, v20, v12
	v_sub_f32_e32 v12, v20, v12
	v_add_f32_e32 v20, v2, v5
	v_sub_f32_e32 v2, v2, v5
	v_cvt_f32_f16_sdwa v5, v127 dst_sel:DWORD dst_unused:UNUSED_PAD src0_sel:WORD_1
	v_cvt_f32_f16_e32 v22, v125
	v_add_f32_e32 v15, v21, v13
	v_sub_f32_e32 v13, v21, v13
	v_sub_f32_e32 v21, v3, v4
	v_add_f32_e32 v3, v3, v4
	v_cvt_f32_f16_sdwa v4, v125 dst_sel:DWORD dst_unused:UNUSED_PAD src0_sel:WORD_1
	v_cvt_f32_f16_e32 v26, v123
	v_cvt_f32_f16_sdwa v25, v123 dst_sel:DWORD dst_unused:UNUSED_PAD src0_sel:WORD_1
	v_cvt_f32_f16_e32 v27, v121
	v_cvt_f32_f16_sdwa v24, v121 dst_sel:DWORD dst_unused:UNUSED_PAD src0_sel:WORD_1
	v_add_f32_e32 v23, v177, v23
	v_add_f32_e32 v22, v177, v22
	v_mul_f32_e32 v5, v5, v15
	v_mul_f32_e32 v15, v23, v15
	v_add_f32_e32 v26, v177, v26
	v_fma_f32 v5, v23, v14, -v5
	v_fma_mix_f32 v14, v127, v14, v15 op_sel:[1,0,0] op_sel_hi:[1,0,0]
	v_mul_f32_e32 v4, v4, v21
	v_mul_f32_e32 v15, v22, v21
	v_add_f32_e32 v27, v177, v27
	v_fma_f32 v4, v22, v20, -v4
	v_fma_mix_f32 v15, v125, v20, v15 op_sel:[1,0,0] op_sel_hi:[1,0,0]
	v_mul_f32_e32 v20, v25, v13
	v_mul_f32_e32 v13, v26, v13
	v_fma_f32 v20, v26, v12, -v20
	v_fma_mix_f32 v12, v123, v12, v13 op_sel:[1,0,0] op_sel_hi:[1,0,0]
	v_mul_f32_e32 v13, v24, v3
	v_mul_f32_e32 v3, v27, v3
	v_mul_f32_e32 v5, 0x38800000, v5
	v_mul_f32_e32 v20, 0x38800000, v20
	v_fma_f32 v13, v27, v2, -v13
	v_fma_mix_f32 v2, v121, v2, v3 op_sel:[1,0,0] op_sel_hi:[1,0,0]
	v_mul_f32_e32 v14, 0x38800000, v14
	v_mul_f32_e32 v4, 0x38800000, v4
	v_mul_f32_e32 v15, 0x38800000, v15
	v_mul_f32_e32 v12, 0x38800000, v12
	v_mul_f32_e32 v13, 0x38800000, v13
	v_mul_f32_e32 v2, 0x38800000, v2
	v_add_f32_e32 v21, v5, v20
	v_sub_f32_e32 v20, v5, v20
	v_add_f32_e32 v5, v4, v13
	v_add_f32_e32 v22, v14, v12
	v_sub_f32_e32 v23, v14, v12
	v_add_f32_e32 v14, v15, v2
	v_sub_f32_e32 v24, v4, v13
	v_sub_f32_e32 v15, v15, v2
	v_add_f32_e32 v2, v21, v5
	v_sub_f32_e32 v12, v21, v5
	v_pk_mul_f32 v[16:17], v[82:83], v[16:17] op_sel_hi:[0,1]
	v_add_f32_e32 v3, v22, v14
	v_sub_f32_e32 v4, v20, v15
	v_add_f32_e32 v5, v23, v24
	v_sub_f32_e32 v13, v22, v14
	v_add_f32_e32 v14, v20, v15
	v_sub_f32_e32 v15, v23, v24
	ds_write_b128 v167, v[2:5]
	ds_write_b128 v167, v[12:15] offset:16
	ds_read_b128 v[2:5], v168
	ds_read_b128 v[12:15], v168 offset:16
	v_pk_mul_f32 v[6:7], v[82:83], v[6:7] op_sel_hi:[0,1]
	v_cvt_pk_f16_f32 v20, v6, v7
	v_cvt_pk_f16_f32 v16, v16, v17
	s_waitcnt lgkmcnt(0)
	v_add_f32_e32 v6, v2, v12
	v_add_f32_e32 v7, v3, v13
	v_sub_f32_e32 v2, v2, v12
	v_sub_f32_e32 v3, v3, v13
	v_add_f32_e32 v12, v4, v14
	v_add_f32_e32 v13, v5, v15
	v_sub_f32_e32 v4, v4, v14
	v_cvt_f32_f16_e32 v17, v8
	v_sub_f32_e32 v5, v5, v15
	v_add_f32_e32 v15, v7, v13
	v_sub_f32_e32 v7, v7, v13
	v_sub_f32_e32 v13, v3, v4
	v_add_f32_e32 v3, v3, v4
	v_cvt_f32_f16_sdwa v4, v8 dst_sel:DWORD dst_unused:UNUSED_PAD src0_sel:WORD_1
	v_cvt_f32_f16_e32 v24, v11
	v_add_f32_e32 v14, v6, v12
	v_sub_f32_e32 v6, v6, v12
	v_add_f32_e32 v12, v2, v5
	v_sub_f32_e32 v2, v2, v5
	v_cvt_f32_f16_sdwa v5, v9 dst_sel:DWORD dst_unused:UNUSED_PAD src0_sel:WORD_1
	v_cvt_f32_f16_e32 v21, v9
	v_cvt_f32_f16_sdwa v23, v11 dst_sel:DWORD dst_unused:UNUSED_PAD src0_sel:WORD_1
	v_cvt_f32_f16_e32 v25, v10
	v_cvt_f32_f16_sdwa v22, v10 dst_sel:DWORD dst_unused:UNUSED_PAD src0_sel:WORD_1
	v_add_f32_e32 v17, v177, v17
	v_add_f32_e32 v24, v177, v24
	v_mul_f32_e32 v4, v4, v13
	v_mul_f32_e32 v13, v17, v13
	v_add_f32_e32 v21, v177, v21
	v_add_f32_e32 v25, v177, v25
	v_mul_f32_e32 v5, v5, v15
	v_fma_f32 v4, v17, v12, -v4
	v_fma_mix_f32 v8, v8, v12, v13 op_sel:[1,0,0] op_sel_hi:[1,0,0]
	v_mul_f32_e32 v12, v23, v7
	v_mul_f32_e32 v7, v24, v7
	v_fma_f32 v5, v21, v14, -v5
	v_mul_f32_e32 v15, v21, v15
	v_fma_f32 v12, v24, v6, -v12
	v_fma_mix_f32 v6, v11, v6, v7 op_sel:[1,0,0] op_sel_hi:[1,0,0]
	v_mul_f32_e32 v7, v22, v3
	v_mul_f32_e32 v3, v25, v3
	v_mul_f32_e32 v5, 0x38800000, v5
	v_fma_mix_f32 v9, v9, v14, v15 op_sel:[1,0,0] op_sel_hi:[1,0,0]
	v_mul_f32_e32 v12, 0x38800000, v12
	v_fma_f32 v7, v25, v2, -v7
	v_fma_mix_f32 v2, v10, v2, v3 op_sel:[1,0,0] op_sel_hi:[1,0,0]
	v_mul_f32_e32 v9, 0x38800000, v9
	v_mul_f32_e32 v4, 0x38800000, v4
	v_mul_f32_e32 v8, 0x38800000, v8
	v_mul_f32_e32 v6, 0x38800000, v6
	v_mul_f32_e32 v7, 0x38800000, v7
	v_mul_f32_e32 v2, 0x38800000, v2
	v_add_f32_e32 v10, v5, v12
	v_sub_f32_e32 v12, v5, v12
	v_add_f32_e32 v5, v4, v7
	v_add_f32_e32 v11, v9, v6
	v_sub_f32_e32 v9, v9, v6
	v_add_f32_e32 v13, v8, v2
	v_sub_f32_e32 v14, v4, v7
	v_sub_f32_e32 v8, v8, v2
	v_add_f32_e32 v2, v10, v5
	v_sub_f32_e32 v6, v10, v5
	v_pk_mul_f32 v[0:1], v[82:83], v[0:1] op_sel_hi:[0,1]
	v_add_f32_e32 v3, v11, v13
	v_sub_f32_e32 v4, v12, v8
	v_add_f32_e32 v5, v9, v14
	v_sub_f32_e32 v7, v11, v13
	v_add_f32_e32 v8, v12, v8
	v_sub_f32_e32 v9, v9, v14
	ds_write_b128 v168, v[2:5]
	ds_write_b128 v168, v[6:9] offset:16
	ds_read_b128 v[2:5], v169
	ds_read_b128 v[6:9], v169 offset:16
	v_pk_mul_f32 v[10:11], v[82:83], v[18:19] op_sel_hi:[0,1]
	v_cvt_pk_f16_f32 v0, v0, v1
	v_cvt_pk_f16_f32 v1, v10, v11
	s_waitcnt lgkmcnt(0)
	v_add_f32_e32 v10, v2, v6
	v_add_f32_e32 v11, v3, v7
	v_sub_f32_e32 v2, v2, v6
	v_sub_f32_e32 v3, v3, v7
	v_add_f32_e32 v6, v4, v8
	v_add_f32_e32 v7, v5, v9
	v_sub_f32_e32 v5, v5, v9
	v_cvt_f32_f16_e32 v13, v20
	v_sub_f32_e32 v4, v4, v8
	v_add_f32_e32 v8, v10, v6
	v_sub_f32_e32 v6, v10, v6
	v_add_f32_e32 v10, v2, v5
	v_sub_f32_e32 v2, v2, v5
	v_cvt_f32_f16_sdwa v5, v20 dst_sel:DWORD dst_unused:UNUSED_PAD src0_sel:WORD_1
	v_cvt_f32_f16_e32 v12, v16
	v_add_f32_e32 v9, v11, v7
	v_sub_f32_e32 v7, v11, v7
	v_sub_f32_e32 v11, v3, v4
	v_add_f32_e32 v3, v3, v4
	v_cvt_f32_f16_sdwa v4, v16 dst_sel:DWORD dst_unused:UNUSED_PAD src0_sel:WORD_1
	v_cvt_f32_f16_e32 v17, v0
	v_cvt_f32_f16_sdwa v15, v0 dst_sel:DWORD dst_unused:UNUSED_PAD src0_sel:WORD_1
	v_cvt_f32_f16_e32 v18, v1
	v_cvt_f32_f16_sdwa v14, v1 dst_sel:DWORD dst_unused:UNUSED_PAD src0_sel:WORD_1
	v_add_f32_e32 v13, v177, v13
	v_add_f32_e32 v12, v177, v12
	v_mul_f32_e32 v5, v5, v9
	v_mul_f32_e32 v9, v13, v9
	v_add_f32_e32 v17, v177, v17
	v_fma_f32 v5, v13, v8, -v5
	v_fma_mix_f32 v8, v20, v8, v9 op_sel:[1,0,0] op_sel_hi:[1,0,0]
	v_mul_f32_e32 v4, v4, v11
	v_mul_f32_e32 v9, v12, v11
	v_add_f32_e32 v18, v177, v18
	v_fma_f32 v4, v12, v10, -v4
	v_fma_mix_f32 v9, v16, v10, v9 op_sel:[1,0,0] op_sel_hi:[1,0,0]
	v_mul_f32_e32 v10, v15, v7
	v_mul_f32_e32 v7, v17, v7
	v_fma_f32 v10, v17, v6, -v10
	v_fma_mix_f32 v0, v0, v6, v7 op_sel:[1,0,0] op_sel_hi:[1,0,0]
	v_mul_f32_e32 v6, v14, v3
	v_mul_f32_e32 v3, v18, v3
	v_mul_f32_e32 v5, 0x38800000, v5
	v_fma_f32 v6, v18, v2, -v6
	v_fma_mix_f32 v1, v1, v2, v3 op_sel:[1,0,0] op_sel_hi:[1,0,0]
	v_mul_f32_e32 v8, 0x38800000, v8
	v_mul_f32_e32 v4, 0x38800000, v4
	v_mul_f32_e32 v10, 0x38800000, v10
	v_mul_f32_e32 v0, 0x38800000, v0
	v_mul_f32_e32 v6, 0x38800000, v6
	v_mul_f32_e32 v1, 0x38800000, v1
	v_add_f32_e32 v2, v5, v10
	v_add_f32_e32 v3, v8, v0
	v_sub_f32_e32 v7, v5, v10
	v_add_f32_e32 v5, v4, v6
	v_mul_f32_e32 v9, 0x38800000, v9
	v_sub_f32_e32 v8, v8, v0
	v_add_f32_e32 v10, v9, v1
	v_sub_f32_e32 v11, v4, v6
	v_sub_f32_e32 v6, v9, v1
	v_add_f32_e32 v0, v2, v5
	v_sub_f32_e32 v4, v2, v5
	v_mov_b32_e32 v34, v143
	v_add_f32_e32 v1, v3, v10
	v_sub_f32_e32 v5, v3, v10
	v_sub_f32_e32 v2, v7, v6
	v_add_f32_e32 v3, v8, v11
	v_add_f32_e32 v6, v7, v6
	v_sub_f32_e32 v7, v8, v11
	ds_write_b128 v169, v[0:3]
	ds_write_b128 v169, v[4:7] offset:16
	v_mov_b32_e32 v35, v144
	ds_read_b64 v[2:3], v142
	ds_read_b64 v[0:1], v141 offset:4096
	ds_read_b64 v[20:21], v142 offset:32
	ds_read_b64 v[22:23], v141 offset:4128
	ds_read_b64 v[24:25], v142 offset:64
	ds_read_b64 v[26:27], v141 offset:4160
	ds_read_b64 v[28:29], v142 offset:96
	ds_read_b64 v[30:31], v141 offset:4192
	ds_read_b64 v[32:33], v142 offset:128
	ds_read_b64 v[40:41], v141 offset:4224
	ds_read_b64 v[42:43], v142 offset:160
	ds_read_b64 v[44:45], v141 offset:4256
	ds_read_b64 v[46:47], v142 offset:192
	ds_read_b64 v[48:49], v141 offset:4288
	ds_read_b64 v[120:121], v142 offset:224
	ds_read_b64 v[122:123], v141 offset:4320
	ds_read_b64 v[124:125], v142 offset:256
	ds_read_b64 v[126:127], v141 offset:4352
	ds_read_b64 v[128:129], v142 offset:288
	ds_read_b64 v[130:131], v141 offset:4384
	ds_read_b64 v[178:179], v142 offset:320
	ds_read_b64 v[180:181], v141 offset:4416
	ds_read_b64 v[182:183], v142 offset:352
	ds_read_b64 v[184:185], v141 offset:4448
	ds_read_b64 v[18:19], v142 offset:384
	ds_read_b64 v[16:17], v141 offset:4480
	ds_read_b64 v[14:15], v142 offset:416
	ds_read_b64 v[12:13], v141 offset:4512
	ds_read_b64 v[10:11], v142 offset:448
	ds_read_b64 v[8:9], v141 offset:4544
	ds_read_b64 v[6:7], v142 offset:480
	ds_read_b64 v[4:5], v141 offset:4576
	s_nop 1
	v_mul_f32_e32 v36, v35, v35
	v_fma_f32 v37, -v34, v34, v36
	v_mul_f32_e32 v36, v35, v34
	v_fma_f32 v82, v34, v35, v36
	v_mul_f32_e32 v36, v37, v35
	v_fma_f32 v132, -v82, v34, v36
	v_mul_f32_e32 v36, v37, v34
	v_fma_f32 v134, v82, v35, v36
	v_mul_f32_e32 v36, v37, v37
	v_fma_f32 v151, -v82, v82, v36
	v_mul_f32_e32 v36, v37, v82
	v_fma_f32 v170, v82, v37, v36
	v_mul_f32_e32 v36, v151, v35
	v_fma_f32 v171, -v170, v34, v36
	v_mul_f32_e32 v36, v151, v34
	v_fma_f32 v177, v170, v35, v36
	v_mul_f32_e32 v36, v132, v132
	v_fma_f32 v186, -v134, v134, v36
	v_mul_f32_e32 v36, v132, v134
	v_fma_f32 v187, v134, v132, v36
	v_mul_f32_e32 v36, v151, v132
	v_fma_f32 v188, -v170, v134, v36
	v_mul_f32_e32 v36, v151, v134
	v_fma_f32 v189, v170, v132, v36
	v_mul_f32_e32 v36, v151, v151
	v_fma_f32 v190, -v170, v170, v36
	v_mul_f32_e32 v36, v151, v170
	v_fma_f32 v191, v170, v151, v36
	v_mul_f32_e32 v36, v190, v35
	v_fma_f32 v192, -v191, v34, v36
	v_mul_f32_e32 v36, v190, v34
	v_fma_f32 v193, v191, v35, v36
	v_mul_f32_e32 v36, v171, v171
	v_fma_f32 v194, -v177, v177, v36
	v_mul_f32_e32 v36, v171, v177
	v_fma_f32 v195, v177, v171, v36
	v_mul_f32_e32 v36, v190, v132
	v_fma_f32 v196, -v191, v134, v36
	v_mul_f32_e32 v36, v190, v134
	v_fma_f32 v197, v191, v132, v36
	v_mul_f32_e32 v36, v186, v186
	v_fma_f32 v198, -v187, v187, v36
	v_mul_f32_e32 v36, v186, v187
	v_fma_f32 v199, v187, v186, v36
	v_mul_f32_e32 v36, v190, v171
	v_fma_f32 v200, -v191, v177, v36
	v_mul_f32_e32 v36, v190, v177
	v_fma_f32 v201, v191, v171, v36
	v_mul_f32_e32 v36, v188, v188
	v_fma_f32 v202, -v189, v189, v36
	v_mul_f32_e32 v36, v188, v189
	v_fma_f32 v203, v189, v188, v36
	v_mul_f32_e32 v36, v190, v188
	v_fma_f32 v204, -v191, v189, v36
	v_mul_f32_e32 v36, v190, v189
	v_fma_f32 v205, v191, v188, v36
	s_waitcnt lgkmcnt(0)
	v_mul_f32_e32 v36, v20, v35
	v_mul_f32_e32 v20, v20, v34
	v_fma_f32 v206, -v21, v34, v36
	v_fma_f32 v20, v21, v35, v20
	v_mul_f32_e32 v21, v22, v35
	v_fma_f32 v38, -v23, v34, v21
	v_mul_f32_e32 v21, v22, v34
	v_mul_f32_e32 v22, v24, v82
	v_fma_f32 v39, v23, v35, v21
	v_mul_f32_e32 v21, v24, v37
	v_mul_f32_e32 v23, v26, v37
	v_fma_f32 v22, v25, v37, v22
	v_mul_f32_e32 v24, v28, v134
	v_fma_f32 v21, -v25, v82, v21
	v_fma_f32 v36, -v27, v82, v23
	v_mul_f32_e32 v23, v26, v82
	v_mul_f32_e32 v25, v30, v132
	v_fma_f32 v24, v29, v132, v24
	v_mul_f32_e32 v26, v32, v170
	v_fma_f32 v37, v27, v37, v23
	v_mul_f32_e32 v27, v40, v151
	v_fma_f32 v34, -v31, v134, v25
	v_mul_f32_e32 v25, v30, v134
	v_mul_f32_e32 v23, v28, v132
	v_mul_f32_e32 v28, v42, v177
	v_fma_f32 v26, v33, v151, v26
	v_fma_f32 v82, -v41, v170, v27
	v_mul_f32_e32 v27, v40, v170
	v_fma_f32 v35, v31, v132, v25
	v_mul_f32_e32 v31, v48, v186
	v_mul_f32_e32 v25, v32, v151
	v_fma_f32 v28, v43, v171, v28
	v_mul_f32_e32 v32, v120, v189
	v_fma_f32 v132, v41, v151, v27
	v_mul_f32_e32 v27, v42, v171
	v_fma_f32 v42, -v49, v187, v31
	v_mul_f32_e32 v31, v48, v187
	v_fma_f32 v23, -v29, v134, v23
	v_fma_f32 v32, v121, v188, v32
	v_mul_f32_e32 v29, v44, v171
	v_fma_f32 v27, -v43, v177, v27
	v_fma_f32 v25, -v33, v170, v25
	v_fma_f32 v43, v49, v186, v31
	v_mul_f32_e32 v31, v120, v188
	v_mul_f32_e32 v120, v130, v192
	v_fma_f32 v134, -v45, v177, v29
	v_mul_f32_e32 v29, v44, v177
	v_mul_f32_e32 v33, v122, v188
	v_mul_f32_e32 v48, v128, v192
	v_fma_f32 v31, -v121, v189, v31
	v_mul_f32_e32 v121, v130, v193
	v_mul_f32_e32 v130, v18, v198
	v_mul_f32_e32 v18, v18, v199
	v_fma_f32 v44, v45, v171, v29
	v_fma_f32 v40, -v123, v189, v33
	v_mul_f32_e32 v33, v122, v189
	v_mul_f32_e32 v122, v178, v194
	v_fma_f32 v130, -v19, v199, v130
	v_fma_f32 v18, v19, v198, v18
	v_mul_f32_e32 v19, v16, v198
	v_mul_f32_e32 v16, v16, v199
	v_fma_f32 v41, v123, v188, v33
	v_mul_f32_e32 v123, v178, v195
	v_mul_f32_e32 v33, v124, v190
	v_mul_f32_e32 v45, v124, v191
	v_mul_f32_e32 v49, v128, v193
	v_fma_f32 v151, v17, v198, v16
	v_mul_f32_e32 v16, v14, v200
	v_mul_f32_e32 v14, v14, v201
	v_fma_f32 v33, -v125, v191, v33
	v_fma_f32 v45, v125, v190, v45
	v_fma_f32 v122, -v179, v195, v122
	v_fma_f32 v123, v179, v194, v123
	v_fma_f32 v16, -v15, v201, v16
	v_fma_f32 v14, v15, v200, v14
	v_mul_f32_e32 v15, v12, v200
	v_mul_f32_e32 v12, v12, v201
	v_mul_f32_e32 v124, v180, v194
	v_mul_f32_e32 v125, v180, v195
	v_mul_f32_e32 v29, v46, v186
	v_mul_f32_e32 v30, v46, v187
	v_fma_f32 v170, -v13, v201, v15
	v_fma_f32 v171, v13, v200, v12
	v_mul_f32_e32 v12, v10, v202
	v_mul_f32_e32 v10, v10, v203
	v_sub_f32_e32 v13, v26, v18
	v_fma_f32 v48, -v129, v193, v48
	v_fma_f32 v49, v129, v192, v49
	v_fma_f32 v120, -v131, v193, v120
	v_fma_f32 v12, -v11, v203, v12
	v_fma_f32 v10, v11, v202, v10
	v_mul_f32_e32 v11, v8, v202
	v_mul_f32_e32 v8, v8, v203
	v_fma_f32 v121, v131, v192, v121
	v_fma_f32 v131, -v17, v199, v19
	v_fma_f32 v29, -v47, v187, v29
	v_fma_f32 v30, v47, v186, v30
	v_fma_f32 v177, -v9, v203, v11
	v_fma_f32 v178, v9, v202, v8
	v_mul_f32_e32 v8, v6, v204
	v_mul_f32_e32 v6, v6, v205
	v_add_f32_e32 v9, v26, v18
	v_sub_f32_e32 v11, v25, v130
	v_mul_f32_e32 v46, v126, v190
	v_mul_f32_e32 v47, v126, v191
	v_fma_f32 v8, -v7, v205, v8
	v_fma_f32 v6, v7, v204, v6
	v_mul_f32_e32 v7, v4, v204
	v_mul_f32_e32 v4, v4, v205
	v_mul_f32_e32 v126, v182, v196
	v_fma_f32 v46, -v127, v191, v46
	v_fma_f32 v47, v127, v190, v47
	v_mul_f32_e32 v127, v182, v197
	v_fma_f32 v179, -v5, v205, v7
	v_fma_f32 v180, v5, v204, v4
	v_add_f32_e32 v4, v2, v33
	v_add_f32_e32 v5, v3, v45
	v_sub_f32_e32 v2, v2, v33
	v_sub_f32_e32 v3, v3, v45
	v_add_f32_e32 v7, v25, v130
	v_fma_f32 v126, -v183, v197, v126
	v_fma_f32 v127, v183, v196, v127
	v_add_f32_e32 v17, v5, v9
	v_sub_f32_e32 v26, v5, v9
	v_add_f32_e32 v9, v3, v11
	v_add_f32_e32 v15, v4, v7
	v_sub_f32_e32 v25, v4, v7
	v_sub_f32_e32 v7, v2, v13
	v_add_f32_e32 v33, v2, v13
	v_sub_f32_e32 v45, v3, v11
	v_add_f32_e32 v2, v206, v48
	v_add_f32_e32 v3, v20, v49
	v_sub_f32_e32 v4, v206, v48
	v_sub_f32_e32 v5, v20, v49
	v_add_f32_e32 v11, v27, v16
	v_add_f32_e32 v13, v28, v14
	v_sub_f32_e32 v16, v27, v16
	v_sub_f32_e32 v14, v28, v14
	v_sub_f32_e32 v20, v21, v122
	v_add_f32_e32 v27, v30, v10
	v_add_f32_e32 v18, v2, v11
	v_add_f32_e32 v19, v3, v13
	v_sub_f32_e32 v2, v2, v11
	v_sub_f32_e32 v3, v3, v13
	v_sub_f32_e32 v11, v4, v14
	v_add_f32_e32 v13, v5, v16
	v_add_f32_e32 v4, v4, v14
	v_sub_f32_e32 v5, v5, v16
	v_add_f32_e32 v14, v21, v122
	v_add_f32_e32 v16, v22, v123
	v_sub_f32_e32 v10, v30, v10
	v_sub_f32_e32 v21, v22, v123
	v_add_f32_e32 v22, v29, v12
	v_sub_f32_e32 v12, v29, v12
	v_add_f32_e32 v48, v32, v6
	v_add_f32_e32 v29, v16, v27
	v_sub_f32_e32 v6, v32, v6
	v_mul_f32_e32 v2, v2, v154
	v_add_f32_e32 v28, v14, v22
	v_sub_f32_e32 v30, v14, v22
	v_sub_f32_e32 v14, v16, v27
	v_sub_f32_e32 v16, v20, v10
	v_add_f32_e32 v10, v20, v10
	v_add_f32_e32 v20, v23, v126
	v_sub_f32_e32 v23, v23, v126
	v_add_f32_e32 v27, v31, v8
	v_sub_f32_e32 v8, v31, v8
	v_add_f32_e32 v22, v21, v12
	v_sub_f32_e32 v12, v21, v12
	v_add_f32_e32 v21, v24, v127
	v_sub_f32_e32 v24, v24, v127
	v_add_f32_e32 v31, v20, v27
	v_sub_f32_e32 v20, v20, v27
	v_sub_f32_e32 v27, v23, v6
	v_add_f32_e32 v6, v23, v6
	v_mul_f32_e32 v23, v11, v152
	v_mul_f32_e32 v11, v11, v156
	v_add_f32_e32 v32, v21, v48
	v_sub_f32_e32 v21, v21, v48
	v_add_f32_e32 v48, v24, v8
	v_sub_f32_e32 v8, v24, v8
	v_fma_f32 v23, -v13, v156, v23
	v_fma_f32 v13, v13, v152, v11
	v_mul_f32_e32 v11, v16, v154
	v_fma_f32 v49, v3, v154, v2
	v_fma_f32 v124, -v181, v195, v124
	v_fma_f32 v125, v181, v194, v125
	v_xor_b32_e32 v122, 0x80000000, v14
	v_fma_f32 v16, -v22, v154, v11
	v_fma_f32 v22, v22, v154, v11
	v_mul_f32_e32 v11, v27, v156
	v_mul_f32_e32 v128, v184, v196
	v_mul_f32_e32 v129, v184, v197
	v_fma_f32 v24, -v48, v152, v11
	v_mul_f32_e32 v11, v27, v152
	v_fma_f32 v128, -v185, v197, v128
	v_fma_f32 v129, v185, v196, v129
	v_fma_f32 v27, v48, v156, v11
	v_fma_f32 v48, -v3, v154, v2
	v_mul_f32_e32 v2, v20, v155
	v_add_f32_e32 v3, v17, v29
	v_fma_f32 v123, -v21, v154, v2
	v_mul_f32_e32 v2, v20, v154
	v_fma_f32 v20, v21, v155, v2
	v_mul_f32_e32 v2, v4, v156
	v_fma_f32 v21, -v5, v152, v2
	v_mul_f32_e32 v2, v4, v152
	v_add_f32_e32 v4, v18, v31
	v_fma_f32 v126, v5, v156, v2
	v_mul_f32_e32 v2, v10, v155
	v_add_f32_e32 v5, v19, v32
	v_fma_f32 v127, -v12, v154, v2
	v_mul_f32_e32 v2, v10, v154
	v_fma_f32 v130, v12, v155, v2
	v_mul_f32_e32 v2, v6, v157
	v_sub_f32_e32 v12, v18, v31
	v_fma_f32 v181, -v8, v153, v2
	v_mul_f32_e32 v2, v6, v153
	v_sub_f32_e32 v6, v15, v28
	v_fma_f32 v182, v8, v157, v2
	v_add_f32_e32 v2, v15, v28
	v_sub_f32_e32 v8, v17, v29
	v_sub_f32_e32 v17, v19, v32
	v_add_f32_e32 v15, v3, v5
	v_sub_f32_e32 v5, v3, v5
	v_add_f32_e32 v14, v2, v4
	v_sub_f32_e32 v4, v2, v4
	v_sub_f32_e32 v10, v6, v17
	v_add_f32_e32 v11, v8, v12
	v_add_f32_e32 v2, v6, v17
	v_sub_f32_e32 v3, v8, v12
	v_add_f32_e32 v6, v7, v16
	v_add_f32_e32 v12, v9, v22
	v_sub_f32_e32 v7, v7, v16
	v_sub_f32_e32 v16, v9, v22
	v_add_f32_e32 v8, v23, v24
	v_add_f32_e32 v9, v13, v27
	v_sub_f32_e32 v17, v23, v24
	v_sub_f32_e32 v13, v13, v27
	v_sub_f32_e32 v24, v25, v122
	v_add_f32_e32 v22, v6, v8
	v_add_f32_e32 v23, v12, v9
	v_sub_f32_e32 v8, v6, v8
	v_sub_f32_e32 v9, v12, v9
	v_sub_f32_e32 v18, v7, v13
	v_add_f32_e32 v19, v16, v17
	v_add_f32_e32 v6, v7, v13
	v_sub_f32_e32 v7, v16, v17
	v_add_f32_e32 v12, v25, v122
	v_add_f32_e32 v13, v26, v30
	v_sub_f32_e32 v25, v26, v30
	v_add_f32_e32 v16, v48, v123
	v_add_f32_e32 v17, v49, v20
	v_sub_f32_e32 v30, v48, v123
	v_sub_f32_e32 v20, v49, v20
	v_sub_f32_e32 v48, v33, v127
	v_sub_f32_e32 v49, v126, v182
	v_add_f32_e32 v28, v12, v16
	v_add_f32_e32 v29, v13, v17
	v_sub_f32_e32 v16, v12, v16
	v_sub_f32_e32 v17, v13, v17
	v_sub_f32_e32 v26, v24, v20
	v_add_f32_e32 v27, v25, v30
	v_add_f32_e32 v12, v24, v20
	v_sub_f32_e32 v13, v25, v30
	v_add_f32_e32 v20, v33, v127
	v_add_f32_e32 v25, v45, v130
	v_sub_f32_e32 v45, v45, v130
	v_add_f32_e32 v24, v21, v181
	v_add_f32_e32 v30, v126, v182
	v_sub_f32_e32 v21, v21, v181
	v_add_f32_e32 v32, v20, v24
	v_add_f32_e32 v33, v25, v30
	v_sub_f32_e32 v24, v20, v24
	v_sub_f32_e32 v25, v25, v30
	v_sub_f32_e32 v30, v48, v49
	v_add_f32_e32 v31, v45, v21
	v_add_f32_e32 v20, v48, v49
	v_sub_f32_e32 v21, v45, v21
	v_add_f32_e32 v45, v0, v46
	v_add_f32_e32 v48, v1, v47
	v_sub_f32_e32 v0, v0, v46
	v_sub_f32_e32 v1, v1, v47
	v_add_f32_e32 v46, v82, v131
	v_add_f32_e32 v47, v132, v151
	v_sub_f32_e32 v49, v82, v131
	v_sub_f32_e32 v82, v132, v151
	v_add_f32_e32 v122, v45, v46
	v_add_f32_e32 v123, v48, v47
	v_sub_f32_e32 v126, v45, v46
	v_sub_f32_e32 v48, v48, v47
	v_sub_f32_e32 v45, v0, v82
	v_add_f32_e32 v46, v1, v49
	v_add_f32_e32 v82, v0, v82
	v_sub_f32_e32 v127, v1, v49
	v_add_f32_e32 v0, v38, v120
	v_add_f32_e32 v1, v39, v121
	v_sub_f32_e32 v38, v38, v120
	v_sub_f32_e32 v39, v39, v121
	v_add_f32_e32 v47, v134, v170
	v_add_f32_e32 v49, v44, v171
	v_sub_f32_e32 v120, v134, v170
	v_sub_f32_e32 v44, v44, v171
	v_add_f32_e32 v121, v0, v47
	v_add_f32_e32 v130, v1, v49
	v_sub_f32_e32 v0, v0, v47
	v_sub_f32_e32 v1, v1, v49
	v_sub_f32_e32 v47, v38, v44
	v_add_f32_e32 v49, v39, v120
	v_add_f32_e32 v38, v38, v44
	v_sub_f32_e32 v39, v39, v120
	v_add_f32_e32 v44, v36, v124
	v_add_f32_e32 v120, v37, v125
	v_sub_f32_e32 v36, v36, v124
	v_sub_f32_e32 v37, v37, v125
	v_add_f32_e32 v124, v42, v177
	v_add_f32_e32 v125, v43, v178
	v_sub_f32_e32 v42, v42, v177
	v_sub_f32_e32 v43, v43, v178
	v_mul_f32_e32 v0, v0, v154
	v_add_f32_e32 v131, v44, v124
	v_add_f32_e32 v132, v120, v125
	v_sub_f32_e32 v124, v44, v124
	v_sub_f32_e32 v44, v120, v125
	v_sub_f32_e32 v120, v36, v43
	v_add_f32_e32 v125, v37, v42
	v_add_f32_e32 v36, v36, v43
	v_sub_f32_e32 v37, v37, v42
	v_add_f32_e32 v42, v34, v128
	v_add_f32_e32 v43, v35, v129
	v_sub_f32_e32 v34, v34, v128
	v_sub_f32_e32 v35, v35, v129
	v_add_f32_e32 v128, v40, v179
	v_add_f32_e32 v129, v41, v180
	v_sub_f32_e32 v40, v40, v179
	v_sub_f32_e32 v41, v41, v180
	v_xor_b32_e32 v170, 0x80000000, v44
	v_add_f32_e32 v134, v42, v128
	v_add_f32_e32 v151, v43, v129
	v_sub_f32_e32 v42, v42, v128
	v_sub_f32_e32 v43, v43, v129
	v_sub_f32_e32 v128, v34, v41
	v_add_f32_e32 v129, v35, v40
	v_add_f32_e32 v34, v34, v41
	v_sub_f32_e32 v35, v35, v40
	v_mul_f32_e32 v40, v47, v152
	v_mul_f32_e32 v41, v47, v156
	v_mul_f32_e32 v47, v120, v154
	v_mul_f32_e32 v120, v128, v156
	v_fma_f32 v40, -v49, v156, v40
	v_fma_f32 v41, v49, v152, v41
	v_fma_f32 v49, -v125, v154, v47
	v_fma_f32 v47, v125, v154, v47
	v_mul_f32_e32 v125, v128, v152
	v_fma_f32 v120, -v129, v152, v120
	v_fma_f32 v128, -v1, v154, v0
	v_fma_f32 v125, v129, v156, v125
	v_fma_f32 v129, v1, v154, v0
	v_mul_f32_e32 v0, v42, v155
	v_add_f32_e32 v44, v40, v120
	v_sub_f32_e32 v120, v40, v120
	v_fma_f32 v171, -v43, v154, v0
	v_mul_f32_e32 v0, v42, v154
	v_sub_f32_e32 v42, v121, v134
	v_fma_f32 v177, v43, v155, v0
	v_mul_f32_e32 v0, v38, v156
	v_sub_f32_e32 v43, v130, v151
	v_fma_f32 v178, -v39, v152, v0
	v_mul_f32_e32 v0, v38, v152
	v_sub_f32_e32 v38, v122, v131
	v_fma_f32 v179, v39, v156, v0
	v_mul_f32_e32 v0, v36, v155
	v_sub_f32_e32 v39, v123, v132
	v_fma_f32 v180, -v37, v154, v0
	v_mul_f32_e32 v0, v36, v154
	v_add_f32_e32 v36, v121, v134
	v_add_f32_e32 v121, v48, v124
	v_fma_f32 v181, v37, v155, v0
	v_mul_f32_e32 v0, v34, v157
	v_add_f32_e32 v37, v130, v151
	v_fma_f32 v182, -v35, v153, v0
	v_mul_f32_e32 v0, v34, v153
	v_add_f32_e32 v34, v122, v131
	v_add_f32_e32 v122, v128, v171
	v_sub_f32_e32 v128, v128, v171
	v_fma_f32 v183, v35, v157, v0
	v_add_f32_e32 v35, v123, v132
	v_add_f32_e32 v0, v34, v36
	v_sub_f32_e32 v34, v34, v36
	v_sub_f32_e32 v36, v38, v43
	v_add_f32_e32 v38, v38, v43
	v_add_f32_e32 v43, v46, v47
	v_add_f32_e32 v1, v35, v37
	v_sub_f32_e32 v35, v35, v37
	v_add_f32_e32 v37, v39, v42
	v_sub_f32_e32 v39, v39, v42
	v_add_f32_e32 v42, v45, v49
	v_sub_f32_e32 v49, v45, v49
	v_sub_f32_e32 v47, v46, v47
	v_add_f32_e32 v45, v41, v125
	v_sub_f32_e32 v46, v41, v125
	v_sub_f32_e32 v125, v126, v170
	v_add_f32_e32 v123, v129, v177
	v_add_f32_e32 v40, v42, v44
	v_sub_f32_e32 v42, v42, v44
	v_add_f32_e32 v41, v43, v45
	v_sub_f32_e32 v43, v43, v45
	v_add_f32_e32 v45, v47, v120
	v_sub_f32_e32 v47, v47, v120
	v_add_f32_e32 v120, v126, v170
	v_sub_f32_e32 v126, v48, v124
	v_sub_f32_e32 v124, v129, v177
	v_sub_f32_e32 v44, v49, v46
	v_add_f32_e32 v46, v49, v46
	v_add_f32_e32 v49, v121, v123
	v_add_f32_e32 v48, v120, v122
	v_sub_f32_e32 v120, v120, v122
	v_sub_f32_e32 v121, v121, v123
	v_sub_f32_e32 v122, v125, v124
	v_add_f32_e32 v123, v126, v128
	v_add_f32_e32 v124, v125, v124
	v_sub_f32_e32 v125, v126, v128
	v_add_f32_e32 v128, v82, v180
	v_add_f32_e32 v129, v127, v181
	v_add_f32_e32 v130, v178, v182
	v_add_f32_e32 v131, v179, v183
	v_sub_f32_e32 v82, v82, v180
	v_sub_f32_e32 v132, v127, v181
	v_sub_f32_e32 v134, v178, v182
	v_sub_f32_e32 v151, v179, v183
	v_add_f32_e32 v126, v128, v130
	v_add_f32_e32 v127, v129, v131
	v_sub_f32_e32 v128, v128, v130
	v_sub_f32_e32 v129, v129, v131
	v_add_f32_e32 v131, v132, v134
	v_sub_f32_e32 v130, v82, v151
	v_add_f32_e32 v178, v82, v151
	v_sub_f32_e32 v179, v132, v134
	ds_write_b64 v142, v[14:15]
	ds_write_b64 v141, v[0:1] offset:4096
	ds_write_b64 v142, v[22:23] offset:32
	ds_write_b64 v141, v[40:41] offset:4128
	ds_write_b64 v142, v[28:29] offset:64
	ds_write_b64 v141, v[48:49] offset:4160
	ds_write_b64 v142, v[32:33] offset:96
	ds_write_b64 v141, v[126:127] offset:4192
	ds_write_b64 v142, v[10:11] offset:128
	ds_write_b64 v141, v[36:37] offset:4224
	ds_write_b64 v142, v[18:19] offset:160
	ds_write_b64 v141, v[44:45] offset:4256
	ds_write_b64 v142, v[26:27] offset:192
	ds_write_b64 v141, v[122:123] offset:4288
	ds_write_b64 v142, v[30:31] offset:224
	ds_write_b64 v141, v[130:131] offset:4320
	ds_write_b64 v142, v[4:5] offset:256
	ds_write_b64 v141, v[34:35] offset:4352
	ds_write_b64 v142, v[8:9] offset:288
	ds_write_b64 v141, v[42:43] offset:4384
	ds_write_b64 v142, v[16:17] offset:320
	ds_write_b64 v141, v[120:121] offset:4416
	ds_write_b64 v142, v[24:25] offset:352
	ds_write_b64 v141, v[128:129] offset:4448
	ds_write_b64 v142, v[2:3] offset:384
	ds_write_b64 v141, v[38:39] offset:4480
	ds_write_b64 v142, v[6:7] offset:416
	ds_write_b64 v141, v[46:47] offset:4512
	ds_write_b64 v142, v[12:13] offset:448
	ds_write_b64 v141, v[124:125] offset:4544
	ds_write_b64 v142, v[20:21] offset:480
	ds_write_b64 v141, v[178:179] offset:4576
	v_mov_b32_e32 v34, v139
	v_mov_b32_e32 v35, v140
	ds_read_b64 v[2:3], v138
	ds_read_b64 v[0:1], v137 offset:4096
	ds_read_b64 v[20:21], v138 offset:544
	ds_read_b64 v[22:23], v137 offset:4640
	ds_read_b64 v[24:25], v138 offset:1088
	ds_read_b64 v[26:27], v137 offset:5184
	ds_read_b64 v[28:29], v138 offset:1632
	ds_read_b64 v[30:31], v137 offset:5728
	ds_read_b64 v[32:33], v138 offset:2176
	ds_read_b64 v[40:41], v137 offset:6272
	ds_read_b64 v[42:43], v138 offset:2720
	ds_read_b64 v[44:45], v137 offset:6816
	ds_read_b64 v[46:47], v138 offset:3264
	ds_read_b64 v[48:49], v137 offset:7360
	ds_read_b64 v[120:121], v138 offset:3808
	ds_read_b64 v[122:123], v137 offset:7904
	ds_read_b64 v[124:125], v138 offset:4352
	ds_read_b64 v[126:127], v137 offset:8448
	ds_read_b64 v[128:129], v138 offset:4896
	ds_read_b64 v[130:131], v137 offset:8992
	ds_read_b64 v[178:179], v138 offset:5440
	ds_read_b64 v[180:181], v137 offset:9536
	ds_read_b64 v[182:183], v138 offset:5984
	ds_read_b64 v[184:185], v137 offset:10080
	ds_read_b64 v[18:19], v138 offset:6528
	ds_read_b64 v[16:17], v137 offset:10624
	ds_read_b64 v[14:15], v138 offset:7072
	ds_read_b64 v[12:13], v137 offset:11168
	ds_read_b64 v[10:11], v138 offset:7616
	ds_read_b64 v[8:9], v137 offset:11712
	ds_read_b64 v[6:7], v138 offset:8160
	ds_read_b64 v[4:5], v137 offset:12256
	s_nop 1
	v_mul_f32_e32 v36, v35, v35
	v_fma_f32 v37, -v34, v34, v36
	v_mul_f32_e32 v36, v35, v34
	v_fma_f32 v82, v34, v35, v36
	v_mul_f32_e32 v36, v37, v35
	v_fma_f32 v132, -v82, v34, v36
	v_mul_f32_e32 v36, v37, v34
	v_fma_f32 v134, v82, v35, v36
	v_mul_f32_e32 v36, v37, v37
	v_fma_f32 v151, -v82, v82, v36
	v_mul_f32_e32 v36, v37, v82
	v_fma_f32 v170, v82, v37, v36
	v_mul_f32_e32 v36, v151, v35
	v_fma_f32 v171, -v170, v34, v36
	v_mul_f32_e32 v36, v151, v34
	v_fma_f32 v177, v170, v35, v36
	v_mul_f32_e32 v36, v132, v132
	v_fma_f32 v186, -v134, v134, v36
	v_mul_f32_e32 v36, v132, v134
	v_fma_f32 v187, v134, v132, v36
	v_mul_f32_e32 v36, v151, v132
	v_fma_f32 v188, -v170, v134, v36
	v_mul_f32_e32 v36, v151, v134
	v_fma_f32 v189, v170, v132, v36
	v_mul_f32_e32 v36, v151, v151
	v_fma_f32 v190, -v170, v170, v36
	v_mul_f32_e32 v36, v151, v170
	v_fma_f32 v191, v170, v151, v36
	v_mul_f32_e32 v36, v190, v35
	v_fma_f32 v192, -v191, v34, v36
	v_mul_f32_e32 v36, v190, v34
	v_fma_f32 v193, v191, v35, v36
	v_mul_f32_e32 v36, v171, v171
	v_fma_f32 v194, -v177, v177, v36
	v_mul_f32_e32 v36, v171, v177
	v_fma_f32 v195, v177, v171, v36
	v_mul_f32_e32 v36, v190, v132
	v_fma_f32 v196, -v191, v134, v36
	v_mul_f32_e32 v36, v190, v134
	v_fma_f32 v197, v191, v132, v36
	v_mul_f32_e32 v36, v186, v186
	v_fma_f32 v198, -v187, v187, v36
	v_mul_f32_e32 v36, v186, v187
	v_fma_f32 v199, v187, v186, v36
	v_mul_f32_e32 v36, v190, v171
	v_fma_f32 v200, -v191, v177, v36
	v_mul_f32_e32 v36, v190, v177
	v_fma_f32 v201, v191, v171, v36
	v_mul_f32_e32 v36, v188, v188
	v_fma_f32 v202, -v189, v189, v36
	v_mul_f32_e32 v36, v188, v189
	v_fma_f32 v203, v189, v188, v36
	v_mul_f32_e32 v36, v190, v188
	v_fma_f32 v204, -v191, v189, v36
	v_mul_f32_e32 v36, v190, v189
	v_fma_f32 v205, v191, v188, v36
	s_waitcnt lgkmcnt(0)
	v_mul_f32_e32 v36, v20, v35
	v_mul_f32_e32 v20, v20, v34
	v_fma_f32 v206, -v21, v34, v36
	v_fma_f32 v20, v21, v35, v20
	v_mul_f32_e32 v21, v22, v35
	v_fma_f32 v38, -v23, v34, v21
	v_mul_f32_e32 v21, v22, v34
	v_mul_f32_e32 v22, v24, v82
	v_fma_f32 v39, v23, v35, v21
	v_mul_f32_e32 v21, v24, v37
	v_mul_f32_e32 v23, v26, v37
	v_fma_f32 v22, v25, v37, v22
	v_mul_f32_e32 v24, v28, v134
	v_fma_f32 v21, -v25, v82, v21
	v_fma_f32 v36, -v27, v82, v23
	v_mul_f32_e32 v23, v26, v82
	v_mul_f32_e32 v25, v30, v132
	v_fma_f32 v24, v29, v132, v24
	v_mul_f32_e32 v26, v32, v170
	v_fma_f32 v37, v27, v37, v23
	v_mul_f32_e32 v27, v40, v151
	v_fma_f32 v34, -v31, v134, v25
	v_mul_f32_e32 v25, v30, v134
	v_mul_f32_e32 v23, v28, v132
	v_mul_f32_e32 v28, v42, v177
	v_fma_f32 v26, v33, v151, v26
	v_fma_f32 v82, -v41, v170, v27
	v_mul_f32_e32 v27, v40, v170
	v_fma_f32 v35, v31, v132, v25
	v_mul_f32_e32 v31, v48, v186
	v_mul_f32_e32 v25, v32, v151
	v_fma_f32 v28, v43, v171, v28
	v_mul_f32_e32 v32, v120, v189
	v_fma_f32 v132, v41, v151, v27
	v_mul_f32_e32 v27, v42, v171
	v_fma_f32 v42, -v49, v187, v31
	v_mul_f32_e32 v31, v48, v187
	v_fma_f32 v23, -v29, v134, v23
	v_fma_f32 v32, v121, v188, v32
	v_mul_f32_e32 v29, v44, v171
	v_fma_f32 v27, -v43, v177, v27
	v_fma_f32 v25, -v33, v170, v25
	v_fma_f32 v43, v49, v186, v31
	v_mul_f32_e32 v31, v120, v188
	v_mul_f32_e32 v120, v130, v192
	v_fma_f32 v134, -v45, v177, v29
	v_mul_f32_e32 v29, v44, v177
	v_mul_f32_e32 v33, v122, v188
	v_mul_f32_e32 v48, v128, v192
	v_fma_f32 v31, -v121, v189, v31
	v_mul_f32_e32 v121, v130, v193
	v_mul_f32_e32 v130, v18, v198
	v_mul_f32_e32 v18, v18, v199
	v_fma_f32 v44, v45, v171, v29
	v_fma_f32 v40, -v123, v189, v33
	v_mul_f32_e32 v33, v122, v189
	v_mul_f32_e32 v122, v178, v194
	v_fma_f32 v130, -v19, v199, v130
	v_fma_f32 v18, v19, v198, v18
	v_mul_f32_e32 v19, v16, v198
	v_mul_f32_e32 v16, v16, v199
	v_fma_f32 v41, v123, v188, v33
	v_mul_f32_e32 v123, v178, v195
	v_mul_f32_e32 v33, v124, v190
	v_mul_f32_e32 v45, v124, v191
	v_mul_f32_e32 v49, v128, v193
	v_fma_f32 v151, v17, v198, v16
	v_mul_f32_e32 v16, v14, v200
	v_mul_f32_e32 v14, v14, v201
	v_fma_f32 v33, -v125, v191, v33
	v_fma_f32 v45, v125, v190, v45
	v_fma_f32 v122, -v179, v195, v122
	v_fma_f32 v123, v179, v194, v123
	v_fma_f32 v16, -v15, v201, v16
	v_fma_f32 v14, v15, v200, v14
	v_mul_f32_e32 v15, v12, v200
	v_mul_f32_e32 v12, v12, v201
	v_mul_f32_e32 v124, v180, v194
	v_mul_f32_e32 v125, v180, v195
	v_mul_f32_e32 v29, v46, v186
	v_mul_f32_e32 v30, v46, v187
	v_fma_f32 v170, -v13, v201, v15
	v_fma_f32 v171, v13, v200, v12
	v_mul_f32_e32 v12, v10, v202
	v_mul_f32_e32 v10, v10, v203
	v_sub_f32_e32 v13, v26, v18
	v_fma_f32 v48, -v129, v193, v48
	v_fma_f32 v49, v129, v192, v49
	v_fma_f32 v120, -v131, v193, v120
	v_fma_f32 v12, -v11, v203, v12
	v_fma_f32 v10, v11, v202, v10
	v_mul_f32_e32 v11, v8, v202
	v_mul_f32_e32 v8, v8, v203
	v_fma_f32 v121, v131, v192, v121
	v_fma_f32 v131, -v17, v199, v19
	v_fma_f32 v29, -v47, v187, v29
	v_fma_f32 v30, v47, v186, v30
	v_fma_f32 v177, -v9, v203, v11
	v_fma_f32 v178, v9, v202, v8
	v_mul_f32_e32 v8, v6, v204
	v_mul_f32_e32 v6, v6, v205
	v_add_f32_e32 v9, v26, v18
	v_sub_f32_e32 v11, v25, v130
	v_mul_f32_e32 v46, v126, v190
	v_mul_f32_e32 v47, v126, v191
	v_fma_f32 v8, -v7, v205, v8
	v_fma_f32 v6, v7, v204, v6
	v_mul_f32_e32 v7, v4, v204
	v_mul_f32_e32 v4, v4, v205
	v_mul_f32_e32 v126, v182, v196
	v_fma_f32 v46, -v127, v191, v46
	v_fma_f32 v47, v127, v190, v47
	v_mul_f32_e32 v127, v182, v197
	v_fma_f32 v179, -v5, v205, v7
	v_fma_f32 v180, v5, v204, v4
	v_add_f32_e32 v4, v2, v33
	v_add_f32_e32 v5, v3, v45
	v_sub_f32_e32 v2, v2, v33
	v_sub_f32_e32 v3, v3, v45
	v_add_f32_e32 v7, v25, v130
	v_fma_f32 v126, -v183, v197, v126
	v_fma_f32 v127, v183, v196, v127
	v_add_f32_e32 v17, v5, v9
	v_sub_f32_e32 v26, v5, v9
	v_add_f32_e32 v9, v3, v11
	v_add_f32_e32 v15, v4, v7
	v_sub_f32_e32 v25, v4, v7
	v_sub_f32_e32 v7, v2, v13
	v_add_f32_e32 v33, v2, v13
	v_sub_f32_e32 v45, v3, v11
	v_add_f32_e32 v2, v206, v48
	v_add_f32_e32 v3, v20, v49
	v_sub_f32_e32 v4, v206, v48
	v_sub_f32_e32 v5, v20, v49
	v_add_f32_e32 v11, v27, v16
	v_add_f32_e32 v13, v28, v14
	v_sub_f32_e32 v16, v27, v16
	v_sub_f32_e32 v14, v28, v14
	v_sub_f32_e32 v20, v21, v122
	v_add_f32_e32 v27, v30, v10
	v_add_f32_e32 v18, v2, v11
	v_add_f32_e32 v19, v3, v13
	v_sub_f32_e32 v2, v2, v11
	v_sub_f32_e32 v3, v3, v13
	v_sub_f32_e32 v11, v4, v14
	v_add_f32_e32 v13, v5, v16
	v_add_f32_e32 v4, v4, v14
	v_sub_f32_e32 v5, v5, v16
	v_add_f32_e32 v14, v21, v122
	v_add_f32_e32 v16, v22, v123
	v_sub_f32_e32 v10, v30, v10
	v_sub_f32_e32 v21, v22, v123
	v_add_f32_e32 v22, v29, v12
	v_sub_f32_e32 v12, v29, v12
	v_add_f32_e32 v48, v32, v6
	v_add_f32_e32 v29, v16, v27
	v_sub_f32_e32 v6, v32, v6
	v_mul_f32_e32 v2, v2, v154
	v_add_f32_e32 v28, v14, v22
	v_sub_f32_e32 v30, v14, v22
	v_sub_f32_e32 v14, v16, v27
	v_sub_f32_e32 v16, v20, v10
	v_add_f32_e32 v10, v20, v10
	v_add_f32_e32 v20, v23, v126
	v_sub_f32_e32 v23, v23, v126
	v_add_f32_e32 v27, v31, v8
	v_sub_f32_e32 v8, v31, v8
	v_add_f32_e32 v22, v21, v12
	v_sub_f32_e32 v12, v21, v12
	v_add_f32_e32 v21, v24, v127
	v_sub_f32_e32 v24, v24, v127
	v_add_f32_e32 v31, v20, v27
	v_sub_f32_e32 v20, v20, v27
	v_sub_f32_e32 v27, v23, v6
	v_add_f32_e32 v6, v23, v6
	v_mul_f32_e32 v23, v11, v152
	v_mul_f32_e32 v11, v11, v156
	v_add_f32_e32 v32, v21, v48
	v_sub_f32_e32 v21, v21, v48
	v_add_f32_e32 v48, v24, v8
	v_sub_f32_e32 v8, v24, v8
	v_fma_f32 v23, -v13, v156, v23
	v_fma_f32 v13, v13, v152, v11
	v_mul_f32_e32 v11, v16, v154
	v_fma_f32 v49, v3, v154, v2
	v_fma_f32 v124, -v181, v195, v124
	v_fma_f32 v125, v181, v194, v125
	v_xor_b32_e32 v122, 0x80000000, v14
	v_fma_f32 v16, -v22, v154, v11
	v_fma_f32 v22, v22, v154, v11
	v_mul_f32_e32 v11, v27, v156
	v_mul_f32_e32 v128, v184, v196
	v_mul_f32_e32 v129, v184, v197
	v_fma_f32 v24, -v48, v152, v11
	v_mul_f32_e32 v11, v27, v152
	v_fma_f32 v128, -v185, v197, v128
	v_fma_f32 v129, v185, v196, v129
	v_fma_f32 v27, v48, v156, v11
	v_fma_f32 v48, -v3, v154, v2
	v_mul_f32_e32 v2, v20, v155
	v_add_f32_e32 v3, v17, v29
	v_fma_f32 v123, -v21, v154, v2
	v_mul_f32_e32 v2, v20, v154
	v_fma_f32 v20, v21, v155, v2
	v_mul_f32_e32 v2, v4, v156
	v_fma_f32 v21, -v5, v152, v2
	v_mul_f32_e32 v2, v4, v152
	v_add_f32_e32 v4, v18, v31
	v_fma_f32 v126, v5, v156, v2
	v_mul_f32_e32 v2, v10, v155
	v_add_f32_e32 v5, v19, v32
	v_fma_f32 v127, -v12, v154, v2
	v_mul_f32_e32 v2, v10, v154
	v_fma_f32 v130, v12, v155, v2
	v_mul_f32_e32 v2, v6, v157
	v_sub_f32_e32 v12, v18, v31
	v_fma_f32 v181, -v8, v153, v2
	v_mul_f32_e32 v2, v6, v153
	v_sub_f32_e32 v6, v15, v28
	v_fma_f32 v182, v8, v157, v2
	v_add_f32_e32 v2, v15, v28
	v_sub_f32_e32 v8, v17, v29
	v_sub_f32_e32 v17, v19, v32
	v_add_f32_e32 v15, v3, v5
	v_sub_f32_e32 v5, v3, v5
	v_add_f32_e32 v14, v2, v4
	v_sub_f32_e32 v4, v2, v4
	v_sub_f32_e32 v10, v6, v17
	v_add_f32_e32 v11, v8, v12
	v_add_f32_e32 v2, v6, v17
	v_sub_f32_e32 v3, v8, v12
	v_add_f32_e32 v6, v7, v16
	v_add_f32_e32 v12, v9, v22
	v_sub_f32_e32 v7, v7, v16
	v_sub_f32_e32 v16, v9, v22
	v_add_f32_e32 v8, v23, v24
	v_add_f32_e32 v9, v13, v27
	v_sub_f32_e32 v17, v23, v24
	v_sub_f32_e32 v13, v13, v27
	v_sub_f32_e32 v24, v25, v122
	v_add_f32_e32 v22, v6, v8
	v_add_f32_e32 v23, v12, v9
	v_sub_f32_e32 v8, v6, v8
	v_sub_f32_e32 v9, v12, v9
	v_sub_f32_e32 v18, v7, v13
	v_add_f32_e32 v19, v16, v17
	v_add_f32_e32 v6, v7, v13
	v_sub_f32_e32 v7, v16, v17
	v_add_f32_e32 v12, v25, v122
	v_add_f32_e32 v13, v26, v30
	v_sub_f32_e32 v25, v26, v30
	v_add_f32_e32 v16, v48, v123
	v_add_f32_e32 v17, v49, v20
	v_sub_f32_e32 v30, v48, v123
	v_sub_f32_e32 v20, v49, v20
	v_sub_f32_e32 v48, v33, v127
	v_sub_f32_e32 v49, v126, v182
	v_add_f32_e32 v28, v12, v16
	v_add_f32_e32 v29, v13, v17
	v_sub_f32_e32 v16, v12, v16
	v_sub_f32_e32 v17, v13, v17
	v_sub_f32_e32 v26, v24, v20
	v_add_f32_e32 v27, v25, v30
	v_add_f32_e32 v12, v24, v20
	v_sub_f32_e32 v13, v25, v30
	v_add_f32_e32 v20, v33, v127
	v_add_f32_e32 v25, v45, v130
	v_sub_f32_e32 v45, v45, v130
	v_add_f32_e32 v24, v21, v181
	v_add_f32_e32 v30, v126, v182
	v_sub_f32_e32 v21, v21, v181
	v_add_f32_e32 v32, v20, v24
	v_add_f32_e32 v33, v25, v30
	v_sub_f32_e32 v24, v20, v24
	v_sub_f32_e32 v25, v25, v30
	v_sub_f32_e32 v30, v48, v49
	v_add_f32_e32 v31, v45, v21
	v_add_f32_e32 v20, v48, v49
	v_sub_f32_e32 v21, v45, v21
	v_add_f32_e32 v45, v0, v46
	v_add_f32_e32 v48, v1, v47
	v_sub_f32_e32 v0, v0, v46
	v_sub_f32_e32 v1, v1, v47
	v_add_f32_e32 v46, v82, v131
	v_add_f32_e32 v47, v132, v151
	v_sub_f32_e32 v49, v82, v131
	v_sub_f32_e32 v82, v132, v151
	v_add_f32_e32 v122, v45, v46
	v_add_f32_e32 v123, v48, v47
	v_sub_f32_e32 v126, v45, v46
	v_sub_f32_e32 v48, v48, v47
	v_sub_f32_e32 v45, v0, v82
	v_add_f32_e32 v46, v1, v49
	v_add_f32_e32 v82, v0, v82
	v_sub_f32_e32 v127, v1, v49
	v_add_f32_e32 v0, v38, v120
	v_add_f32_e32 v1, v39, v121
	v_sub_f32_e32 v38, v38, v120
	v_sub_f32_e32 v39, v39, v121
	v_add_f32_e32 v47, v134, v170
	v_add_f32_e32 v49, v44, v171
	v_sub_f32_e32 v120, v134, v170
	v_sub_f32_e32 v44, v44, v171
	v_add_f32_e32 v121, v0, v47
	v_add_f32_e32 v130, v1, v49
	v_sub_f32_e32 v0, v0, v47
	v_sub_f32_e32 v1, v1, v49
	v_sub_f32_e32 v47, v38, v44
	v_add_f32_e32 v49, v39, v120
	v_add_f32_e32 v38, v38, v44
	v_sub_f32_e32 v39, v39, v120
	v_add_f32_e32 v44, v36, v124
	v_add_f32_e32 v120, v37, v125
	v_sub_f32_e32 v36, v36, v124
	v_sub_f32_e32 v37, v37, v125
	v_add_f32_e32 v124, v42, v177
	v_add_f32_e32 v125, v43, v178
	v_sub_f32_e32 v42, v42, v177
	v_sub_f32_e32 v43, v43, v178
	v_mul_f32_e32 v0, v0, v154
	v_add_f32_e32 v131, v44, v124
	v_add_f32_e32 v132, v120, v125
	v_sub_f32_e32 v124, v44, v124
	v_sub_f32_e32 v44, v120, v125
	v_sub_f32_e32 v120, v36, v43
	v_add_f32_e32 v125, v37, v42
	v_add_f32_e32 v36, v36, v43
	v_sub_f32_e32 v37, v37, v42
	v_add_f32_e32 v42, v34, v128
	v_add_f32_e32 v43, v35, v129
	v_sub_f32_e32 v34, v34, v128
	v_sub_f32_e32 v35, v35, v129
	v_add_f32_e32 v128, v40, v179
	v_add_f32_e32 v129, v41, v180
	v_sub_f32_e32 v40, v40, v179
	v_sub_f32_e32 v41, v41, v180
	v_xor_b32_e32 v170, 0x80000000, v44
	v_add_f32_e32 v134, v42, v128
	v_add_f32_e32 v151, v43, v129
	v_sub_f32_e32 v42, v42, v128
	v_sub_f32_e32 v43, v43, v129
	v_sub_f32_e32 v128, v34, v41
	v_add_f32_e32 v129, v35, v40
	v_add_f32_e32 v34, v34, v41
	v_sub_f32_e32 v35, v35, v40
	v_mul_f32_e32 v40, v47, v152
	v_mul_f32_e32 v41, v47, v156
	v_mul_f32_e32 v47, v120, v154
	v_mul_f32_e32 v120, v128, v156
	v_fma_f32 v40, -v49, v156, v40
	v_fma_f32 v41, v49, v152, v41
	v_fma_f32 v49, -v125, v154, v47
	v_fma_f32 v47, v125, v154, v47
	v_mul_f32_e32 v125, v128, v152
	v_fma_f32 v120, -v129, v152, v120
	v_fma_f32 v128, -v1, v154, v0
	v_fma_f32 v125, v129, v156, v125
	v_fma_f32 v129, v1, v154, v0
	v_mul_f32_e32 v0, v42, v155
	v_add_f32_e32 v44, v40, v120
	v_sub_f32_e32 v120, v40, v120
	v_fma_f32 v171, -v43, v154, v0
	v_mul_f32_e32 v0, v42, v154
	v_sub_f32_e32 v42, v121, v134
	v_fma_f32 v177, v43, v155, v0
	v_mul_f32_e32 v0, v38, v156
	v_sub_f32_e32 v43, v130, v151
	v_fma_f32 v178, -v39, v152, v0
	v_mul_f32_e32 v0, v38, v152
	v_sub_f32_e32 v38, v122, v131
	v_fma_f32 v179, v39, v156, v0
	v_mul_f32_e32 v0, v36, v155
	v_sub_f32_e32 v39, v123, v132
	v_fma_f32 v180, -v37, v154, v0
	v_mul_f32_e32 v0, v36, v154
	v_add_f32_e32 v36, v121, v134
	v_add_f32_e32 v121, v48, v124
	v_fma_f32 v181, v37, v155, v0
	v_mul_f32_e32 v0, v34, v157
	v_add_f32_e32 v37, v130, v151
	v_fma_f32 v182, -v35, v153, v0
	v_mul_f32_e32 v0, v34, v153
	v_add_f32_e32 v34, v122, v131
	v_add_f32_e32 v122, v128, v171
	v_sub_f32_e32 v128, v128, v171
	v_fma_f32 v183, v35, v157, v0
	v_add_f32_e32 v35, v123, v132
	v_add_f32_e32 v0, v34, v36
	v_sub_f32_e32 v34, v34, v36
	v_sub_f32_e32 v36, v38, v43
	v_add_f32_e32 v38, v38, v43
	v_add_f32_e32 v43, v46, v47
	v_add_f32_e32 v1, v35, v37
	v_sub_f32_e32 v35, v35, v37
	v_add_f32_e32 v37, v39, v42
	v_sub_f32_e32 v39, v39, v42
	v_add_f32_e32 v42, v45, v49
	v_sub_f32_e32 v49, v45, v49
	v_sub_f32_e32 v47, v46, v47
	v_add_f32_e32 v45, v41, v125
	v_sub_f32_e32 v46, v41, v125
	v_sub_f32_e32 v125, v126, v170
	v_add_f32_e32 v123, v129, v177
	v_add_f32_e32 v40, v42, v44
	v_sub_f32_e32 v42, v42, v44
	v_add_f32_e32 v41, v43, v45
	v_sub_f32_e32 v43, v43, v45
	v_add_f32_e32 v45, v47, v120
	v_sub_f32_e32 v47, v47, v120
	v_add_f32_e32 v120, v126, v170
	v_sub_f32_e32 v126, v48, v124
	v_sub_f32_e32 v124, v129, v177
	v_sub_f32_e32 v44, v49, v46
	v_add_f32_e32 v46, v49, v46
	v_add_f32_e32 v49, v121, v123
	v_add_f32_e32 v48, v120, v122
	v_sub_f32_e32 v120, v120, v122
	v_sub_f32_e32 v121, v121, v123
	v_sub_f32_e32 v122, v125, v124
	v_add_f32_e32 v123, v126, v128
	v_add_f32_e32 v124, v125, v124
	v_sub_f32_e32 v125, v126, v128
	v_add_f32_e32 v128, v82, v180
	v_add_f32_e32 v129, v127, v181
	v_add_f32_e32 v130, v178, v182
	v_add_f32_e32 v131, v179, v183
	v_sub_f32_e32 v82, v82, v180
	v_sub_f32_e32 v132, v127, v181
	v_sub_f32_e32 v134, v178, v182
	v_sub_f32_e32 v151, v179, v183
	v_add_f32_e32 v126, v128, v130
	v_add_f32_e32 v127, v129, v131
	v_sub_f32_e32 v128, v128, v130
	v_sub_f32_e32 v129, v129, v131
	v_add_f32_e32 v131, v132, v134
	v_sub_f32_e32 v130, v82, v151
	v_add_f32_e32 v178, v82, v151
	v_sub_f32_e32 v179, v132, v134
	ds_write_b64 v138, v[14:15]
	ds_write_b64 v137, v[0:1] offset:4096
	ds_write_b64 v138, v[22:23] offset:544
	ds_write_b64 v137, v[40:41] offset:4640
	ds_write_b64 v138, v[28:29] offset:1088
	ds_write_b64 v137, v[48:49] offset:5184
	ds_write_b64 v138, v[32:33] offset:1632
	ds_write_b64 v137, v[126:127] offset:5728
	ds_write_b64 v138, v[10:11] offset:2176
	ds_write_b64 v137, v[36:37] offset:6272
	ds_write_b64 v138, v[18:19] offset:2720
	ds_write_b64 v137, v[44:45] offset:6816
	ds_write_b64 v138, v[26:27] offset:3264
	ds_write_b64 v137, v[122:123] offset:7360
	ds_write_b64 v138, v[30:31] offset:3808
	ds_write_b64 v137, v[130:131] offset:7904
	ds_write_b64 v138, v[4:5] offset:4352
	ds_write_b64 v137, v[34:35] offset:8448
	ds_write_b64 v138, v[8:9] offset:4896
	ds_write_b64 v137, v[42:43] offset:8992
	ds_write_b64 v138, v[16:17] offset:5440
	ds_write_b64 v137, v[120:121] offset:9536
	ds_write_b64 v138, v[24:25] offset:5984
	ds_write_b64 v137, v[128:129] offset:10080
	ds_write_b64 v138, v[2:3] offset:6528
	ds_write_b64 v137, v[38:39] offset:10624
	ds_write_b64 v138, v[6:7] offset:7072
	ds_write_b64 v137, v[46:47] offset:11168
	ds_write_b64 v138, v[12:13] offset:7616
	ds_write_b64 v137, v[124:125] offset:11712
	ds_write_b64 v138, v[20:21] offset:8160
	ds_write_b64 v137, v[178:179] offset:12256
	v_lshl_add_u64 v[18:19], s[36:37], 0, v[86:87]
	v_add_co_u32_e32 v0, vcc, s87, v18
	v_lshl_add_u64 v[2:3], s[36:37], 0, v[88:89]
	v_addc_co_u32_e32 v1, vcc, 0, v19, vcc
	v_lshl_add_u64 v[4:5], s[36:37], 0, v[90:91]
	global_load_dwordx4 v[12:15], v[0:1], off nt
	global_load_ushort v177, v[2:3], off
	global_load_ushort v134, v[4:5], off
	v_add_co_u32_e32 v0, vcc, s88, v18
	v_lshl_add_u64 v[16:17], s[36:37], 0, v[98:99]
	v_addc_co_u32_e32 v1, vcc, 0, v19, vcc
	v_lshl_add_u64 v[2:3], s[36:37], 0, v[94:95]
	v_lshl_add_u64 v[4:5], s[36:37], 0, v[96:97]
	global_load_dwordx4 v[8:11], v[0:1], off nt
	global_load_ushort v179, v[2:3], off
	global_load_ushort v178, v[4:5], off
	v_add_co_u32_e32 v0, vcc, s87, v16
	v_lshl_add_u64 v[20:21], s[36:37], 0, v[102:103]
	v_addc_co_u32_e32 v1, vcc, 0, v17, vcc
	v_lshl_add_u64 v[2:3], s[36:37], 0, v[100:101]
	global_load_dwordx4 v[4:7], v[0:1], off nt
	global_load_ushort v131, v[2:3], off
	global_load_ushort v82, v[20:21], off
	v_lshl_add_u64 v[0:1], s[36:37], 0, v[104:105]
	v_lshl_add_u64 v[20:21], s[36:37], 0, v[106:107]
	v_lshl_add_u64 v[22:23], s[36:37], 0, v[108:109]
	global_load_dwordx4 v[0:3], v[0:1], off nt
	global_load_ushort v132, v[20:21], off
	global_load_ushort v130, v[22:23], off
	v_mov_b32_e32 v20, v92
	s_waitcnt lgkmcnt(0)
	s_barrier
	v_ashrrev_i32_e32 v22, 31, v20
	v_lshrrev_b32_e32 v22, 22, v22
	v_add_u32_e32 v22, v20, v22
	v_ashrrev_i32_e32 v22, 10, v22
	v_add_u32_e32 v21, 0x200, v20
	v_mul_i32_i24_e32 v23, 0x400, v22
	v_sub_u32_e32 v24, v20, v23
	v_ashrrev_i32_e32 v23, 31, v21
	v_lshrrev_b32_e32 v23, 22, v23
	v_add_u32_e32 v23, v21, v23
	v_lshl_add_u32 v22, v22, 14, v24
	v_ashrrev_i32_e32 v23, 10, v23
	v_mul_i32_i24_e32 v25, 0x3c00, v23
	v_mad_i32_i24 v21, v23, s64, v21
	v_ashrrev_i32_e32 v23, 4, v22
	v_lshlrev_b32_e32 v23, 3, v23
	v_ashrrev_i32_e32 v21, 4, v21
	v_and_b32_e32 v23, 0xffffffe0, v23
	v_lshlrev_b32_e32 v22, 3, v22
	v_lshlrev_b32_e32 v21, 3, v21
	v_add3_u32 v180, 0, v23, v22
	v_and_b32_e32 v21, 0xffffffe0, v21
	v_add_lshl_u32 v20, v25, v20, 3
	v_add3_u32 v181, 0, v21, v20
	v_add_u32_e32 v25, 0x11000, v180
	ds_read_b64 v[22:23], v180
	ds_read_b64 v[20:21], v181 offset:4096
	ds_read_b64 v[182:183], v180 offset:8704
	ds_read_b64 v[184:185], v181 offset:12800
	ds_read_b64 v[188:189], v180 offset:17408
	ds_read_b64 v[190:191], v181 offset:21504
	ds_read_b64 v[192:193], v180 offset:26112
	ds_read_b64 v[194:195], v181 offset:30208
	ds_read_b64 v[196:197], v180 offset:34816
	ds_read_b64 v[198:199], v181 offset:38912
	ds_read_b64 v[200:201], v180 offset:43520
	ds_read_b64 v[202:203], v181 offset:47616
	ds_read_b64 v[204:205], v180 offset:52224
	ds_read_b64 v[206:207], v181 offset:56320
	ds_read_b64 v[128:129], v180 offset:60928
	ds_read_b64 v[126:127], v181 offset:65024
	ds_read_b64 v[124:125], v25
	v_add_u32_e32 v25, 0x12000, v181
	ds_read_b64 v[122:123], v25
	v_add_u32_e32 v25, 0x13200, v180
	ds_read_b64 v[120:121], v25
	v_add_u32_e32 v25, 0x14200, v181
	ds_read_b64 v[48:49], v25
	v_add_u32_e32 v25, 0x15400, v180
	ds_read_b64 v[46:47], v25
	v_add_u32_e32 v25, 0x16400, v181
	ds_read_b64 v[44:45], v25
	v_add_u32_e32 v25, 0x17600, v180
	ds_read_b64 v[42:43], v25
	v_add_u32_e32 v25, 0x18600, v181
	ds_read_b64 v[40:41], v25
	v_add_u32_e32 v25, 0x19800, v180
	ds_read_b64 v[38:39], v25
	v_add_u32_e32 v25, 0x1a800, v181
	v_cvt_f32_i32_e32 v24, v24
	ds_read_b64 v[36:37], v25
	v_add_u32_e32 v25, 0x1ba00, v180
	ds_read_b64 v[34:35], v25
	v_add_u32_e32 v25, 0x1ca00, v181
	ds_read_b64 v[32:33], v25
	v_add_u32_e32 v25, 0x1dc00, v180
	ds_read_b64 v[28:29], v25
	v_add_u32_e32 v25, 0x1ec00, v181
	v_mul_f32_e32 v24, 0x38800000, v24
	ds_read_b64 v[30:31], v25
	v_add_u32_e32 v25, 0x1fe00, v180
	v_sin_f32_e32 v151, v24
	v_cos_f32_e32 v170, v24
	v_add_u32_e32 v24, 0x20e00, v181
	ds_read_b64 v[26:27], v25
	ds_read_b64 v[24:25], v24
	s_nop 1
	v_mul_f32_e32 v171, v170, v170
	v_mul_f32_e32 v186, v170, v151
	v_fma_f32 v171, -v151, v151, v171
	v_fma_f32 v208, v151, v170, v186
	v_mul_f32_e32 v186, v171, v170
	v_fma_f32 v209, -v208, v151, v186
	v_mul_f32_e32 v186, v171, v151
	v_fma_f32 v210, v208, v170, v186
	v_mul_f32_e32 v186, v171, v171
	v_fma_f32 v211, -v208, v208, v186
	v_mul_f32_e32 v186, v171, v208
	v_fma_f32 v212, v208, v171, v186
	v_mul_f32_e32 v186, v211, v170
	v_fma_f32 v213, -v212, v151, v186
	v_mul_f32_e32 v186, v211, v151
	v_fma_f32 v214, v212, v170, v186
	v_mul_f32_e32 v186, v209, v209
	v_fma_f32 v215, -v210, v210, v186
	v_mul_f32_e32 v186, v209, v210
	v_fma_f32 v216, v210, v209, v186
	v_mul_f32_e32 v186, v211, v209
	v_fma_f32 v217, -v212, v210, v186
	v_mul_f32_e32 v186, v211, v210
	v_fma_f32 v218, v212, v209, v186
	v_mul_f32_e32 v186, v211, v211
	v_fma_f32 v219, -v212, v212, v186
	v_mul_f32_e32 v186, v211, v212
	v_fma_f32 v220, v212, v211, v186
	v_mul_f32_e32 v186, v219, v170
	v_fma_f32 v221, -v220, v151, v186
	v_mul_f32_e32 v186, v219, v151
	v_fma_f32 v222, v220, v170, v186
	v_mul_f32_e32 v186, v213, v213
	v_fma_f32 v223, -v214, v214, v186
	v_mul_f32_e32 v186, v213, v214
	v_fma_f32 v224, v214, v213, v186
	v_mul_f32_e32 v186, v219, v209
	v_fma_f32 v225, -v220, v210, v186
	v_mul_f32_e32 v186, v219, v210
	v_fma_f32 v226, v220, v209, v186
	v_mul_f32_e32 v186, v215, v215
	v_fma_f32 v227, -v216, v216, v186
	v_mul_f32_e32 v186, v215, v216
	v_fma_f32 v228, v216, v215, v186
	v_mul_f32_e32 v186, v219, v213
	v_fma_f32 v229, -v220, v214, v186
	v_mul_f32_e32 v186, v219, v214
	v_fma_f32 v230, v220, v213, v186
	v_mul_f32_e32 v186, v217, v217
	v_fma_f32 v231, -v218, v218, v186
	v_mul_f32_e32 v186, v217, v218
	v_fma_f32 v232, v218, v217, v186
	v_mul_f32_e32 v186, v219, v217
	v_fma_f32 v233, -v220, v218, v186
	v_mul_f32_e32 v186, v219, v218
	v_fma_f32 v234, v220, v217, v186
	s_waitcnt lgkmcnt(0)
	v_mul_f32_e32 v186, v182, v170
	v_mul_f32_e32 v182, v182, v151
	v_fma_f32 v236, v183, v170, v182
	v_mul_f32_e32 v182, s71, v184
	v_fma_f32 v235, -v183, v151, v186
	v_mul_f32_e32 v183, s77, v184
	v_fma_f32 v182, -v185, s77, v182
	v_fma_f32 v183, v185, s71, v183
	v_mul_f32_e32 v184, v182, v170
	v_fma_f32 v186, -v183, v151, v184
	v_mul_f32_e32 v151, v182, v151
	v_mul_f32_e32 v182, s65, v190
	v_fma_f32 v182, -v191, s69, v182
	v_fma_f32 v187, v183, v170, v151
	v_mul_f32_e32 v183, s69, v190
	v_mul_f32_e32 v170, v188, v208
	v_mul_f32_e32 v151, v188, v171
	v_mul_f32_e32 v184, v182, v171
	v_mul_f32_e32 v182, v182, v208
	v_fma_f32 v183, v191, s65, v183
	v_fma_f32 v170, v189, v171, v170
	v_fma_f32 v151, -v189, v208, v151
	v_fma_f32 v185, v183, v171, v182
	v_mul_f32_e32 v182, v192, v210
	v_fma_f32 v184, -v183, v208, v184
	v_mul_f32_e32 v171, v192, v209
	v_mul_f32_e32 v183, s75, v194
	v_fma_f32 v192, v193, v209, v182
	v_mul_f32_e32 v182, s73, v194
	v_fma_f32 v183, v195, s73, v183
	v_fma_f32 v171, -v193, v210, v171
	v_fma_f32 v188, -v195, s75, v182
	v_mul_f32_e32 v182, v188, v209
	v_mul_f32_e32 v188, v188, v210
	v_fma_f32 v182, -v183, v210, v182
	v_fma_f32 v183, v183, v209, v188
	v_mul_f32_e32 v188, v196, v211
	s_waitcnt vmcnt(0)
	v_lshlrev_b32_e32 v210, 16, v13
	v_fma_f32 v193, -v197, v212, v188
	v_mul_f32_e32 v188, v196, v212
	v_fma_f32 v194, v197, v211, v188
	v_mul_f32_e32 v188, s67, v198
	v_fma_f32 v189, -v199, s67, v188
	v_fma_f32 v188, v199, s67, v188
	v_mul_f32_e32 v190, v189, v211
	v_mul_f32_e32 v189, v189, v212
	v_fma_f32 v195, -v188, v212, v190
	v_fma_f32 v196, v188, v211, v189
	v_mul_f32_e32 v188, v200, v213
	v_mul_f32_e32 v189, s73, v202
	v_lshlrev_b32_e32 v211, 16, v14
	v_fma_f32 v197, -v201, v214, v188
	v_mul_f32_e32 v188, v200, v214
	v_fma_f32 v189, v203, s75, v189
	v_and_b32_e32 v14, 0xffff0000, v14
	v_fma_f32 v198, v201, v213, v188
	v_mul_f32_e32 v188, s75, v202
	v_fma_f32 v188, -v203, s73, v188
	v_mul_f32_e32 v190, v188, v213
	v_mul_f32_e32 v188, v188, v214
	v_fma_f32 v191, v189, v213, v188
	v_mul_f32_e32 v188, v204, v215
	v_fma_f32 v190, -v189, v214, v190
	v_mul_f32_e32 v189, s65, v206
	v_fma_f32 v199, -v205, v216, v188
	v_mul_f32_e32 v188, v204, v216
	v_fma_f32 v189, v207, s69, v189
	v_fma_f32 v200, v205, v215, v188
	v_mul_f32_e32 v188, s69, v206
	v_fma_f32 v201, -v207, s65, v188
	v_mul_f32_e32 v188, v201, v215
	v_mul_f32_e32 v201, v201, v216
	v_fma_f32 v188, -v189, v216, v188
	v_fma_f32 v189, v189, v215, v201
	v_mul_f32_e32 v201, v128, v217
	v_mul_f32_e32 v128, v128, v218
	v_fma_f32 v201, -v129, v218, v201
	v_fma_f32 v128, v129, v217, v128
	v_mul_f32_e32 v129, s77, v126
	v_mul_f32_e32 v126, s71, v126
	v_fma_f32 v129, -v127, s71, v129
	v_fma_f32 v127, v127, s77, v126
	v_mul_f32_e32 v126, v129, v217
	v_mul_f32_e32 v129, v129, v218
	v_fma_f32 v126, -v127, v218, v126
	v_fma_f32 v127, v127, v217, v129
	v_mul_f32_e32 v129, v124, v219
	v_mul_f32_e32 v124, v124, v220
	v_fma_f32 v129, -v125, v220, v129
	v_fma_f32 v124, v125, v219, v124
	v_mul_f32_e32 v125, s59, v122
	v_mul_f32_e32 v122, s84, v122
	v_fma_f32 v125, -v123, s84, v125
	v_fma_f32 v122, v123, s59, v122
	v_mul_f32_e32 v123, v125, v219
	v_mul_f32_e32 v125, v125, v220
	v_fma_f32 v123, -v122, v220, v123
	v_fma_f32 v122, v122, v219, v125
	v_mul_f32_e32 v125, v120, v221
	v_mul_f32_e32 v120, v120, v222
	v_fma_f32 v125, -v121, v222, v125
	v_fma_f32 v120, v121, v221, v120
	v_mul_f32_e32 v121, s72, v48
	v_mul_f32_e32 v48, s71, v48
	v_fma_f32 v121, -v49, s71, v121
	v_fma_f32 v48, v49, s72, v48
	v_mul_f32_e32 v49, v121, v221
	v_mul_f32_e32 v121, v121, v222
	v_fma_f32 v49, -v48, v222, v49
	v_fma_f32 v48, v48, v221, v121
	v_mul_f32_e32 v121, v46, v223
	v_mul_f32_e32 v46, v46, v224
	v_fma_f32 v121, -v47, v224, v121
	v_fma_f32 v46, v47, v223, v46
	v_mul_f32_e32 v47, s66, v44
	v_mul_f32_e32 v44, s65, v44
	v_fma_f32 v47, -v45, s65, v47
	v_fma_f32 v44, v45, s66, v44
	v_mul_f32_e32 v45, v47, v223
	v_mul_f32_e32 v47, v47, v224
	v_fma_f32 v45, -v44, v224, v45
	v_fma_f32 v44, v44, v223, v47
	v_mul_f32_e32 v47, v42, v225
	v_mul_f32_e32 v42, v42, v226
	v_fma_f32 v47, -v43, v226, v47
	v_fma_f32 v42, v43, v225, v42
	v_mul_f32_e32 v43, s74, v40
	v_mul_f32_e32 v40, s73, v40
	v_fma_f32 v43, -v41, s73, v43
	v_fma_f32 v40, v41, s74, v40
	v_mul_f32_e32 v41, v43, v225
	v_mul_f32_e32 v43, v43, v226
	v_fma_f32 v41, -v40, v226, v41
	v_fma_f32 v40, v40, v225, v43
	v_mul_f32_e32 v43, v38, v227
	v_mul_f32_e32 v38, v38, v228
	v_fma_f32 v43, -v39, v228, v43
	v_fma_f32 v38, v39, v227, v38
	v_mul_f32_e32 v39, s68, v36
	v_mul_f32_e32 v36, s67, v36
	v_fma_f32 v39, -v37, s67, v39
	v_fma_f32 v36, v37, s68, v36
	v_mul_f32_e32 v37, v39, v227
	v_fma_f32 v202, -v36, v228, v37
	v_mul_f32_e32 v37, v39, v228
	v_fma_f32 v39, v36, v227, v37
	v_mul_f32_e32 v36, v34, v229
	v_mul_f32_e32 v34, v34, v230
	v_fma_f32 v36, -v35, v230, v36
	v_fma_f32 v34, v35, v229, v34
	v_mul_f32_e32 v35, s76, v32
	v_mul_f32_e32 v32, s75, v32
	v_fma_f32 v35, -v33, s75, v35
	v_fma_f32 v32, v33, s76, v32
	v_mul_f32_e32 v33, v35, v229
	v_fma_f32 v203, -v32, v230, v33
	v_mul_f32_e32 v33, v35, v230
	v_fma_f32 v204, v32, v229, v33
	v_mul_f32_e32 v32, v28, v231
	v_mul_f32_e32 v28, v28, v232
	v_sub_f32_e32 v33, v194, v38
	v_fma_f32 v32, -v29, v232, v32
	v_fma_f32 v28, v29, v231, v28
	v_mul_f32_e32 v29, s70, v30
	v_mul_f32_e32 v30, s69, v30
	v_fma_f32 v29, -v31, s69, v29
	v_fma_f32 v30, v31, s70, v30
	v_mul_f32_e32 v31, v29, v231
	v_mul_f32_e32 v29, v29, v232
	v_fma_f32 v206, v30, v231, v29
	v_mul_f32_e32 v29, v26, v233
	v_mul_f32_e32 v26, v26, v234
	v_fma_f32 v205, -v30, v232, v31
	v_add_f32_e32 v30, v194, v38
	v_sub_f32_e32 v31, v193, v43
	v_fma_f32 v29, -v27, v234, v29
	v_fma_f32 v26, v27, v233, v26
	v_mul_f32_e32 v27, s78, v24
	v_mul_f32_e32 v24, s77, v24
	v_fma_f32 v27, -v25, s77, v27
	v_fma_f32 v24, v25, s78, v24
	v_mul_f32_e32 v25, v27, v233
	v_fma_f32 v207, -v24, v234, v25
	v_mul_f32_e32 v25, v27, v234
	v_add_f32_e32 v27, v193, v43
	v_fma_f32 v208, v24, v233, v25
	v_add_f32_e32 v24, v22, v129
	v_add_f32_e32 v25, v23, v124
	v_sub_f32_e32 v22, v22, v129
	v_sub_f32_e32 v23, v23, v124
	v_add_f32_e32 v35, v24, v27
	v_add_f32_e32 v37, v25, v30
	v_sub_f32_e32 v38, v24, v27
	v_sub_f32_e32 v43, v25, v30
	v_sub_f32_e32 v24, v22, v33
	v_add_f32_e32 v25, v23, v31
	v_add_f32_e32 v33, v22, v33
	v_sub_f32_e32 v124, v23, v31
	v_add_f32_e32 v22, v235, v125
	v_add_f32_e32 v23, v236, v120
	v_sub_f32_e32 v27, v235, v125
	v_sub_f32_e32 v30, v236, v120
	v_add_f32_e32 v31, v197, v36
	v_add_f32_e32 v120, v198, v34
	v_sub_f32_e32 v36, v197, v36
	v_sub_f32_e32 v34, v198, v34
	v_add_f32_e32 v125, v22, v31
	v_add_f32_e32 v129, v23, v120
	v_sub_f32_e32 v22, v22, v31
	v_sub_f32_e32 v23, v23, v120
	v_sub_f32_e32 v31, v27, v34
	v_add_f32_e32 v120, v30, v36
	v_add_f32_e32 v27, v27, v34
	v_sub_f32_e32 v30, v30, v36
	v_add_f32_e32 v34, v151, v121
	v_add_f32_e32 v36, v170, v46
	v_sub_f32_e32 v121, v151, v121
	v_sub_f32_e32 v46, v170, v46
	v_add_f32_e32 v151, v199, v32
	v_add_f32_e32 v170, v200, v28
	v_sub_f32_e32 v32, v199, v32
	v_sub_f32_e32 v28, v200, v28
	v_mul_f32_e32 v22, v22, v154
	v_add_f32_e32 v193, v34, v151
	v_add_f32_e32 v194, v36, v170
	v_sub_f32_e32 v34, v34, v151
	v_sub_f32_e32 v36, v36, v170
	v_sub_f32_e32 v151, v121, v28
	v_add_f32_e32 v170, v46, v32
	v_add_f32_e32 v28, v121, v28
	v_sub_f32_e32 v32, v46, v32
	v_add_f32_e32 v46, v171, v47
	v_add_f32_e32 v121, v192, v42
	v_sub_f32_e32 v47, v171, v47
	v_sub_f32_e32 v42, v192, v42
	v_add_f32_e32 v171, v201, v29
	v_add_f32_e32 v192, v128, v26
	v_sub_f32_e32 v29, v201, v29
	v_sub_f32_e32 v26, v128, v26
	v_xor_b32_e32 v36, 0x80000000, v36
	v_add_f32_e32 v128, v46, v171
	v_add_f32_e32 v197, v121, v192
	v_sub_f32_e32 v46, v46, v171
	v_sub_f32_e32 v121, v121, v192
	v_sub_f32_e32 v171, v47, v26
	v_add_f32_e32 v192, v42, v29
	v_add_f32_e32 v26, v47, v26
	v_sub_f32_e32 v29, v42, v29
	v_mul_f32_e32 v42, v31, v152
	v_mul_f32_e32 v31, v31, v156
	v_mul_f32_e32 v47, v151, v154
	v_mul_f32_e32 v151, v171, v156
	v_fma_f32 v42, -v120, v156, v42
	v_fma_f32 v31, v120, v152, v31
	v_fma_f32 v120, -v170, v154, v47
	v_fma_f32 v47, v170, v154, v47
	v_mul_f32_e32 v170, v171, v152
	v_fma_f32 v151, -v192, v152, v151
	v_fma_f32 v171, -v23, v154, v22
	v_fma_f32 v170, v192, v156, v170
	v_fma_f32 v192, v23, v154, v22
	v_mul_f32_e32 v22, v46, v155
	v_add_f32_e32 v23, v37, v194
	v_fma_f32 v198, -v121, v154, v22
	v_mul_f32_e32 v22, v46, v154
	v_fma_f32 v46, v121, v155, v22
	v_mul_f32_e32 v22, v27, v156
	v_fma_f32 v121, -v30, v152, v22
	v_mul_f32_e32 v22, v27, v152
	v_add_f32_e32 v27, v129, v197
	v_fma_f32 v199, v30, v156, v22
	v_mul_f32_e32 v22, v28, v155
	v_sub_f32_e32 v30, v125, v128
	v_add_f32_e32 v27, v23, v27
	v_fma_f32 v200, -v32, v154, v22
	v_mul_f32_e32 v22, v28, v154
	v_sub_f32_e32 v28, v35, v193
	v_fma_f32 v32, v32, v155, v22
	v_mul_f32_e32 v22, v26, v157
	v_fma_f32 v201, -v29, v153, v22
	v_mul_f32_e32 v22, v26, v153
	v_add_f32_e32 v26, v125, v128
	v_sub_f32_e32 v125, v191, v204
	v_fma_f32 v209, v29, v157, v22
	v_add_f32_e32 v22, v35, v193
	v_sub_f32_e32 v29, v37, v194
	v_sub_f32_e32 v35, v129, v197
	v_sub_f32_e32 v37, v42, v151
	v_and_b32_e32 v197, 0xffff0000, v13
	v_add_f32_e32 v26, v22, v26
	v_sub_f32_e32 v22, v28, v35
	v_add_f32_e32 v23, v29, v30
	v_add_f32_e32 v28, v24, v120
	v_add_f32_e32 v29, v25, v47
	v_sub_f32_e32 v24, v24, v120
	v_sub_f32_e32 v25, v25, v47
	v_add_f32_e32 v30, v42, v151
	v_add_f32_e32 v35, v31, v170
	v_sub_f32_e32 v42, v31, v170
	v_sub_f32_e32 v47, v195, v202
	v_add_f32_e32 v151, v188, v205
	v_add_f32_e32 v25, v25, v37
	v_add_f32_e32 v30, v28, v30
	v_add_f32_e32 v31, v29, v35
	v_sub_f32_e32 v24, v24, v42
	v_add_f32_e32 v28, v38, v36
	v_add_f32_e32 v29, v43, v34
	v_sub_f32_e32 v36, v38, v36
	v_sub_f32_e32 v37, v43, v34
	v_add_f32_e32 v34, v171, v198
	v_add_f32_e32 v35, v192, v46
	v_sub_f32_e32 v38, v171, v198
	v_sub_f32_e32 v42, v192, v46
	v_sub_f32_e32 v43, v121, v201
	v_sub_f32_e32 v46, v199, v209
	v_add_f32_e32 v34, v28, v34
	v_add_f32_e32 v35, v29, v35
	v_add_f32_e32 v29, v37, v38
	v_sub_f32_e32 v28, v36, v42
	v_add_f32_e32 v36, v33, v200
	v_add_f32_e32 v37, v124, v32
	v_sub_f32_e32 v33, v33, v200
	v_sub_f32_e32 v38, v124, v32
	v_add_f32_e32 v32, v121, v201
	v_add_f32_e32 v42, v199, v209
	v_add_f32_e32 v170, v189, v206
	v_sub_f32_e32 v171, v188, v205
	v_and_b32_e32 v205, 0xffff0000, v8
	v_add_f32_e32 v36, v36, v32
	v_add_f32_e32 v37, v37, v42
	v_sub_f32_e32 v32, v33, v46
	v_add_f32_e32 v33, v38, v43
	v_add_f32_e32 v38, v20, v123
	v_add_f32_e32 v42, v21, v122
	v_sub_f32_e32 v20, v20, v123
	v_sub_f32_e32 v21, v21, v122
	v_add_f32_e32 v43, v195, v202
	v_add_f32_e32 v46, v196, v39
	v_sub_f32_e32 v39, v196, v39
	v_and_b32_e32 v195, 0xffff0000, v12
	v_add_f32_e32 v120, v38, v43
	v_add_f32_e32 v121, v42, v46
	v_sub_f32_e32 v122, v38, v43
	v_sub_f32_e32 v46, v42, v46
	v_sub_f32_e32 v42, v20, v39
	v_add_f32_e32 v43, v21, v47
	v_add_f32_e32 v123, v20, v39
	v_sub_f32_e32 v124, v21, v47
	v_add_f32_e32 v20, v186, v49
	v_add_f32_e32 v21, v187, v48
	v_sub_f32_e32 v38, v186, v49
	v_sub_f32_e32 v39, v187, v48
	v_add_f32_e32 v47, v190, v203
	v_add_f32_e32 v48, v191, v204
	v_sub_f32_e32 v49, v190, v203
	v_mov_b32_e32 v196, v195
	v_add_f32_e32 v128, v20, v47
	v_add_f32_e32 v129, v21, v48
	v_sub_f32_e32 v20, v20, v47
	v_sub_f32_e32 v21, v21, v48
	v_sub_f32_e32 v47, v38, v125
	v_add_f32_e32 v48, v39, v49
	v_add_f32_e32 v38, v38, v125
	v_sub_f32_e32 v39, v39, v49
	v_add_f32_e32 v49, v184, v45
	v_add_f32_e32 v125, v185, v44
	v_sub_f32_e32 v45, v184, v45
	v_sub_f32_e32 v44, v185, v44
	v_sub_f32_e32 v184, v189, v206
	v_mul_f32_e32 v20, v20, v154
	v_add_f32_e32 v185, v49, v151
	v_add_f32_e32 v186, v125, v170
	v_sub_f32_e32 v49, v49, v151
	v_sub_f32_e32 v125, v125, v170
	v_sub_f32_e32 v151, v45, v184
	v_add_f32_e32 v170, v44, v171
	v_add_f32_e32 v45, v45, v184
	v_sub_f32_e32 v44, v44, v171
	v_add_f32_e32 v171, v182, v41
	v_add_f32_e32 v184, v183, v40
	v_sub_f32_e32 v41, v182, v41
	v_sub_f32_e32 v40, v183, v40
	v_add_f32_e32 v182, v126, v207
	v_sub_f32_e32 v126, v126, v207
	v_add_f32_e32 v183, v127, v208
	v_sub_f32_e32 v127, v127, v208
	v_xor_b32_e32 v125, 0x80000000, v125
	v_add_f32_e32 v187, v171, v182
	v_add_f32_e32 v188, v184, v183
	v_sub_f32_e32 v171, v171, v182
	v_sub_f32_e32 v182, v184, v183
	v_add_f32_e32 v184, v40, v126
	v_sub_f32_e32 v40, v40, v126
	v_mul_f32_e32 v126, v47, v152
	v_mul_f32_e32 v47, v47, v156
	v_sub_f32_e32 v183, v41, v127
	v_add_f32_e32 v41, v41, v127
	v_lshlrev_b32_e32 v204, 16, v8
	v_fma_f32 v126, -v48, v156, v126
	v_fma_f32 v47, v48, v152, v47
	v_mul_f32_e32 v48, v151, v154
	v_mul_f32_e32 v151, v183, v156
	v_mov_b32_e32 v13, v210
	v_fma_f32 v127, -v170, v154, v48
	v_fma_f32 v48, v170, v154, v48
	v_mul_f32_e32 v170, v183, v152
	v_fma_f32 v151, -v184, v152, v151
	v_fma_f32 v183, -v21, v154, v20
	v_lshlrev_b32_e32 v199, 16, v15
	v_fma_f32 v170, v184, v156, v170
	v_fma_f32 v184, v21, v154, v20
	v_mul_f32_e32 v20, v171, v155
	v_add_f32_e32 v21, v121, v186
	v_and_b32_e32 v15, 0xffff0000, v15
	v_fma_f32 v189, -v182, v154, v20
	v_mul_f32_e32 v20, v171, v154
	v_mov_b32_e32 v198, v14
	v_fma_f32 v171, v182, v155, v20
	v_mul_f32_e32 v20, v38, v156
	v_and_b32_e32 v207, 0xffff0000, v9
	v_fma_f32 v182, -v39, v152, v20
	v_mul_f32_e32 v20, v38, v152
	v_sub_f32_e32 v38, v120, v185
	v_mov_b32_e32 v206, v205
	v_fma_f32 v190, v39, v156, v20
	v_mul_f32_e32 v20, v45, v155
	v_sub_f32_e32 v39, v121, v186
	v_sub_f32_e32 v121, v184, v171
	v_lshlrev_b32_e32 v209, 16, v11
	v_fma_f32 v191, -v44, v154, v20
	v_mul_f32_e32 v20, v45, v154
	v_sub_f32_e32 v45, v129, v188
	v_and_b32_e32 v11, 0xffff0000, v11
	v_fma_f32 v192, v44, v155, v20
	v_mul_f32_e32 v20, v41, v157
	v_sub_f32_e32 v44, v128, v187
	v_sub_f32_e32 v38, v38, v45
	v_add_f32_e32 v45, v47, v170
	v_sub_f32_e32 v47, v47, v170
	v_mov_b32_e32 v202, v209
	v_fma_f32 v193, -v40, v153, v20
	v_mul_f32_e32 v20, v41, v153
	v_add_f32_e32 v41, v129, v188
	v_add_f32_e32 v39, v39, v44
	v_add_f32_e32 v44, v126, v151
	v_fma_f32 v194, v40, v157, v20
	v_add_f32_e32 v20, v120, v185
	v_add_f32_e32 v40, v128, v187
	v_add_f32_e32 v21, v21, v41
	v_add_f32_e32 v41, v43, v48
	v_sub_f32_e32 v43, v43, v48
	v_sub_f32_e32 v48, v126, v151
	v_sub_f32_e32 v120, v183, v189
	v_add_f32_e32 v20, v20, v40
	v_add_f32_e32 v40, v42, v127
	v_sub_f32_e32 v42, v42, v127
	v_add_f32_e32 v41, v41, v45
	v_add_f32_e32 v43, v43, v48
	v_add_f32_e32 v45, v46, v49
	v_sub_f32_e32 v48, v46, v49
	v_add_f32_e32 v40, v40, v44
	v_sub_f32_e32 v42, v42, v47
	v_add_f32_e32 v44, v122, v125
	v_sub_f32_e32 v47, v122, v125
	v_add_f32_e32 v46, v183, v189
	v_add_f32_e32 v49, v184, v171
	v_add_f32_e32 v122, v182, v193
	v_sub_f32_e32 v125, v190, v194
	v_lshl_add_u64 v[126:127], v[58:59], 1, s[44:45]
	v_add_f32_e32 v44, v44, v46
	v_add_f32_e32 v45, v45, v49
	v_sub_f32_e32 v46, v47, v121
	v_add_f32_e32 v47, v48, v120
	v_add_f32_e32 v48, v123, v191
	v_add_f32_e32 v49, v124, v192
	v_sub_f32_e32 v120, v123, v191
	v_sub_f32_e32 v121, v124, v192
	v_add_f32_e32 v123, v190, v194
	v_sub_f32_e32 v124, v182, v193
	v_add_f32_e32 v48, v48, v122
	v_lshl_add_u64 v[128:129], v[60:61], 1, s[44:45]
	v_add_f32_e32 v49, v49, v123
	v_sub_f32_e32 v120, v120, v125
	v_add_f32_e32 v121, v121, v124
	ds_write_b64 v180, v[26:27]
	ds_write_b64 v181, v[20:21] offset:4096
	ds_write_b64 v180, v[30:31] offset:8704
	ds_write_b64 v181, v[40:41] offset:12800
	ds_write_b64 v180, v[34:35] offset:17408
	ds_write_b64 v181, v[44:45] offset:21504
	ds_write_b64 v180, v[36:37] offset:26112
	ds_write_b64 v181, v[48:49] offset:30208
	ds_write_b64 v180, v[22:23] offset:34816
	ds_write_b64 v181, v[38:39] offset:38912
	ds_write_b64 v180, v[24:25] offset:43520
	ds_write_b64 v181, v[42:43] offset:47616
	ds_write_b64 v180, v[28:29] offset:52224
	ds_write_b64 v181, v[46:47] offset:56320
	ds_write_b64 v180, v[32:33] offset:60928
	ds_write_b64 v181, v[120:121] offset:65024
	s_waitcnt lgkmcnt(0)
	s_barrier
	v_lshl_add_u64 v[34:35], v[84:85], 0, s[0:1]
	s_add_u32 s0, s40, s26
	s_addc_u32 s1, s41, s27
	global_load_dword v21, v83, s[48:49]
	global_load_dword v20, v175, s[48:49]
	global_load_dword v22, v83, s[0:1]
	global_load_dword v24, v176, s[48:49]
	v_add_co_u32_e32 v32, vcc, s58, v34
	v_lshl_add_u64 v[38:39], v[50:51], 1, s[44:45]
	v_addc_co_u32_e32 v33, vcc, 0, v35, vcc
	v_add_co_u32_e32 v36, vcc, s60, v34
	v_lshl_add_u64 v[46:47], v[52:53], 1, s[44:45]
	v_addc_co_u32_e32 v37, vcc, 0, v35, vcc
	v_add_co_u32_e32 v40, vcc, s61, v34
	v_lshl_add_u64 v[48:49], v[54:55], 1, s[44:45]
	v_addc_co_u32_e32 v41, vcc, 0, v35, vcc
	v_lshl_add_u64 v[124:125], v[56:57], 1, s[44:45]
	global_load_ushort v23, v[34:35], off nt
	global_load_ushort v25, v[34:35], off offset:2048 nt
	global_load_ushort v26, v[32:33], off offset:2048 nt
	global_load_ushort v27, v[40:41], off nt
	global_load_ushort v28, v[34:35], off offset:3072 nt
	global_load_ushort v30, v[32:33], off offset:3072 nt
	global_load_ushort v32, v[32:33], off offset:1024 nt
	global_load_ushort v31, v[34:35], off offset:1024 nt
	global_load_ushort v42, v[36:37], off offset:-4096 nt
	global_load_ushort v44, v[36:37], off nt
	global_load_ushort v45, v[36:37], off offset:2048 nt
	global_load_ushort v121, v[36:37], off offset:3072 nt
	global_load_ushort v122, v[36:37], off offset:1024 nt
	global_load_ushort v29, v[40:41], off offset:2048 nt
	global_load_ushort v33, v[38:39], off nt
	global_load_ushort v34, v[46:47], off nt
	global_load_ushort v35, v[48:49], off nt
	global_load_ushort v36, v[124:125], off nt
	global_load_ushort v37, v[126:127], off nt
	global_load_ushort v38, v[40:41], off offset:3072 nt
	global_load_ushort v39, v[40:41], off offset:1024 nt
	v_lshl_add_u64 v[46:47], v[66:67], 1, s[44:45]
	v_lshl_add_u64 v[48:49], v[68:69], 1, s[44:45]
	v_lshl_add_u64 v[180:181], v[62:63], 1, s[44:45]
	v_lshl_add_u64 v[182:183], v[64:65], 1, s[44:45]
	v_lshl_add_u64 v[124:125], v[70:71], 1, s[44:45]
	v_lshl_add_u64 v[126:127], v[72:73], 1, s[44:45]
	v_lshl_add_u64 v[184:185], v[74:75], 1, s[44:45]
	global_load_ushort v40, v[128:129], off nt
	global_load_ushort v41, v[180:181], off nt
	global_load_ushort v43, v[182:183], off nt
	global_load_ushort v46, v[46:47], off nt
	global_load_ushort v47, v[48:49], off nt
	global_load_ushort v48, v[124:125], off nt
	global_load_ushort v49, v[126:127], off nt
	global_load_ushort v120, v[184:185], off nt
	v_lshl_add_u64 v[124:125], v[76:77], 1, s[44:45]
	v_lshl_add_u64 v[126:127], v[78:79], 1, s[44:45]
	v_lshl_add_u64 v[128:129], v[80:81], 1, s[44:45]
	global_load_ushort v123, v[124:125], off nt
	global_load_ushort v124, v[126:127], off nt
	global_load_ushort v125, v[128:129], off nt
	v_lshlrev_b32_e32 v126, 16, v177
	v_cndmask_b32_e64 v191, 0, v126, s[12:13]
	v_lshlrev_b32_e32 v126, 16, v134
	v_lshlrev_b32_e32 v194, 16, v12
	v_lshlrev_b32_e32 v12, 16, v179
	v_mov_b32_e32 v190, v210
	v_cndmask_b32_e64 v193, 0, v126, s[4:5]
	v_cndmask_b32_e64 v201, 0, v12, s[12:13]
	v_lshlrev_b32_e32 v12, 16, v178
	ds_read_b128 v[126:129], v145
	ds_read_b128 v[178:181], v145 offset:16
	ds_read_b128 v[182:185], v145 offset:32
	ds_read_b128 v[186:189], v145 offset:48
	v_cndmask_b32_e64 v203, 0, v12, s[4:5]
	v_mov_b32_e32 v12, v194
	v_mov_b32_e32 v192, v199
	s_add_u32 s24, s24, s34
	s_addc_u32 s25, s25, s35
	s_add_u32 s42, s42, s34
	s_addc_u32 s43, s43, s35
	s_add_u32 s40, s40, s34
	s_addc_u32 s41, s41, s35
	s_add_u32 s36, s36, s38
	s_addc_u32 s37, s37, s39
	s_mov_b32 s44, s52
	s_waitcnt vmcnt(35)
	v_mov_b32_e32 v8, v21
	s_waitcnt vmcnt(34)
	v_pk_mul_f32 v[190:191], v[190:191], v[20:21]
	v_pk_fma_f32 v[190:191], v[20:21], v[194:195], v[190:191] op_sel:[0,0,1] op_sel_hi:[1,1,0]
	v_pk_mul_f32 v[194:195], v[20:21], v[196:197] op_sel_hi:[0,1]
	s_waitcnt vmcnt(30)
	v_pk_fma_f32 v[190:191], v[24:25], v[196:197], v[190:191] op_sel_hi:[0,1,1]
	v_pk_fma_f32 v[12:13], v[8:9], v[12:13], v[194:195] op_sel_hi:[0,1,1]
	v_pk_add_f32 v[190:191], v[22:23], v[190:191] op_sel_hi:[0,1]
	v_pk_fma_f32 v[12:13], v[24:25], v[210:211], v[12:13] op_sel_hi:[0,1,1]
	s_waitcnt lgkmcnt(3)
	v_mov_b32_e32 v194, v126
	s_waitcnt lgkmcnt(2)
	v_mov_b32_e32 v195, v178
	v_pk_add_f32 v[12:13], v[22:23], v[12:13] op_sel_hi:[0,1]
	v_pk_mul_f32 v[190:191], v[194:195], v[190:191]
	v_mov_b32_e32 v194, v128
	v_mov_b32_e32 v195, v180
	v_pk_mul_f32 v[12:13], v[194:195], v[12:13]
	v_pk_mov_b32 v[194:195], v[196:197], v[14:15] op_sel:[1,0]
	v_mov_b32_e32 v196, v211
	v_mov_b32_e32 v197, v199
	v_pk_mul_f32 v[196:197], v[20:21], v[196:197] op_sel_hi:[0,1]
	v_pk_fma_f32 v[194:195], v[8:9], v[194:195], v[196:197] op_sel_hi:[0,1,1]
	v_mov_b32_e32 v210, v15
	v_pk_fma_f32 v[194:195], v[24:25], v[14:15], v[194:195] op_sel_hi:[0,1,1]
	v_pk_mul_f32 v[14:15], v[20:21], v[210:211]
	v_pk_add_f32 v[194:195], v[22:23], v[194:195] op_sel_hi:[0,1]
	v_pk_fma_f32 v[14:15], v[20:21], v[198:199], v[14:15] op_sel:[0,0,1] op_sel_hi:[1,1,0]
	v_bfe_u32 v134, v13, 16, 1
	v_pk_fma_f32 v[14:15], v[24:25], v[192:193], v[14:15] op_sel_hi:[0,1,1]
	s_waitcnt lgkmcnt(1)
	v_mov_b32_e32 v192, v182
	s_waitcnt lgkmcnt(0)
	v_mov_b32_e32 v193, v186
	v_pk_add_f32 v[14:15], v[22:23], v[14:15] op_sel_hi:[0,1]
	v_pk_mul_f32 v[192:193], v[194:195], v[192:193]
	v_mov_b32_e32 v194, v184
	v_mov_b32_e32 v195, v188
	v_pk_mul_f32 v[14:15], v[14:15], v[194:195]
	v_add3_u32 v13, v13, v134, s89
	v_bfe_u32 v126, v15, 16, 1
	v_bfe_u32 v128, v14, 16, 1
	v_bfe_u32 v134, v190, 16, 1
	v_bfe_u32 v151, v12, 16, 1
	v_add3_u32 v14, v14, v128, s89
	v_add3_u32 v15, v15, v126, s89
	v_bfe_u32 v126, v192, 16, 1
	v_bfe_u32 v128, v193, 16, 1
	v_add3_u32 v134, v190, v134, s89
	v_lshlrev_b32_e32 v190, 16, v9
	v_add3_u32 v12, v12, v151, s89
	v_bfe_u32 v151, v191, 16, 1
	v_add3_u32 v128, v193, v128, s89
	v_add3_u32 v126, v192, v126, s89
	v_mov_b32_e32 v192, v204
	v_mov_b32_e32 v193, v190
	v_mov_b32_e32 v200, v190
	v_pk_mul_f32 v[196:197], v[20:21], v[206:207] op_sel_hi:[0,1]
	v_add3_u32 v151, v191, v151, s89
	v_lshlrev_b32_e32 v191, 16, v10
	v_pk_mul_f32 v[194:195], v[200:201], v[20:21]
	v_pk_fma_f32 v[192:193], v[8:9], v[192:193], v[196:197] op_sel_hi:[0,1,1]
	v_pk_fma_f32 v[194:195], v[20:21], v[204:205], v[194:195] op_sel:[0,0,1] op_sel_hi:[1,1,0]
	v_pk_fma_f32 v[192:193], v[24:25], v[190:191], v[192:193] op_sel_hi:[0,1,1]
	v_lshrrev_b32_e32 v128, 16, v128
	v_pk_fma_f32 v[194:195], v[24:25], v[206:207], v[194:195] op_sel_hi:[0,1,1]
	v_pk_add_f32 v[192:193], v[22:23], v[192:193] op_sel_hi:[0,1]
	v_mov_b32_e32 v180, v129
	v_lshrrev_b32_e32 v126, 16, v126
	v_and_or_b32 v15, v15, s85, v128
	v_pk_add_f32 v[194:195], v[22:23], v[194:195] op_sel_hi:[0,1]
	v_mov_b32_e32 v178, v127
	v_pk_mul_f32 v[128:129], v[180:181], v[192:193]
	v_and_b32_e32 v10, 0xffff0000, v10
	v_mov_b32_e32 v180, v191
	v_mov_b32_e32 v181, v209
	v_and_or_b32 v14, v14, s85, v126
	v_pk_mul_f32 v[126:127], v[178:179], v[194:195]
	v_pk_mov_b32 v[178:179], v[206:207], v[10:11] op_sel:[1,0]
	v_pk_mul_f32 v[180:181], v[20:21], v[180:181] op_sel_hi:[0,1]
	v_pk_fma_f32 v[178:179], v[8:9], v[178:179], v[180:181] op_sel_hi:[0,1,1]
	v_mov_b32_e32 v190, v11
	v_mov_b32_e32 v208, v10
	v_pk_fma_f32 v[178:179], v[24:25], v[10:11], v[178:179] op_sel_hi:[0,1,1]
	v_pk_mul_f32 v[10:11], v[20:21], v[190:191]
	v_mov_b32_e32 v188, v185
	v_pk_fma_f32 v[10:11], v[20:21], v[208:209], v[10:11] op_sel:[0,0,1] op_sel_hi:[1,1,0]
	v_pk_add_f32 v[178:179], v[22:23], v[178:179] op_sel_hi:[0,1]
	v_pk_fma_f32 v[10:11], v[24:25], v[202:203], v[10:11] op_sel_hi:[0,1,1]
	v_pk_add_f32 v[10:11], v[22:23], v[10:11] op_sel_hi:[0,1]
	v_mov_b32_e32 v186, v183
	v_pk_mul_f32 v[10:11], v[10:11], v[188:189]
	v_lshrrev_b32_e32 v134, 16, v134
	v_lshrrev_b32_e32 v151, 16, v151
	v_pk_mul_f32 v[178:179], v[178:179], v[186:187]
	v_bfe_u32 v9, v11, 16, 1
	v_bfe_u32 v170, v128, 16, 1
	v_and_or_b32 v13, v13, s85, v151
	v_and_or_b32 v12, v12, s85, v134
	v_bfe_u32 v134, v10, 16, 1
	v_bfe_u32 v151, v129, 16, 1
	v_add3_u32 v9, v11, v9, s89
	v_add3_u32 v11, v128, v170, s89
	v_bfe_u32 v128, v178, 16, 1
	v_add3_u32 v10, v10, v134, s89
	v_add3_u32 v134, v129, v151, s89
	v_bfe_u32 v151, v126, 16, 1
	v_add3_u32 v128, v178, v128, s89
	v_add3_u32 v126, v126, v151, s89
	v_lshrrev_b32_e32 v128, 16, v128
	v_bfe_u32 v129, v179, 16, 1
	v_bfe_u32 v170, v127, 16, 1
	v_lshrrev_b32_e32 v126, 16, v126
	v_and_or_b32 v128, v10, s85, v128
	v_add_co_u32_e32 v10, vcc, s90, v18
	v_add3_u32 v129, v179, v129, s89
	v_add3_u32 v127, v127, v170, s89
	v_and_or_b32 v126, v11, s85, v126
	v_addc_co_u32_e32 v11, vcc, 0, v19, vcc
	v_lshrrev_b32_e32 v129, 16, v129
	v_lshrrev_b32_e32 v127, 16, v127
	global_store_dwordx4 v[10:11], v[12:15], off
	v_add_co_u32_e32 v10, vcc, s91, v18
	v_and_or_b32 v129, v9, s85, v129
	v_and_or_b32 v127, v134, s85, v127
	v_addc_co_u32_e32 v11, vcc, 0, v19, vcc
	v_lshlrev_b32_e32 v9, 16, v131
	v_lshlrev_b32_e32 v200, 16, v5
	global_store_dwordx4 v[10:11], v[126:129], off
	v_cndmask_b32_e64 v15, 0, v9, s[6:7]
	v_lshlrev_b32_e32 v186, 16, v4
	v_and_b32_e32 v187, 0xffff0000, v4
	v_lshlrev_b32_e32 v4, 16, v132
	v_mov_b32_e32 v14, v200
	v_and_b32_e32 v131, 0xffff0000, v5
	v_cndmask_b32_e64 v191, 0, v4, s[6:7]
	v_lshlrev_b32_e32 v4, 16, v130
	ds_read_b128 v[10:13], v146 offset:32768
	ds_read_b128 v[126:129], v146 offset:32784
	ds_read_b128 v[178:181], v146 offset:32800
	ds_read_b128 v[182:185], v146 offset:32816
	v_mov_b32_e32 v130, v187
	v_pk_mul_f32 v[14:15], v[14:15], v[20:21]
	v_lshlrev_b32_e32 v9, 16, v82
	v_cndmask_b32_e64 v193, 0, v4, s[8:9]
	v_mov_b32_e32 v4, v186
	v_mov_b32_e32 v5, v200
	v_pk_fma_f32 v[14:15], v[20:21], v[186:187], v[14:15] op_sel:[0,0,1] op_sel_hi:[1,1,0]
	v_pk_mul_f32 v[186:187], v[20:21], v[130:131] op_sel_hi:[0,1]
	v_lshlrev_b32_e32 v201, 16, v6
	v_pk_fma_f32 v[14:15], v[24:25], v[130:131], v[14:15] op_sel_hi:[0,1,1]
	v_pk_fma_f32 v[4:5], v[8:9], v[4:5], v[186:187] op_sel_hi:[0,1,1]
	v_pk_add_f32 v[14:15], v[22:23], v[14:15] op_sel_hi:[0,1]
	v_pk_fma_f32 v[4:5], v[24:25], v[200:201], v[4:5] op_sel_hi:[0,1,1]
	s_waitcnt lgkmcnt(3)
	v_mov_b32_e32 v186, v10
	s_waitcnt lgkmcnt(2)
	v_mov_b32_e32 v187, v126
	v_lshlrev_b32_e32 v189, 16, v7
	v_pk_add_f32 v[4:5], v[22:23], v[4:5] op_sel_hi:[0,1]
	v_pk_mul_f32 v[14:15], v[14:15], v[186:187]
	v_mov_b32_e32 v186, v12
	v_mov_b32_e32 v187, v128
	v_pk_mul_f32 v[4:5], v[4:5], v[186:187]
	v_and_b32_e32 v7, 0xffff0000, v7
	v_and_b32_e32 v6, 0xffff0000, v6
	v_mov_b32_e32 v186, v201
	v_mov_b32_e32 v187, v189
	v_pk_mov_b32 v[130:131], v[130:131], v[6:7] op_sel:[1,0]
	v_pk_mul_f32 v[186:187], v[20:21], v[186:187] op_sel_hi:[0,1]
	v_pk_fma_f32 v[130:131], v[8:9], v[130:131], v[186:187] op_sel_hi:[0,1,1]
	v_mov_b32_e32 v200, v7
	v_mov_b32_e32 v188, v6
	v_pk_fma_f32 v[130:131], v[24:25], v[6:7], v[130:131] op_sel_hi:[0,1,1]
	v_pk_mul_f32 v[6:7], v[20:21], v[200:201]
	v_cndmask_b32_e64 v19, 0, v9, s[8:9]
	v_mov_b32_e32 v18, v189
	v_pk_fma_f32 v[6:7], v[20:21], v[188:189], v[6:7] op_sel:[0,0,1] op_sel_hi:[1,1,0]
	v_pk_add_f32 v[130:131], v[22:23], v[130:131] op_sel_hi:[0,1]
	v_pk_fma_f32 v[6:7], v[24:25], v[18:19], v[6:7] op_sel_hi:[0,1,1]
	s_waitcnt lgkmcnt(1)
	v_mov_b32_e32 v18, v178
	s_waitcnt lgkmcnt(0)
	v_mov_b32_e32 v19, v182
	v_pk_add_f32 v[6:7], v[22:23], v[6:7] op_sel_hi:[0,1]
	v_pk_mul_f32 v[18:19], v[130:131], v[18:19]
	v_mov_b32_e32 v130, v180
	v_mov_b32_e32 v131, v184
	v_pk_mul_f32 v[6:7], v[6:7], v[130:131]
	v_lshlrev_b32_e32 v194, 16, v0
	v_and_b32_e32 v195, 0xffff0000, v0
	v_bfe_u32 v0, v7, 16, 1
	v_bfe_u32 v10, v5, 16, 1
	v_add3_u32 v0, v7, v0, s89
	v_bfe_u32 v7, v18, 16, 1
	v_bfe_u32 v9, v6, 16, 1
	v_add3_u32 v5, v5, v10, s89
	v_bfe_u32 v10, v14, 16, 1
	v_add3_u32 v7, v18, v7, s89
	v_add3_u32 v6, v6, v9, s89
	v_add3_u32 v10, v14, v10, s89
	v_lshrrev_b32_e32 v14, 16, v7
	v_and_or_b32 v6, v6, s85, v14
	v_lshlrev_b32_e32 v14, 16, v1
	v_bfe_u32 v9, v19, 16, 1
	v_mov_b32_e32 v190, v14
	v_bfe_u32 v12, v4, 16, 1
	v_add3_u32 v9, v19, v9, s89
	v_pk_mul_f32 v[18:19], v[190:191], v[20:21]
	v_and_b32_e32 v197, 0xffff0000, v1
	v_add3_u32 v4, v4, v12, s89
	v_bfe_u32 v12, v15, 16, 1
	v_mov_b32_e32 v196, v195
	v_pk_fma_f32 v[18:19], v[20:21], v[194:195], v[18:19] op_sel:[0,0,1] op_sel_hi:[1,1,0]
	v_add3_u32 v12, v15, v12, s89
	v_pk_fma_f32 v[18:19], v[24:25], v[196:197], v[18:19] op_sel_hi:[0,1,1]
	v_lshlrev_b32_e32 v199, 16, v3
	v_lshrrev_b32_e32 v7, 16, v9
	v_lshrrev_b32_e32 v9, 16, v10
	v_lshrrev_b32_e32 v10, 16, v12
	v_lshlrev_b32_e32 v15, 16, v2
	v_pk_add_f32 v[18:19], v[22:23], v[18:19] op_sel_hi:[0,1]
	v_mov_b32_e32 v126, v11
	v_and_or_b32 v7, v0, s85, v7
	v_and_or_b32 v5, v5, s85, v10
	v_mov_b32_e32 v0, v194
	v_mov_b32_e32 v1, v14
	v_pk_mul_f32 v[130:131], v[20:21], v[196:197] op_sel_hi:[0,1]
	v_pk_mul_f32 v[10:11], v[18:19], v[126:127]
	v_and_b32_e32 v3, 0xffff0000, v3
	v_and_b32_e32 v2, 0xffff0000, v2
	v_mov_b32_e32 v18, v15
	v_mov_b32_e32 v19, v199
	v_pk_fma_f32 v[0:1], v[8:9], v[0:1], v[130:131] op_sel_hi:[0,1,1]
	v_mov_b32_e32 v128, v13
	v_pk_mov_b32 v[12:13], v[196:197], v[2:3] op_sel:[1,0]
	v_pk_mul_f32 v[18:19], v[20:21], v[18:19] op_sel_hi:[0,1]
	v_and_or_b32 v4, v4, s85, v9
	v_pk_fma_f32 v[0:1], v[24:25], v[14:15], v[0:1] op_sel_hi:[0,1,1]
	v_pk_fma_f32 v[8:9], v[8:9], v[12:13], v[18:19] op_sel_hi:[0,1,1]
	v_mov_b32_e32 v14, v3
	v_mov_b32_e32 v198, v2
	v_pk_fma_f32 v[8:9], v[24:25], v[2:3], v[8:9] op_sel_hi:[0,1,1]
	v_pk_mul_f32 v[2:3], v[20:21], v[14:15]
	v_mov_b32_e32 v192, v199
	v_pk_fma_f32 v[2:3], v[20:21], v[198:199], v[2:3] op_sel:[0,0,1] op_sel_hi:[1,1,0]
	v_mov_b32_e32 v184, v181
	v_pk_fma_f32 v[2:3], v[24:25], v[192:193], v[2:3] op_sel_hi:[0,1,1]
	v_pk_add_f32 v[2:3], v[22:23], v[2:3] op_sel_hi:[0,1]
	v_pk_add_f32 v[8:9], v[22:23], v[8:9] op_sel_hi:[0,1]
	v_mov_b32_e32 v182, v179
	v_pk_mul_f32 v[2:3], v[2:3], v[184:185]
	v_pk_mul_f32 v[8:9], v[8:9], v[182:183]
	v_bfe_u32 v12, v3, 16, 1
	v_pk_add_f32 v[0:1], v[22:23], v[0:1] op_sel_hi:[0,1]
	v_bfe_u32 v13, v2, 16, 1
	v_add3_u32 v3, v3, v12, s89
	v_bfe_u32 v12, v8, 16, 1
	v_pk_mul_f32 v[0:1], v[0:1], v[128:129]
	v_add3_u32 v2, v2, v13, s89
	v_bfe_u32 v13, v9, 16, 1
	v_add3_u32 v8, v8, v12, s89
	v_bfe_u32 v14, v1, 16, 1
	v_bfe_u32 v15, v0, 16, 1
	v_add3_u32 v9, v9, v13, s89
	v_lshrrev_b32_e32 v8, 16, v8
	v_add3_u32 v0, v0, v15, s89
	v_add3_u32 v1, v1, v14, s89
	v_bfe_u32 v14, v10, 16, 1
	v_bfe_u32 v15, v11, 16, 1
	v_lshrrev_b32_e32 v9, 16, v9
	v_and_or_b32 v2, v2, s85, v8
	v_add_co_u32_e32 v8, vcc, s90, v16
	v_add3_u32 v11, v11, v15, s89
	v_add3_u32 v10, v10, v14, s89
	v_and_or_b32 v3, v3, s85, v9
	v_addc_co_u32_e32 v9, vcc, 0, v17, vcc
	v_lshrrev_b32_e32 v10, 16, v10
	v_lshrrev_b32_e32 v11, 16, v11
	global_store_dwordx4 v[8:9], v[4:7], off
	v_and_or_b32 v1, v1, s85, v11
	v_and_or_b32 v0, v0, s85, v10
	v_add_co_u32_e32 v4, vcc, s91, v16
	s_nop 1
	v_addc_co_u32_e32 v5, vcc, 0, v17, vcc
	global_store_dwordx4 v[4:5], v[0:3], off
	s_waitcnt lgkmcnt(0)
	s_barrier
	s_and_b64 vcc, exec, s[46:47]
	s_cbranch_vccz .LBB0_414
